# P3 epilogue: ss1 row scales preloaded once, QK-norm gains loaded once, rope/rotary tables prefetched one block ahead into dead fragment VGPRs with counted vmcnt
# speedup vs baseline: 1.0126x; 1.0126x over previous
; __device__ __forceinline__ float fast_sigmoid(float a) { return __builtin_amdgcn_rcpf(1.0f + __expf(-a)); }
;     __device__ __forceinline__ void operator()(const Acc& acc, const Unit& u, int wr, int wc, int fr, int fq) const {
;     ...
;                 const int row = u.pm * 256 + ai * 128 + wr * 64 + m * 16 + fr;
;                 const float rs = rsqrtf(ss1[row] * (1.0f / DM) + EPS);
;                 const int posidx = row < MPROMPT ? (row & 2047) : 2048;
;                 f32x4 v[2][2];
; #pragma unroll
;                 for (int bj = 0; bj < 2; ++bj)
; #pragma unroll
;                     for (int n = 0; n < 2; ++n) v[bj][n] = acc[ai][bj][m][n] * rs;
;     ...
;                 } else if (kind == 7) {
; #pragma unroll
;                     for (int bj = 0; bj < 2; ++bj)
; #pragma unroll
;                         for (int n = 0; n < 2; ++n)
; #pragma unroll
;                             for (int j = 0; j < 4; ++j) v[bj][n][j] = fast_sigmoid(v[bj][n][j]);
.LBB0_694:
	v_sub_co_u32_e64 v128, s[10:11], s49, 1
	s_and_b64 s[12:13], s[10:11], exec
	s_cselect_b32 s19, s23, s25
	s_cselect_b32 s18, s22, s24
	s_lshl_b32 s87, s2, 8
	s_add_i32 s87, s87, s61
	v_or_b32_e32 v160, s87, v145
	v_ashrrev_i32_e32 v161, 31, v160
	v_readfirstlane_b32 s47, v128
	v_lshl_add_u64 v[128:129], v[160:161], 2, s[28:29]
	global_load_dword v181, v[128:129], off offset:64
	global_load_dword v182, v[128:129], off offset:128
	global_load_dword v183, v[128:129], off offset:192
	global_load_dword v184, v[128:129], off offset:512
	global_load_dword v185, v[128:129], off offset:576
	global_load_dword v186, v[128:129], off offset:640
	global_load_dword v187, v[128:129], off offset:704
	global_load_dword v128, v[128:129], off
	s_cmp_gt_u32 s49, 1
	s_cselect_b64 s[14:15], -1, 0
	s_add_i32 s1, s49, -3
	s_cmp_gt_u32 s1, 1
	s_cselect_b64 s[16:17], -1, 0
	s_cmp_eq_u32 s49, 4
	s_cselect_b64 vcc, -1, 0
	v_cndmask_b32_e32 v156, 1.0, v175, vcc
	v_bitop3_b32 v161, s87, v176, v145 bitop3:0xc8
	v_cmp_lt_i32_e64 s[12:13], s75, v160
	s_mov_b64 s[2:3], -1
	s_waitcnt vmcnt(0)
	v_fmamk_f32 v128, v128, 0x3a800000, v174
	v_cmp_gt_f32_e32 vcc, s74, v128
	v_mul_f32_e32 v129, 0x4b800000, v128
	s_nop 0
	v_cndmask_b32_e32 v128, v128, v129, vcc
	v_rsq_f32_e32 v128, v128
	s_nop 0
	v_mul_f32_e32 v129, 0x45800000, v128
	v_cndmask_b32_e32 v132, v128, v129, vcc
	v_cmp_gt_i32_e32 vcc, s64, v160
	v_pk_mul_f32 v[162:163], v[126:127], v[132:133] op_sel_hi:[1,0]
	v_pk_mul_f32 v[166:167], v[124:125], v[132:133] op_sel_hi:[1,0]
	v_pk_mul_f32 v[136:137], v[122:123], v[132:133] op_sel_hi:[1,0]
	v_pk_mul_f32 v[164:165], v[120:121], v[132:133] op_sel_hi:[1,0]
	v_pk_mul_f32 v[130:131], v[118:119], v[132:133] op_sel_hi:[1,0]
	v_pk_mul_f32 v[134:135], v[116:117], v[132:133] op_sel_hi:[1,0]
	v_pk_mul_f32 v[128:129], v[114:115], v[132:133] op_sel_hi:[1,0]
	v_pk_mul_f32 v[132:133], v[112:113], v[132:133] op_sel_hi:[1,0]
	v_cndmask_b32_e32 v155, v177, v161, vcc
	s_and_b64 vcc, exec, s[14:15]
	s_cbranch_vccz .LBB0_705
	s_and_b64 vcc, exec, s[16:17]
	s_cbranch_vccz .LBB0_702
	s_cmp_gt_i32 s49, 6
	s_cbranch_scc0 .LBB0_698
	v_mul_f32_e32 v112, 0xbfb8aa3b, v166
	v_exp_f32_e32 v112, v112
	v_mul_f32_e32 v113, 0xbfb8aa3b, v167
	v_exp_f32_e32 v113, v113
	v_mul_f32_e32 v114, 0xbfb8aa3b, v163
	v_add_f32_e32 v112, 1.0, v112
	v_rcp_f32_e32 v116, v112
	v_mul_f32_e32 v112, 0xbfb8aa3b, v162
	v_exp_f32_e32 v112, v112
	v_exp_f32_e32 v114, v114
	v_add_f32_e32 v113, 1.0, v113
	v_rcp_f32_e32 v117, v113
	v_add_f32_e32 v112, 1.0, v112
	v_mul_f32_e32 v113, 0xbfb8aa3b, v164
	v_rcp_f32_e32 v118, v112
	v_add_f32_e32 v112, 1.0, v114
	v_exp_f32_e32 v113, v113
	v_mul_f32_e32 v114, 0xbfb8aa3b, v165
	v_exp_f32_e32 v114, v114
	v_rcp_f32_e32 v119, v112
	v_add_f32_e32 v112, 1.0, v113
	v_mul_f32_e32 v113, 0xbfb8aa3b, v136
	v_rcp_f32_e32 v124, v112
	v_add_f32_e32 v112, 1.0, v114
	v_exp_f32_e32 v113, v113
	v_mul_f32_e32 v114, 0xbfb8aa3b, v137
	v_exp_f32_e32 v114, v114
	v_rcp_f32_e32 v125, v112
	v_add_f32_e32 v112, 1.0, v113
	v_rcp_f32_e32 v126, v112
	v_add_f32_e32 v112, 1.0, v114
	v_mul_f32_e32 v113, 0xbfb8aa3b, v134
	v_mul_f32_e32 v114, 0xbfb8aa3b, v135
	v_exp_f32_e32 v113, v113
	v_exp_f32_e32 v114, v114
	v_rcp_f32_e32 v127, v112
	v_mul_f32_e32 v115, 0xbfb8aa3b, v131
	v_add_f32_e32 v112, 1.0, v113
	v_add_f32_e32 v113, 1.0, v114
	v_mul_f32_e32 v114, 0xbfb8aa3b, v130
	v_mul_f32_e32 v120, 0xbfb8aa3b, v132
	v_mul_f32_e32 v121, 0xbfb8aa3b, v133
	v_mul_f32_e32 v122, 0xbfb8aa3b, v128
	v_mul_f32_e32 v123, 0xbfb8aa3b, v129
	v_exp_f32_e32 v114, v114
	v_exp_f32_e32 v115, v115
	v_exp_f32_e32 v120, v120
	v_exp_f32_e32 v121, v121
	v_exp_f32_e32 v122, v122
	v_exp_f32_e32 v123, v123
	v_add_f32_e32 v114, 1.0, v114
	v_add_f32_e32 v115, 1.0, v115
	v_add_f32_e32 v120, 1.0, v120
	v_add_f32_e32 v121, 1.0, v121
	v_add_f32_e32 v122, 1.0, v122
	v_add_f32_e32 v123, 1.0, v123
	v_rcp_f32_e32 v112, v112
	v_rcp_f32_e32 v113, v113
	v_rcp_f32_e32 v114, v114
	v_rcp_f32_e32 v115, v115
	v_rcp_f32_e32 v120, v120
	v_rcp_f32_e32 v121, v121
	v_rcp_f32_e32 v122, v122
	v_rcp_f32_e32 v123, v123
	s_mov_b64 s[2:3], 0

;     __device__ __forceinline__ void operator()(const Acc& acc, const Unit& u, int wr, int wc, int fr, int fq) const {
;     ...
;                 } else if (kind == 3 || kind == 4) {
;                     const float ksc = (kind == 4) ? 0.0625f : 1.0f;
; #pragma unroll
;                     for (int bj = 0; bj < 2; ++bj)
; #pragma unroll
;                         for (int n = 0; n < 2; ++n) {
;                             const int i0 = (wc * 64 + bj * 32 + fq * 8 + n * 4) >> 1;
;                             const f32x4 cs = *(const f32x4*)(rrot + ((size_t)posidx * 128 + i0) * 2);
;                             const f32x4 x = v[bj][n]; f32x4 o;
;                             o[0] = (x[0] * cs[0] - x[1] * cs[1]) * ksc; o[1] = (x[1] * cs[0] + x[0] * cs[1]) * ksc;
;                             o[2] = (x[2] * cs[2] - x[3] * cs[3]) * ksc; o[3] = (x[3] * cs[2] + x[2] * cs[3]) * ksc;
;                             v[bj][n] = o;
;                         }
.LBB0_702:
	s_and_b64 vcc, exec, s[2:3]
	s_cbranch_vccz .LBB0_704
	v_lshlrev_b32_e32 v112, 2, v170
	v_lshl_or_b32 v142, v155, 10, v112
	global_load_dwordx4 v[188:191], v142, s[20:21] offset:16
	global_load_dwordx4 v[192:195], v142, s[20:21]
	global_load_dwordx4 v[196:199], v142, s[20:21] offset:144
	global_load_dwordx4 v[200:203], v142, s[20:21] offset:128
	v_add_u32_e32 v236, 0x4000, v142
	global_load_dwordx4 v[212:215], v236, s[20:21] offset:16
	global_load_dwordx4 v[216:219], v236, s[20:21]
	global_load_dwordx4 v[220:223], v236, s[20:21] offset:144
	global_load_dwordx4 v[224:227], v236, s[20:21] offset:128
	s_waitcnt vmcnt(4)
	v_mov_b32_e32 v112, v188
	v_mov_b32_e32 v113, v189
	v_mov_b32_e32 v114, v190
	v_mov_b32_e32 v115, v191
	v_mov_b32_e32 v116, v192
	v_mov_b32_e32 v117, v193
	v_mov_b32_e32 v118, v194
	v_mov_b32_e32 v119, v195
	v_pk_mul_f32 v[120:121], v[166:167], v[116:117] op_sel:[1,1] op_sel_hi:[0,1]
	v_pk_fma_f32 v[122:123], v[166:167], v[116:117], v[120:121] neg_lo:[0,0,1] neg_hi:[0,0,1]
	v_pk_fma_f32 v[116:117], v[166:167], v[116:117], v[120:121] op_sel_hi:[1,0,1]
	v_mul_f32_e32 v120, v163, v119
	v_mov_b32_e32 v123, v117
	v_pk_mul_f32 v[116:117], v[156:157], v[122:123] op_sel_hi:[0,1]
	v_mul_f32_e32 v122, v163, v118
	v_pk_fma_f32 v[120:121], v[162:163], v[118:119], v[120:121] op_sel_hi:[1,1,0] neg_lo:[0,0,1] neg_hi:[0,0,1]
	v_pk_fma_f32 v[118:119], v[162:163], v[118:119], v[122:123] op_sel:[1,0,0] op_sel_hi:[0,1,0]
	v_mov_b32_e32 v121, v119
	v_pk_mul_f32 v[118:119], v[156:157], v[120:121] op_sel_hi:[0,1]
	v_pk_mul_f32 v[120:121], v[164:165], v[112:113] op_sel:[1,1] op_sel_hi:[0,1]
	v_pk_fma_f32 v[122:123], v[164:165], v[112:113], v[120:121] neg_lo:[0,0,1] neg_hi:[0,0,1]
	v_pk_fma_f32 v[112:113], v[164:165], v[112:113], v[120:121] op_sel_hi:[1,0,1]
	v_mul_f32_e32 v120, v137, v114
	v_mul_f32_e32 v112, v137, v115
	v_mov_b32_e32 v123, v113
	v_pk_fma_f32 v[112:113], v[136:137], v[114:115], v[112:113] op_sel_hi:[1,1,0] neg_lo:[0,0,1] neg_hi:[0,0,1]
	v_pk_fma_f32 v[114:115], v[136:137], v[114:115], v[120:121] op_sel:[1,0,0] op_sel_hi:[0,1,0]
	v_mov_b32_e32 v113, v115
	v_pk_mul_f32 v[124:125], v[156:157], v[122:123] op_sel_hi:[0,1]
	v_pk_mul_f32 v[126:127], v[156:157], v[112:113] op_sel_hi:[0,1]
	v_mov_b32_e32 v120, v196
	v_mov_b32_e32 v121, v197
	v_mov_b32_e32 v122, v198
	v_mov_b32_e32 v123, v199
	v_mov_b32_e32 v112, v200
	v_mov_b32_e32 v113, v201
	v_mov_b32_e32 v114, v202
	v_mov_b32_e32 v115, v203
	s_nop 0
	v_pk_mul_f32 v[158:159], v[134:135], v[112:113] op_sel:[1,1] op_sel_hi:[0,1]
	v_mul_f32_e32 v142, v131, v115
	v_pk_fma_f32 v[168:169], v[134:135], v[112:113], v[158:159] neg_lo:[0,0,1] neg_hi:[0,0,1]
	v_pk_fma_f32 v[112:113], v[134:135], v[112:113], v[158:159] op_sel_hi:[1,0,1]
	v_pk_fma_f32 v[158:159], v[130:131], v[114:115], v[142:143] op_sel_hi:[1,1,0] neg_lo:[0,0,1] neg_hi:[0,0,1]
	v_mul_f32_e32 v142, v131, v114
	v_pk_fma_f32 v[114:115], v[130:131], v[114:115], v[142:143] op_sel:[1,0,0] op_sel_hi:[0,1,0]
	v_mov_b32_e32 v159, v115
	v_mov_b32_e32 v169, v113
	v_pk_mul_f32 v[114:115], v[156:157], v[158:159] op_sel_hi:[0,1]
	v_pk_mul_f32 v[158:159], v[132:133], v[120:121] op_sel:[1,1] op_sel_hi:[0,1]
	v_mul_f32_e32 v142, v129, v123
	v_pk_mul_f32 v[112:113], v[156:157], v[168:169] op_sel_hi:[0,1]
	v_pk_fma_f32 v[168:169], v[132:133], v[120:121], v[158:159] neg_lo:[0,0,1] neg_hi:[0,0,1]
	v_pk_fma_f32 v[120:121], v[132:133], v[120:121], v[158:159] op_sel_hi:[1,0,1]
	v_pk_fma_f32 v[158:159], v[128:129], v[122:123], v[142:143] op_sel_hi:[1,1,0] neg_lo:[0,0,1] neg_hi:[0,0,1]
	v_mul_f32_e32 v142, v129, v122
	v_pk_fma_f32 v[122:123], v[128:129], v[122:123], v[142:143] op_sel:[1,0,0] op_sel_hi:[0,1,0]
	v_mov_b32_e32 v169, v121
	v_mov_b32_e32 v159, v123
	v_pk_mul_f32 v[120:121], v[156:157], v[168:169] op_sel_hi:[0,1]
	v_pk_mul_f32 v[122:123], v[156:157], v[158:159] op_sel_hi:[0,1]

;     __device__ __forceinline__ void operator()(const Acc& acc, const Unit& u, int wr, int wc, int fr, int fq) const {
;     ...
;                 if (kind <= 1) {
;                     float s2 = 0.f;
; #pragma unroll
;                     for (int bj = 0; bj < 2; ++bj)
; #pragma unroll
;                         for (int n = 0; n < 2; ++n) s2 += (v[bj][n][0] * v[bj][n][0] + v[bj][n][1] * v[bj][n][1]) + (v[bj][n][2] * v[bj][n][2] + v[bj][n][3] * v[bj][n][3]);
;                     s2 += __shfl_xor(s2, 16); s2 += __shfl_xor(s2, 32);
;                     const float r = rsqrtf(s2 * (1.0f / 64.0f) + EPS);
; #pragma unroll
;                     for (int bj = 0; bj < 2; ++bj)
; #pragma unroll
;                         for (int n = 0; n < 2; ++n) { const f32x4 gv = *(const f32x4*)(gp + bj * 32 + fq * 8 + n * 4); v[bj][n] = v[bj][n] * r * gv; }
; #pragma unroll
;                     for (int n = 0; n < 2; ++n) { const f32x4 csa = *(const f32x4*)(rope + ((size_t)posidx * 8 + 4 * n) * 2), csb = *(const f32x4*)(rope + ((size_t)posidx * 8 + 4 * n) * 2 + 4);
;                         const float cc[4] = {csa[0], csa[2], csb[0], csb[2]}, sn[4] = {csa[1], csa[3], csb[1], csb[3]};
; #pragma unroll
;                         for (int j = 0; j < 4; ++j) { const float mine = v[0][n][j], other = __shfl_xor(mine, 16);
;                             const float rot = (fq == 0) ? (mine * cc[j] - other * sn[j]) : (mine * cc[j] + other * sn[j]);
;                             v[0][n][j] = (fq < 2) ? rot : mine; } }
;                     if (kind == 0) {
; #pragma unroll
;                         for (int bj = 0; bj < 2; ++bj)
; #pragma unroll
;                             for (int n = 0; n < 2; ++n) v[bj][n] = v[bj][n] * 0.125f;
;                     }
.LBB0_705:
	v_lshlrev_b32_e32 v142, 2, v144
	v_cndmask_b32_e64 v168, 0, 1, s[10:11]
	v_lshl_add_u64 v[158:159], s[18:19], 0, v[142:143]
	s_andn2_b64 vcc, exec, s[2:3]
	v_cmp_ne_u32_e64 s[10:11], 1, v168
	s_cbranch_vccnz .LBB0_708
	global_load_dwordx4 v[188:191], v[158:159], off offset:16
	global_load_dwordx4 v[192:195], v[158:159], off
	global_load_dwordx4 v[196:199], v[158:159], off offset:144
	global_load_dwordx4 v[200:203], v[158:159], off offset:128
	v_lshlrev_b32_e32 v236, 6, v155
	global_load_dwordx4 v[212:215], v236, s[26:27] offset:48
	global_load_dwordx4 v[216:219], v236, s[26:27] offset:32
	global_load_dwordx4 v[220:223], v236, s[26:27] offset:16
	global_load_dwordx4 v[224:227], v236, s[26:27]
	v_pk_mul_f32 v[112:113], v[162:163], v[162:163]
	v_pk_mul_f32 v[114:115], v[166:167], v[166:167]
	s_nop 0
	v_pk_mov_b32 v[116:117], v[114:115], v[112:113] op_sel:[1,0]
	v_mov_b32_e32 v115, v113
	v_pk_add_f32 v[112:113], v[116:117], v[114:115]
	v_pk_mul_f32 v[114:115], v[136:137], v[136:137]
	v_pk_add_f32 v[112:113], v[112:113], v[112:113] op_sel_hi:[0,1]
	v_pk_mul_f32 v[116:117], v[164:165], v[164:165]
	v_mul_f32_e32 v112, v134, v134
	v_pk_mov_b32 v[118:119], v[116:117], v[114:115] op_sel:[1,0]
	v_mov_b32_e32 v117, v115
	v_pk_add_f32 v[114:115], v[118:119], v[116:117]
	v_pk_fma_f32 v[116:117], v[134:135], v[134:135], v[112:113] op_sel_hi:[1,1,0]
	v_mul_f32_e32 v112, v130, v130
	v_pk_add_f32 v[114:115], v[114:115], v[114:115] op_sel_hi:[0,1]
	v_pk_fma_f32 v[118:119], v[130:131], v[130:131], v[112:113] op_sel_hi:[1,1,0]
	v_mul_f32_e32 v116, v132, v132
	v_mul_f32_e32 v118, v133, v133
	v_mul_f32_e32 v112, v128, v128
	v_mul_f32_e32 v114, v129, v129
	v_pk_add_f32 v[116:117], v[116:117], v[118:119]
	v_pk_add_f32 v[112:113], v[112:113], v[114:115]
	v_and_b32_e32 v114, 64, v178
	v_pk_add_f32 v[112:113], v[116:117], v[112:113]
	v_add_u32_e32 v114, 64, v114
	v_add_f32_e32 v112, v112, v113
	v_xor_b32_e32 v113, 16, v178
	v_cmp_lt_i32_e32 vcc, v113, v114
	s_nop 1
	v_cndmask_b32_e32 v113, v178, v113, vcc
	v_lshlrev_b32_e32 v179, 2, v113
	ds_bpermute_b32 v113, v179, v112
	s_waitcnt lgkmcnt(0)
	v_add_f32_e32 v112, v112, v113
	v_xor_b32_e32 v113, 32, v178
	v_cmp_lt_i32_e32 vcc, v113, v114
	s_nop 1
	v_cndmask_b32_e32 v113, v178, v113, vcc
	v_lshlrev_b32_e32 v113, 2, v113
	ds_bpermute_b32 v113, v113, v112
	s_waitcnt lgkmcnt(0)
	v_add_f32_e32 v112, v112, v113
	v_fmamk_f32 v112, v112, 0x3c800000, v174
	v_cmp_gt_f32_e32 vcc, s74, v112
	v_mul_f32_e32 v113, 0x4b800000, v112
	s_nop 0
	v_cndmask_b32_e32 v112, v112, v113, vcc
	v_rsq_f32_e32 v112, v112
	s_nop 0
	v_mul_f32_e32 v113, 0x45800000, v112
	v_cndmask_b32_e32 v116, v112, v113, vcc
	s_waitcnt vmcnt(4)
	v_mov_b32_e32 v112, v188
	v_mov_b32_e32 v113, v189
	v_mov_b32_e32 v114, v190
	v_mov_b32_e32 v115, v191
	v_mov_b32_e32 v118, v192
	v_mov_b32_e32 v119, v193
	v_mov_b32_e32 v120, v194
	v_mov_b32_e32 v121, v195
	v_pk_mul_f32 v[122:123], v[166:167], v[116:117] op_sel_hi:[1,0]
	v_pk_mul_f32 v[124:125], v[162:163], v[116:117] op_sel_hi:[1,0]
	v_pk_mul_f32 v[126:127], v[130:131], v[116:117] op_sel_hi:[1,0]
	s_and_b64 vcc, exec, s[10:11]
	s_nop 0
	v_pk_mul_f32 v[166:167], v[120:121], v[124:125]
	v_pk_mul_f32 v[168:169], v[118:119], v[122:123]
	v_pk_mul_f32 v[118:119], v[164:165], v[116:117] op_sel_hi:[1,0]
	v_pk_mul_f32 v[120:121], v[136:137], v[116:117] op_sel_hi:[1,0]
	v_pk_mul_f32 v[124:125], v[112:113], v[118:119]
	v_pk_mul_f32 v[162:163], v[114:115], v[120:121]
	v_mov_b32_e32 v118, v196
	v_mov_b32_e32 v119, v197
	v_mov_b32_e32 v120, v198
	v_mov_b32_e32 v121, v199
	v_mov_b32_e32 v112, v200
	v_mov_b32_e32 v113, v201
	v_mov_b32_e32 v114, v202
	v_mov_b32_e32 v115, v203
	v_pk_mul_f32 v[122:123], v[134:135], v[116:117] op_sel_hi:[1,0]
	s_nop 0
	v_pk_mul_f32 v[114:115], v[114:115], v[126:127]
	v_pk_mul_f32 v[126:127], v[132:133], v[116:117] op_sel_hi:[1,0]
	v_pk_mul_f32 v[116:117], v[128:129], v[116:117] op_sel_hi:[1,0]
	v_pk_mul_f32 v[112:113], v[112:113], v[122:123]
	v_pk_mul_f32 v[122:123], v[120:121], v[116:117]
	v_lshlrev_b32_e32 v116, 6, v155
	v_pk_mul_f32 v[120:121], v[118:119], v[126:127]
	s_waitcnt vmcnt(0)
	v_mov_b32_e32 v126, v212
	v_mov_b32_e32 v127, v213
	v_mov_b32_e32 v128, v214
	v_mov_b32_e32 v129, v215
	v_mov_b32_e32 v130, v216
	v_mov_b32_e32 v131, v217
	v_mov_b32_e32 v132, v218
	v_mov_b32_e32 v133, v219
	v_mov_b32_e32 v134, v220
	v_mov_b32_e32 v135, v221
	v_mov_b32_e32 v136, v222
	v_mov_b32_e32 v137, v223
	s_nop 0
	v_mov_b32_e32 v116, v224
	v_mov_b32_e32 v117, v225
	v_mov_b32_e32 v118, v226
	v_mov_b32_e32 v119, v227
	v_lshlrev_b32_e32 v236, 6, v155
	v_add_u32_e32 v236, 1024, v236
	global_load_dwordx4 v[212:215], v236, s[26:27] offset:48
	global_load_dwordx4 v[216:219], v236, s[26:27] offset:32
	global_load_dwordx4 v[220:223], v236, s[26:27] offset:16
	global_load_dwordx4 v[224:227], v236, s[26:27]
	ds_bpermute_b32 v155, v179, v168
	s_waitcnt lgkmcnt(0)
	v_mul_f32_e32 v117, v117, v155
	v_cndmask_b32_e64 v117, v117, -v117, s[4:5]
	v_fmac_f32_e32 v117, v116, v168
	v_cndmask_b32_e64 v116, v168, v117, s[6:7]
	ds_bpermute_b32 v117, v179, v169
	s_waitcnt lgkmcnt(0)
	v_mul_f32_e32 v117, v119, v117
	v_cndmask_b32_e64 v117, v117, -v117, s[4:5]
	v_fmac_f32_e32 v117, v118, v169
	ds_bpermute_b32 v118, v179, v166
	ds_bpermute_b32 v119, v179, v167
	v_cndmask_b32_e64 v117, v169, v117, s[6:7]
	s_waitcnt lgkmcnt(1)
	v_mul_f32_e32 v118, v135, v118
	v_cndmask_b32_e64 v118, v118, -v118, s[4:5]
	v_fmac_f32_e32 v118, v134, v166
	ds_bpermute_b32 v134, v179, v124
	s_waitcnt lgkmcnt(1)
	v_mul_f32_e32 v119, v137, v119
	v_cndmask_b32_e64 v119, v119, -v119, s[4:5]
	v_fmac_f32_e32 v119, v136, v167
	v_cndmask_b32_e64 v118, v166, v118, s[6:7]
	s_waitcnt lgkmcnt(0)
	v_mul_f32_e32 v131, v131, v134
	v_cndmask_b32_e64 v131, v131, -v131, s[4:5]
	v_fmac_f32_e32 v131, v130, v124
	ds_bpermute_b32 v130, v179, v125
	v_cndmask_b32_e64 v119, v167, v119, s[6:7]
	v_cndmask_b32_e64 v124, v124, v131, s[6:7]
	s_waitcnt lgkmcnt(0)
	v_mul_f32_e32 v130, v133, v130
	v_cndmask_b32_e64 v130, v130, -v130, s[4:5]
	v_fmac_f32_e32 v130, v132, v125
	v_cndmask_b32_e64 v125, v125, v130, s[6:7]
	ds_bpermute_b32 v130, v179, v162
	s_waitcnt lgkmcnt(0)
	v_mul_f32_e32 v127, v127, v130
	v_cndmask_b32_e64 v127, v127, -v127, s[4:5]
	v_fmac_f32_e32 v127, v126, v162
	v_cndmask_b32_e64 v126, v162, v127, s[6:7]
	ds_bpermute_b32 v127, v179, v163
	s_waitcnt lgkmcnt(0)
	v_mul_f32_e32 v127, v129, v127
	v_cndmask_b32_e64 v127, v127, -v127, s[4:5]
	v_fmac_f32_e32 v127, v128, v163
	v_cndmask_b32_e64 v127, v163, v127, s[6:7]
	s_cbranch_vccnz .LBB0_708
	v_pk_mul_f32 v[118:119], v[118:119], s[42:43] op_sel_hi:[1,0]
	v_pk_mul_f32 v[116:117], v[116:117], s[42:43] op_sel_hi:[1,0]
	v_pk_mul_f32 v[126:127], v[126:127], s[42:43] op_sel_hi:[1,0]
	v_pk_mul_f32 v[124:125], v[124:125], s[42:43] op_sel_hi:[1,0]
	v_pk_mul_f32 v[114:115], v[114:115], s[42:43] op_sel_hi:[1,0]
	v_pk_mul_f32 v[112:113], v[112:113], s[42:43] op_sel_hi:[1,0]
	v_pk_mul_f32 v[122:123], v[122:123], s[42:43] op_sel_hi:[1,0]
	v_pk_mul_f32 v[120:121], v[120:121], s[42:43] op_sel_hi:[1,0]

; __device__ __forceinline__ float fast_sigmoid(float a) { return __builtin_amdgcn_rcpf(1.0f + __expf(-a)); }
;     __device__ __forceinline__ void operator()(const Acc& acc, const Unit& u, int wr, int wc, int fr, int fq) const {
;     ...
;                 const int row = u.pm * 256 + ai * 128 + wr * 64 + m * 16 + fr;
;                 const float rs = rsqrtf(ss1[row] * (1.0f / DM) + EPS);
;                 const int posidx = row < MPROMPT ? (row & 2047) : 2048;
;                 f32x4 v[2][2];
; #pragma unroll
;                 for (int bj = 0; bj < 2; ++bj)
; #pragma unroll
;                     for (int n = 0; n < 2; ++n) v[bj][n] = acc[ai][bj][m][n] * rs;
;     ...
;                 } else if (kind == 7) {
; #pragma unroll
;                     for (int bj = 0; bj < 2; ++bj)
; #pragma unroll
;                         for (int n = 0; n < 2; ++n)
; #pragma unroll
;                             for (int j = 0; j < 4; ++j) v[bj][n][j] = fast_sigmoid(v[bj][n][j]);
.LBB0_714:
	s_nop 0
	v_or_b32_e32 v122, 16, v160
	v_ashrrev_i32_e32 v123, 31, v122
	v_lshl_add_u64 v[112:113], v[122:123], 2, s[28:29]
	v_mov_b32_e32 v112, v181
	v_cndmask_b32_e64 v113, 0, 1, s[14:15]
	v_cndmask_b32_e64 v130, 0, 1, s[16:17]
	v_cmp_ne_u32_e64 s[16:17], 1, v113
	v_bitop3_b32 v123, v160, s91, 16 bitop3:0xc8
	v_cmp_gt_i32_e32 vcc, s64, v122
	s_mov_b64 s[50:51], -1
	v_cmp_lt_i32_e64 s[18:19], s75, v122
	v_cndmask_b32_e32 v132, v177, v123, vcc
	s_andn2_b64 vcc, exec, s[14:15]
	v_cmp_ne_u32_e64 s[12:13], 1, v130
	s_nop 0
	v_fmamk_f32 v112, v112, 0x3a800000, v174
	v_mul_f32_e32 v114, 0x4b800000, v112
	v_cmp_gt_f32_e64 s[0:1], s74, v112
	s_nop 1
	v_cndmask_b32_e64 v112, v112, v114, s[0:1]
	v_rsq_f32_e32 v112, v112
	s_nop 0
	v_mul_f32_e32 v113, 0x45800000, v112
	v_cndmask_b32_e64 v116, v112, v113, s[0:1]
	v_pk_mul_f32 v[124:125], v[110:111], v[116:117] op_sel_hi:[1,0]
	v_pk_mul_f32 v[128:129], v[108:109], v[116:117] op_sel_hi:[1,0]
	v_pk_mul_f32 v[120:121], v[106:107], v[116:117] op_sel_hi:[1,0]
	v_pk_mul_f32 v[126:127], v[104:105], v[116:117] op_sel_hi:[1,0]
	v_pk_mul_f32 v[114:115], v[102:103], v[116:117] op_sel_hi:[1,0]
	v_pk_mul_f32 v[118:119], v[100:101], v[116:117] op_sel_hi:[1,0]
	v_pk_mul_f32 v[112:113], v[98:99], v[116:117] op_sel_hi:[1,0]
	v_pk_mul_f32 v[116:117], v[96:97], v[116:117] op_sel_hi:[1,0]
	s_cbranch_vccnz .LBB0_725
	s_and_b64 vcc, exec, s[12:13]
	s_mov_b64 s[0:1], -1
	s_cbranch_vccnz .LBB0_722
	s_cmp_gt_i32 s49, 6
	s_cbranch_scc0 .LBB0_718
	v_mul_f32_e32 v96, 0xbfb8aa3b, v128
	v_exp_f32_e32 v96, v96
	v_mul_f32_e32 v97, 0xbfb8aa3b, v129
	v_exp_f32_e32 v97, v97
	v_mul_f32_e32 v98, 0xbfb8aa3b, v125
	v_add_f32_e32 v96, 1.0, v96
	v_rcp_f32_e32 v100, v96
	v_mul_f32_e32 v96, 0xbfb8aa3b, v124
	v_exp_f32_e32 v96, v96
	v_exp_f32_e32 v98, v98
	v_add_f32_e32 v97, 1.0, v97
	v_rcp_f32_e32 v101, v97
	v_add_f32_e32 v96, 1.0, v96
	v_mul_f32_e32 v97, 0xbfb8aa3b, v126
	v_rcp_f32_e32 v102, v96
	v_add_f32_e32 v96, 1.0, v98
	v_exp_f32_e32 v97, v97
	v_mul_f32_e32 v98, 0xbfb8aa3b, v127
	v_exp_f32_e32 v98, v98
	v_rcp_f32_e32 v103, v96
	v_add_f32_e32 v96, 1.0, v97
	v_mul_f32_e32 v97, 0xbfb8aa3b, v120
	v_rcp_f32_e32 v108, v96
	v_add_f32_e32 v96, 1.0, v98
	v_exp_f32_e32 v97, v97
	v_mul_f32_e32 v98, 0xbfb8aa3b, v121
	v_exp_f32_e32 v98, v98
	v_rcp_f32_e32 v109, v96
	v_add_f32_e32 v96, 1.0, v97
	v_rcp_f32_e32 v110, v96
	v_add_f32_e32 v96, 1.0, v98
	v_mul_f32_e32 v97, 0xbfb8aa3b, v118
	v_mul_f32_e32 v98, 0xbfb8aa3b, v119
	v_exp_f32_e32 v97, v97
	v_exp_f32_e32 v98, v98
	v_rcp_f32_e32 v111, v96
	v_mul_f32_e32 v99, 0xbfb8aa3b, v115
	v_add_f32_e32 v96, 1.0, v97
	v_add_f32_e32 v97, 1.0, v98
	v_mul_f32_e32 v98, 0xbfb8aa3b, v114
	v_mul_f32_e32 v104, 0xbfb8aa3b, v116
	v_mul_f32_e32 v105, 0xbfb8aa3b, v117
	v_mul_f32_e32 v106, 0xbfb8aa3b, v112
	v_mul_f32_e32 v107, 0xbfb8aa3b, v113
	v_exp_f32_e32 v98, v98
	v_exp_f32_e32 v99, v99
	v_exp_f32_e32 v104, v104
	v_exp_f32_e32 v105, v105
	v_exp_f32_e32 v106, v106
	v_exp_f32_e32 v107, v107
	v_add_f32_e32 v98, 1.0, v98
	v_add_f32_e32 v99, 1.0, v99
	v_add_f32_e32 v104, 1.0, v104
	v_add_f32_e32 v105, 1.0, v105
	v_add_f32_e32 v106, 1.0, v106
	v_add_f32_e32 v107, 1.0, v107
	v_rcp_f32_e32 v96, v96
	v_rcp_f32_e32 v97, v97
	v_rcp_f32_e32 v98, v98
	v_rcp_f32_e32 v99, v99
	v_rcp_f32_e32 v104, v104
	v_rcp_f32_e32 v105, v105
	v_rcp_f32_e32 v106, v106
	v_rcp_f32_e32 v107, v107
	s_mov_b64 s[0:1], 0

;     __device__ __forceinline__ void operator()(const Acc& acc, const Unit& u, int wr, int wc, int fr, int fq) const {
;     ...
;                 } else if (kind == 3 || kind == 4) {
;                     const float ksc = (kind == 4) ? 0.0625f : 1.0f;
; #pragma unroll
;                     for (int bj = 0; bj < 2; ++bj)
; #pragma unroll
;                         for (int n = 0; n < 2; ++n) {
;                             const int i0 = (wc * 64 + bj * 32 + fq * 8 + n * 4) >> 1;
;                             const f32x4 cs = *(const f32x4*)(rrot + ((size_t)posidx * 128 + i0) * 2);
;                             const f32x4 x = v[bj][n]; f32x4 o;
;                             o[0] = (x[0] * cs[0] - x[1] * cs[1]) * ksc; o[1] = (x[1] * cs[0] + x[0] * cs[1]) * ksc;
;                             o[2] = (x[2] * cs[2] - x[3] * cs[3]) * ksc; o[3] = (x[3] * cs[2] + x[2] * cs[3]) * ksc;
;                             v[bj][n] = o;
;                         }
.LBB0_722:
	s_and_b64 vcc, exec, s[0:1]
	s_cbranch_vccz .LBB0_724
	v_lshlrev_b32_e32 v96, 2, v170
	v_lshl_or_b32 v130, v132, 10, v96
	v_add_u32_e32 v236, 0x4000, v130
	global_load_dwordx4 v[188:191], v236, s[20:21] offset:16
	global_load_dwordx4 v[192:195], v236, s[20:21]
	global_load_dwordx4 v[196:199], v236, s[20:21] offset:144
	global_load_dwordx4 v[200:203], v236, s[20:21] offset:128
	s_waitcnt vmcnt(6)
	v_mov_b32_e32 v96, v212
	v_mov_b32_e32 v97, v213
	v_mov_b32_e32 v98, v214
	v_mov_b32_e32 v99, v215
	v_mov_b32_e32 v100, v216
	v_mov_b32_e32 v101, v217
	v_mov_b32_e32 v102, v218
	v_mov_b32_e32 v103, v219
	v_pk_mul_f32 v[104:105], v[128:129], v[100:101] op_sel:[1,1] op_sel_hi:[0,1]
	v_pk_fma_f32 v[106:107], v[128:129], v[100:101], v[104:105] neg_lo:[0,0,1] neg_hi:[0,0,1]
	v_pk_fma_f32 v[100:101], v[128:129], v[100:101], v[104:105] op_sel_hi:[1,0,1]
	v_mul_f32_e32 v104, v125, v103
	v_mov_b32_e32 v107, v101
	v_pk_mul_f32 v[100:101], v[156:157], v[106:107] op_sel_hi:[0,1]
	v_mul_f32_e32 v106, v125, v102
	v_pk_fma_f32 v[104:105], v[124:125], v[102:103], v[104:105] op_sel_hi:[1,1,0] neg_lo:[0,0,1] neg_hi:[0,0,1]
	v_pk_fma_f32 v[102:103], v[124:125], v[102:103], v[106:107] op_sel:[1,0,0] op_sel_hi:[0,1,0]
	v_mov_b32_e32 v105, v103
	v_pk_mul_f32 v[102:103], v[156:157], v[104:105] op_sel_hi:[0,1]
	v_pk_mul_f32 v[104:105], v[126:127], v[96:97] op_sel:[1,1] op_sel_hi:[0,1]
	v_pk_fma_f32 v[106:107], v[126:127], v[96:97], v[104:105] neg_lo:[0,0,1] neg_hi:[0,0,1]
	v_pk_fma_f32 v[96:97], v[126:127], v[96:97], v[104:105] op_sel_hi:[1,0,1]
	v_mul_f32_e32 v104, v121, v98
	v_mul_f32_e32 v96, v121, v99
	v_mov_b32_e32 v107, v97
	v_pk_fma_f32 v[96:97], v[120:121], v[98:99], v[96:97] op_sel_hi:[1,1,0] neg_lo:[0,0,1] neg_hi:[0,0,1]
	v_pk_fma_f32 v[98:99], v[120:121], v[98:99], v[104:105] op_sel:[1,0,0] op_sel_hi:[0,1,0]
	v_mov_b32_e32 v97, v99
	v_pk_mul_f32 v[108:109], v[156:157], v[106:107] op_sel_hi:[0,1]
	v_pk_mul_f32 v[110:111], v[156:157], v[96:97] op_sel_hi:[0,1]
	v_mov_b32_e32 v104, v220
	v_mov_b32_e32 v105, v221
	v_mov_b32_e32 v106, v222
	v_mov_b32_e32 v107, v223
	v_mov_b32_e32 v96, v224
	v_mov_b32_e32 v97, v225
	v_mov_b32_e32 v98, v226
	v_mov_b32_e32 v99, v227
	s_nop 0
	v_pk_mul_f32 v[130:131], v[118:119], v[96:97] op_sel:[1,1] op_sel_hi:[0,1]
	v_pk_fma_f32 v[134:135], v[118:119], v[96:97], v[130:131] neg_lo:[0,0,1] neg_hi:[0,0,1]
	v_pk_fma_f32 v[96:97], v[118:119], v[96:97], v[130:131] op_sel_hi:[1,0,1]
	v_mul_f32_e32 v130, v115, v99
	v_mov_b32_e32 v135, v97
	v_pk_mul_f32 v[96:97], v[156:157], v[134:135] op_sel_hi:[0,1]
	v_mul_f32_e32 v134, v115, v98
	v_pk_fma_f32 v[130:131], v[114:115], v[98:99], v[130:131] op_sel_hi:[1,1,0] neg_lo:[0,0,1] neg_hi:[0,0,1]
	v_pk_fma_f32 v[98:99], v[114:115], v[98:99], v[134:135] op_sel:[1,0,0] op_sel_hi:[0,1,0]
	v_mov_b32_e32 v131, v99
	v_pk_mul_f32 v[98:99], v[156:157], v[130:131] op_sel_hi:[0,1]
	v_pk_mul_f32 v[130:131], v[116:117], v[104:105] op_sel:[1,1] op_sel_hi:[0,1]
	v_pk_fma_f32 v[134:135], v[116:117], v[104:105], v[130:131] neg_lo:[0,0,1] neg_hi:[0,0,1]
	v_pk_fma_f32 v[104:105], v[116:117], v[104:105], v[130:131] op_sel_hi:[1,0,1]
	v_mul_f32_e32 v130, v113, v107
	v_mov_b32_e32 v135, v105
	v_pk_mul_f32 v[104:105], v[156:157], v[134:135] op_sel_hi:[0,1]
	v_mul_f32_e32 v134, v113, v106
	v_pk_fma_f32 v[130:131], v[112:113], v[106:107], v[130:131] op_sel_hi:[1,1,0] neg_lo:[0,0,1] neg_hi:[0,0,1]
	v_pk_fma_f32 v[106:107], v[112:113], v[106:107], v[134:135] op_sel:[1,0,0] op_sel_hi:[0,1,0]
	v_mov_b32_e32 v131, v107
	v_pk_mul_f32 v[106:107], v[156:157], v[130:131] op_sel_hi:[0,1]

;     __device__ __forceinline__ void operator()(const Acc& acc, const Unit& u, int wr, int wc, int fr, int fq) const {
;     ...
;                 if (kind <= 1) {
;                     float s2 = 0.f;
; #pragma unroll
;                     for (int bj = 0; bj < 2; ++bj)
; #pragma unroll
;                         for (int n = 0; n < 2; ++n) s2 += (v[bj][n][0] * v[bj][n][0] + v[bj][n][1] * v[bj][n][1]) + (v[bj][n][2] * v[bj][n][2] + v[bj][n][3] * v[bj][n][3]);
;                     s2 += __shfl_xor(s2, 16); s2 += __shfl_xor(s2, 32);
;                     const float r = rsqrtf(s2 * (1.0f / 64.0f) + EPS);
; #pragma unroll
;                     for (int bj = 0; bj < 2; ++bj)
; #pragma unroll
;                         for (int n = 0; n < 2; ++n) { const f32x4 gv = *(const f32x4*)(gp + bj * 32 + fq * 8 + n * 4); v[bj][n] = v[bj][n] * r * gv; }
; #pragma unroll
;                     for (int n = 0; n < 2; ++n) { const f32x4 csa = *(const f32x4*)(rope + ((size_t)posidx * 8 + 4 * n) * 2), csb = *(const f32x4*)(rope + ((size_t)posidx * 8 + 4 * n) * 2 + 4);
;                         const float cc[4] = {csa[0], csa[2], csb[0], csb[2]}, sn[4] = {csa[1], csa[3], csb[1], csb[3]};
; #pragma unroll
;                         for (int j = 0; j < 4; ++j) { const float mine = v[0][n][j], other = __shfl_xor(mine, 16);
;                             const float rot = (fq == 0) ? (mine * cc[j] - other * sn[j]) : (mine * cc[j] + other * sn[j]);
;                             v[0][n][j] = (fq < 2) ? rot : mine; } }
;                     if (kind == 0) {
; #pragma unroll
;                         for (int bj = 0; bj < 2; ++bj)
; #pragma unroll
;                             for (int n = 0; n < 2; ++n) v[bj][n] = v[bj][n] * 0.125f;
;                     }
.LBB0_725:
	s_andn2_b64 vcc, exec, s[50:51]
	s_cbranch_vccnz .LBB0_728
	v_pk_mul_f32 v[96:97], v[124:125], v[124:125]
	v_pk_mul_f32 v[98:99], v[128:129], v[128:129]
	s_nop 0
	v_pk_mov_b32 v[100:101], v[98:99], v[96:97] op_sel:[1,0]
	v_mov_b32_e32 v99, v97
	v_pk_add_f32 v[96:97], v[100:101], v[98:99]
	v_pk_mul_f32 v[98:99], v[120:121], v[120:121]
	v_pk_add_f32 v[96:97], v[96:97], v[96:97] op_sel_hi:[0,1]
	v_pk_mul_f32 v[100:101], v[126:127], v[126:127]
	v_mul_f32_e32 v96, v118, v118
	v_pk_mov_b32 v[102:103], v[100:101], v[98:99] op_sel:[1,0]
	v_mov_b32_e32 v101, v99
	v_pk_add_f32 v[98:99], v[102:103], v[100:101]
	v_pk_fma_f32 v[100:101], v[118:119], v[118:119], v[96:97] op_sel_hi:[1,1,0]
	v_mul_f32_e32 v96, v114, v114
	v_pk_add_f32 v[98:99], v[98:99], v[98:99] op_sel_hi:[0,1]
	v_pk_fma_f32 v[102:103], v[114:115], v[114:115], v[96:97] op_sel_hi:[1,1,0]
	v_mul_f32_e32 v100, v116, v116
	v_mul_f32_e32 v102, v117, v117
	v_mul_f32_e32 v96, v112, v112
	v_mul_f32_e32 v98, v113, v113
	v_pk_add_f32 v[100:101], v[100:101], v[102:103]
	v_pk_add_f32 v[96:97], v[96:97], v[98:99]
	v_and_b32_e32 v98, 64, v178
	v_pk_add_f32 v[96:97], v[100:101], v[96:97]
	v_add_u32_e32 v98, 64, v98
	v_add_f32_e32 v96, v96, v97
	v_xor_b32_e32 v97, 16, v178
	v_cmp_lt_i32_e32 vcc, v97, v98
	s_nop 1
	v_cndmask_b32_e32 v97, v178, v97, vcc
	v_lshlrev_b32_e32 v133, 2, v97
	ds_bpermute_b32 v97, v133, v96
	s_waitcnt lgkmcnt(0)
	v_add_f32_e32 v96, v96, v97
	v_xor_b32_e32 v97, 32, v178
	v_cmp_lt_i32_e32 vcc, v97, v98
	s_nop 1
	v_cndmask_b32_e32 v97, v178, v97, vcc
	v_lshlrev_b32_e32 v97, 2, v97
	ds_bpermute_b32 v97, v97, v96
	s_waitcnt lgkmcnt(0)
	v_add_f32_e32 v96, v96, v97
	v_fmamk_f32 v96, v96, 0x3c800000, v174
	v_cmp_gt_f32_e32 vcc, s74, v96
	v_mul_f32_e32 v97, 0x4b800000, v96
	s_nop 0
	v_cndmask_b32_e32 v96, v96, v97, vcc
	v_rsq_f32_e32 v96, v96
	s_nop 0
	v_mul_f32_e32 v97, 0x45800000, v96
	v_cndmask_b32_e32 v100, v96, v97, vcc
	v_mov_b32_e32 v96, v188
	v_mov_b32_e32 v97, v189
	v_mov_b32_e32 v98, v190
	v_mov_b32_e32 v99, v191
	v_mov_b32_e32 v102, v192
	v_mov_b32_e32 v103, v193
	v_mov_b32_e32 v104, v194
	v_mov_b32_e32 v105, v195
	v_pk_mul_f32 v[106:107], v[128:129], v[100:101] op_sel_hi:[1,0]
	v_pk_mul_f32 v[108:109], v[124:125], v[100:101] op_sel_hi:[1,0]
	v_pk_mul_f32 v[110:111], v[114:115], v[100:101] op_sel_hi:[1,0]
	s_and_b64 vcc, exec, s[10:11]
	s_nop 0
	v_pk_mul_f32 v[128:129], v[104:105], v[108:109]
	v_pk_mul_f32 v[130:131], v[102:103], v[106:107]
	v_pk_mul_f32 v[102:103], v[126:127], v[100:101] op_sel_hi:[1,0]
	v_pk_mul_f32 v[104:105], v[120:121], v[100:101] op_sel_hi:[1,0]
	v_pk_mul_f32 v[108:109], v[96:97], v[102:103]
	v_pk_mul_f32 v[124:125], v[98:99], v[104:105]
	v_mov_b32_e32 v102, v196
	v_mov_b32_e32 v103, v197
	v_mov_b32_e32 v104, v198
	v_mov_b32_e32 v105, v199
	v_mov_b32_e32 v96, v200
	v_mov_b32_e32 v97, v201
	v_mov_b32_e32 v98, v202
	v_mov_b32_e32 v99, v203
	v_pk_mul_f32 v[106:107], v[118:119], v[100:101] op_sel_hi:[1,0]
	ds_bpermute_b32 v126, v133, v130
	s_nop 0
	v_pk_mul_f32 v[98:99], v[98:99], v[110:111]
	v_pk_mul_f32 v[110:111], v[116:117], v[100:101] op_sel_hi:[1,0]
	v_pk_mul_f32 v[100:101], v[112:113], v[100:101] op_sel_hi:[1,0]
	v_pk_mul_f32 v[96:97], v[96:97], v[106:107]
	v_pk_mul_f32 v[106:107], v[104:105], v[100:101]
	v_lshlrev_b32_e32 v100, 6, v132
	v_pk_mul_f32 v[104:105], v[102:103], v[110:111]
	s_waitcnt vmcnt(2)
	v_mov_b32_e32 v110, v212
	v_mov_b32_e32 v111, v213
	v_mov_b32_e32 v112, v214
	v_mov_b32_e32 v113, v215
	v_mov_b32_e32 v114, v216
	v_mov_b32_e32 v115, v217
	v_mov_b32_e32 v116, v218
	v_mov_b32_e32 v117, v219
	v_mov_b32_e32 v118, v220
	v_mov_b32_e32 v119, v221
	v_mov_b32_e32 v120, v222
	v_mov_b32_e32 v121, v223
	s_nop 0
	v_mov_b32_e32 v100, v224
	v_mov_b32_e32 v101, v225
	v_mov_b32_e32 v102, v226
	v_mov_b32_e32 v103, v227
	v_lshlrev_b32_e32 v236, 6, v132
	v_add_u32_e32 v236, 1024, v236
	global_load_dwordx4 v[212:215], v236, s[26:27] offset:48
	global_load_dwordx4 v[216:219], v236, s[26:27] offset:32
	global_load_dwordx4 v[220:223], v236, s[26:27] offset:16
	global_load_dwordx4 v[224:227], v236, s[26:27]
	s_waitcnt lgkmcnt(0)
	v_mul_f32_e32 v101, v101, v126
	v_cndmask_b32_e64 v101, v101, -v101, s[4:5]
	v_fmac_f32_e32 v101, v100, v130
	v_cndmask_b32_e64 v100, v130, v101, s[6:7]
	ds_bpermute_b32 v101, v133, v131
	s_waitcnt lgkmcnt(0)
	v_mul_f32_e32 v101, v103, v101
	v_cndmask_b32_e64 v101, v101, -v101, s[4:5]
	v_fmac_f32_e32 v101, v102, v131
	ds_bpermute_b32 v102, v133, v128
	ds_bpermute_b32 v103, v133, v129
	v_cndmask_b32_e64 v101, v131, v101, s[6:7]
	s_waitcnt lgkmcnt(1)
	v_mul_f32_e32 v102, v119, v102
	v_cndmask_b32_e64 v102, v102, -v102, s[4:5]
	v_fmac_f32_e32 v102, v118, v128
	ds_bpermute_b32 v118, v133, v108
	s_waitcnt lgkmcnt(1)
	v_mul_f32_e32 v103, v121, v103
	v_cndmask_b32_e64 v103, v103, -v103, s[4:5]
	v_fmac_f32_e32 v103, v120, v129
	v_cndmask_b32_e64 v102, v128, v102, s[6:7]
	s_waitcnt lgkmcnt(0)
	v_mul_f32_e32 v115, v115, v118
	v_cndmask_b32_e64 v115, v115, -v115, s[4:5]
	v_fmac_f32_e32 v115, v114, v108
	ds_bpermute_b32 v114, v133, v109
	v_cndmask_b32_e64 v103, v129, v103, s[6:7]
	v_cndmask_b32_e64 v108, v108, v115, s[6:7]
	s_waitcnt lgkmcnt(0)
	v_mul_f32_e32 v114, v117, v114
	v_cndmask_b32_e64 v114, v114, -v114, s[4:5]
	v_fmac_f32_e32 v114, v116, v109
	v_cndmask_b32_e64 v109, v109, v114, s[6:7]
	ds_bpermute_b32 v114, v133, v124
	s_waitcnt lgkmcnt(0)
	v_mul_f32_e32 v111, v111, v114
	v_cndmask_b32_e64 v111, v111, -v111, s[4:5]
	v_fmac_f32_e32 v111, v110, v124
	v_cndmask_b32_e64 v110, v124, v111, s[6:7]
	ds_bpermute_b32 v111, v133, v125
	s_waitcnt lgkmcnt(0)
	v_mul_f32_e32 v111, v113, v111
	v_cndmask_b32_e64 v111, v111, -v111, s[4:5]
	v_fmac_f32_e32 v111, v112, v125
	v_cndmask_b32_e64 v111, v125, v111, s[6:7]
	s_cbranch_vccnz .LBB0_728
	v_pk_mul_f32 v[102:103], v[102:103], s[42:43] op_sel_hi:[1,0]
	v_pk_mul_f32 v[100:101], v[100:101], s[42:43] op_sel_hi:[1,0]
	v_pk_mul_f32 v[110:111], v[110:111], s[42:43] op_sel_hi:[1,0]
	v_pk_mul_f32 v[108:109], v[108:109], s[42:43] op_sel_hi:[1,0]
	v_pk_mul_f32 v[98:99], v[98:99], s[42:43] op_sel_hi:[1,0]
	v_pk_mul_f32 v[96:97], v[96:97], s[42:43] op_sel_hi:[1,0]
	v_pk_mul_f32 v[106:107], v[106:107], s[42:43] op_sel_hi:[1,0]
	v_pk_mul_f32 v[104:105], v[104:105], s[42:43] op_sel_hi:[1,0]

; __device__ __forceinline__ float fast_sigmoid(float a) { return __builtin_amdgcn_rcpf(1.0f + __expf(-a)); }
;     __device__ __forceinline__ void operator()(const Acc& acc, const Unit& u, int wr, int wc, int fr, int fq) const {
;     ...
;                 const int row = u.pm * 256 + ai * 128 + wr * 64 + m * 16 + fr;
;                 const float rs = rsqrtf(ss1[row] * (1.0f / DM) + EPS);
;                 const int posidx = row < MPROMPT ? (row & 2047) : 2048;
;                 f32x4 v[2][2];
; #pragma unroll
;                 for (int bj = 0; bj < 2; ++bj)
; #pragma unroll
;                     for (int n = 0; n < 2; ++n) v[bj][n] = acc[ai][bj][m][n] * rs;
;     ...
;                 } else if (kind == 7) {
; #pragma unroll
;                     for (int bj = 0; bj < 2; ++bj)
; #pragma unroll
;                         for (int n = 0; n < 2; ++n)
; #pragma unroll
;                             for (int j = 0; j < 4; ++j) v[bj][n][j] = fast_sigmoid(v[bj][n][j]);
.LBB0_734:
	s_nop 0
	v_or_b32_e32 v106, 32, v160
	v_ashrrev_i32_e32 v107, 31, v106
	v_lshl_add_u64 v[96:97], v[106:107], 2, s[28:29]
	v_mov_b32_e32 v96, v182
	v_bitop3_b32 v107, v160, s92, 32 bitop3:0xc8
	v_cmp_lt_i32_e64 s[18:19], s75, v106
	s_mov_b64 s[0:1], -1
	s_nop 0
	v_fmamk_f32 v96, v96, 0x3a800000, v174
	v_cmp_gt_f32_e32 vcc, s74, v96
	v_mul_f32_e32 v97, 0x4b800000, v96
	s_nop 0
	v_cndmask_b32_e32 v96, v96, v97, vcc
	v_rsq_f32_e32 v96, v96
	s_nop 0
	v_mul_f32_e32 v97, 0x45800000, v96
	v_cndmask_b32_e32 v100, v96, v97, vcc
	v_cmp_gt_i32_e32 vcc, s64, v106
	v_pk_mul_f32 v[108:109], v[94:95], v[100:101] op_sel_hi:[1,0]
	v_pk_mul_f32 v[112:113], v[92:93], v[100:101] op_sel_hi:[1,0]
	v_pk_mul_f32 v[104:105], v[90:91], v[100:101] op_sel_hi:[1,0]
	v_pk_mul_f32 v[110:111], v[88:89], v[100:101] op_sel_hi:[1,0]
	v_pk_mul_f32 v[98:99], v[86:87], v[100:101] op_sel_hi:[1,0]
	v_pk_mul_f32 v[102:103], v[84:85], v[100:101] op_sel_hi:[1,0]
	v_pk_mul_f32 v[96:97], v[82:83], v[100:101] op_sel_hi:[1,0]
	v_pk_mul_f32 v[100:101], v[80:81], v[100:101] op_sel_hi:[1,0]
	v_cndmask_b32_e32 v116, v177, v107, vcc
	s_and_b64 vcc, exec, s[16:17]
	s_cbranch_vccnz .LBB0_745
	s_and_b64 vcc, exec, s[12:13]
	s_cbranch_vccnz .LBB0_742
	s_cmp_gt_i32 s49, 6
	s_cbranch_scc0 .LBB0_738
	v_mul_f32_e32 v80, 0xbfb8aa3b, v112
	v_exp_f32_e32 v80, v80
	v_mul_f32_e32 v81, 0xbfb8aa3b, v113
	v_exp_f32_e32 v81, v81
	v_mul_f32_e32 v82, 0xbfb8aa3b, v109
	v_add_f32_e32 v80, 1.0, v80
	v_rcp_f32_e32 v84, v80
	v_mul_f32_e32 v80, 0xbfb8aa3b, v108
	v_exp_f32_e32 v80, v80
	v_exp_f32_e32 v82, v82
	v_add_f32_e32 v81, 1.0, v81
	v_rcp_f32_e32 v85, v81
	v_add_f32_e32 v80, 1.0, v80
	v_mul_f32_e32 v81, 0xbfb8aa3b, v110
	v_rcp_f32_e32 v86, v80
	v_add_f32_e32 v80, 1.0, v82
	v_exp_f32_e32 v81, v81
	v_mul_f32_e32 v82, 0xbfb8aa3b, v111
	v_exp_f32_e32 v82, v82
	v_rcp_f32_e32 v87, v80
	v_add_f32_e32 v80, 1.0, v81
	v_mul_f32_e32 v81, 0xbfb8aa3b, v104
	v_rcp_f32_e32 v92, v80
	v_add_f32_e32 v80, 1.0, v82
	v_exp_f32_e32 v81, v81
	v_mul_f32_e32 v82, 0xbfb8aa3b, v105
	v_exp_f32_e32 v82, v82
	v_rcp_f32_e32 v93, v80
	v_add_f32_e32 v80, 1.0, v81
	v_rcp_f32_e32 v94, v80
	v_add_f32_e32 v80, 1.0, v82
	v_mul_f32_e32 v81, 0xbfb8aa3b, v102
	v_mul_f32_e32 v82, 0xbfb8aa3b, v103
	v_exp_f32_e32 v81, v81
	v_exp_f32_e32 v82, v82
	v_rcp_f32_e32 v95, v80
	v_mul_f32_e32 v83, 0xbfb8aa3b, v99
	v_add_f32_e32 v80, 1.0, v81
	v_add_f32_e32 v81, 1.0, v82
	v_mul_f32_e32 v82, 0xbfb8aa3b, v98
	v_mul_f32_e32 v88, 0xbfb8aa3b, v100
	v_mul_f32_e32 v89, 0xbfb8aa3b, v101
	v_mul_f32_e32 v90, 0xbfb8aa3b, v96
	v_mul_f32_e32 v91, 0xbfb8aa3b, v97
	v_exp_f32_e32 v82, v82
	v_exp_f32_e32 v83, v83
	v_exp_f32_e32 v88, v88
	v_exp_f32_e32 v89, v89
	v_exp_f32_e32 v90, v90
	v_exp_f32_e32 v91, v91
	v_add_f32_e32 v82, 1.0, v82
	v_add_f32_e32 v83, 1.0, v83
	v_add_f32_e32 v88, 1.0, v88
	v_add_f32_e32 v89, 1.0, v89
	v_add_f32_e32 v90, 1.0, v90
	v_add_f32_e32 v91, 1.0, v91
	v_rcp_f32_e32 v80, v80
	v_rcp_f32_e32 v81, v81
	v_rcp_f32_e32 v82, v82
	v_rcp_f32_e32 v83, v83
	v_rcp_f32_e32 v88, v88
	v_rcp_f32_e32 v89, v89
	v_rcp_f32_e32 v90, v90
	v_rcp_f32_e32 v91, v91
	s_mov_b64 s[0:1], 0

;     __device__ __forceinline__ void operator()(const Acc& acc, const Unit& u, int wr, int wc, int fr, int fq) const {
;     ...
;                 } else if (kind == 3 || kind == 4) {
;                     const float ksc = (kind == 4) ? 0.0625f : 1.0f;
; #pragma unroll
;                     for (int bj = 0; bj < 2; ++bj)
; #pragma unroll
;                         for (int n = 0; n < 2; ++n) {
;                             const int i0 = (wc * 64 + bj * 32 + fq * 8 + n * 4) >> 1;
;                             const f32x4 cs = *(const f32x4*)(rrot + ((size_t)posidx * 128 + i0) * 2);
;                             const f32x4 x = v[bj][n]; f32x4 o;
;                             o[0] = (x[0] * cs[0] - x[1] * cs[1]) * ksc; o[1] = (x[1] * cs[0] + x[0] * cs[1]) * ksc;
;                             o[2] = (x[2] * cs[2] - x[3] * cs[3]) * ksc; o[3] = (x[3] * cs[2] + x[2] * cs[3]) * ksc;
;                             v[bj][n] = o;
;                         }
.LBB0_742:
	s_and_b64 vcc, exec, s[0:1]
	s_cbranch_vccz .LBB0_744
	v_lshlrev_b32_e32 v80, 2, v170
	v_lshl_or_b32 v114, v116, 10, v80
	v_add_u32_e32 v236, 0x4000, v114
	global_load_dwordx4 v[212:215], v236, s[20:21] offset:16
	global_load_dwordx4 v[216:219], v236, s[20:21]
	global_load_dwordx4 v[220:223], v236, s[20:21] offset:144
	global_load_dwordx4 v[224:227], v236, s[20:21] offset:128
	s_waitcnt vmcnt(6)
	v_mov_b32_e32 v80, v188
	v_mov_b32_e32 v81, v189
	v_mov_b32_e32 v82, v190
	v_mov_b32_e32 v83, v191
	v_mov_b32_e32 v84, v192
	v_mov_b32_e32 v85, v193
	v_mov_b32_e32 v86, v194
	v_mov_b32_e32 v87, v195
	v_pk_mul_f32 v[88:89], v[112:113], v[84:85] op_sel:[1,1] op_sel_hi:[0,1]
	v_pk_fma_f32 v[90:91], v[112:113], v[84:85], v[88:89] neg_lo:[0,0,1] neg_hi:[0,0,1]
	v_pk_fma_f32 v[84:85], v[112:113], v[84:85], v[88:89] op_sel_hi:[1,0,1]
	v_mul_f32_e32 v88, v109, v87
	v_mov_b32_e32 v91, v85
	v_pk_mul_f32 v[84:85], v[156:157], v[90:91] op_sel_hi:[0,1]
	v_mul_f32_e32 v90, v109, v86
	v_pk_fma_f32 v[88:89], v[108:109], v[86:87], v[88:89] op_sel_hi:[1,1,0] neg_lo:[0,0,1] neg_hi:[0,0,1]
	v_pk_fma_f32 v[86:87], v[108:109], v[86:87], v[90:91] op_sel:[1,0,0] op_sel_hi:[0,1,0]
	v_mov_b32_e32 v89, v87
	v_pk_mul_f32 v[86:87], v[156:157], v[88:89] op_sel_hi:[0,1]
	v_pk_mul_f32 v[88:89], v[110:111], v[80:81] op_sel:[1,1] op_sel_hi:[0,1]
	v_pk_fma_f32 v[90:91], v[110:111], v[80:81], v[88:89] neg_lo:[0,0,1] neg_hi:[0,0,1]
	v_pk_fma_f32 v[80:81], v[110:111], v[80:81], v[88:89] op_sel_hi:[1,0,1]
	v_mul_f32_e32 v88, v105, v82
	v_mul_f32_e32 v80, v105, v83
	v_mov_b32_e32 v91, v81
	v_pk_fma_f32 v[80:81], v[104:105], v[82:83], v[80:81] op_sel_hi:[1,1,0] neg_lo:[0,0,1] neg_hi:[0,0,1]
	v_pk_fma_f32 v[82:83], v[104:105], v[82:83], v[88:89] op_sel:[1,0,0] op_sel_hi:[0,1,0]
	v_mov_b32_e32 v81, v83
	v_pk_mul_f32 v[92:93], v[156:157], v[90:91] op_sel_hi:[0,1]
	v_pk_mul_f32 v[94:95], v[156:157], v[80:81] op_sel_hi:[0,1]
	v_mov_b32_e32 v88, v196
	v_mov_b32_e32 v89, v197
	v_mov_b32_e32 v90, v198
	v_mov_b32_e32 v91, v199
	v_mov_b32_e32 v80, v200
	v_mov_b32_e32 v81, v201
	v_mov_b32_e32 v82, v202
	v_mov_b32_e32 v83, v203
	s_nop 0
	v_pk_mul_f32 v[114:115], v[102:103], v[80:81] op_sel:[1,1] op_sel_hi:[0,1]
	v_pk_fma_f32 v[118:119], v[102:103], v[80:81], v[114:115] neg_lo:[0,0,1] neg_hi:[0,0,1]
	v_pk_fma_f32 v[80:81], v[102:103], v[80:81], v[114:115] op_sel_hi:[1,0,1]
	v_mul_f32_e32 v114, v99, v83
	v_mov_b32_e32 v119, v81
	v_pk_mul_f32 v[80:81], v[156:157], v[118:119] op_sel_hi:[0,1]
	v_mul_f32_e32 v118, v99, v82
	v_pk_fma_f32 v[114:115], v[98:99], v[82:83], v[114:115] op_sel_hi:[1,1,0] neg_lo:[0,0,1] neg_hi:[0,0,1]
	v_pk_fma_f32 v[82:83], v[98:99], v[82:83], v[118:119] op_sel:[1,0,0] op_sel_hi:[0,1,0]
	v_mov_b32_e32 v115, v83
	v_pk_mul_f32 v[82:83], v[156:157], v[114:115] op_sel_hi:[0,1]
	v_pk_mul_f32 v[114:115], v[100:101], v[88:89] op_sel:[1,1] op_sel_hi:[0,1]
	v_pk_fma_f32 v[118:119], v[100:101], v[88:89], v[114:115] neg_lo:[0,0,1] neg_hi:[0,0,1]
	v_pk_fma_f32 v[88:89], v[100:101], v[88:89], v[114:115] op_sel_hi:[1,0,1]
	v_mul_f32_e32 v114, v97, v91
	v_mov_b32_e32 v119, v89
	v_pk_mul_f32 v[88:89], v[156:157], v[118:119] op_sel_hi:[0,1]
	v_mul_f32_e32 v118, v97, v90
	v_pk_fma_f32 v[114:115], v[96:97], v[90:91], v[114:115] op_sel_hi:[1,1,0] neg_lo:[0,0,1] neg_hi:[0,0,1]
	v_pk_fma_f32 v[90:91], v[96:97], v[90:91], v[118:119] op_sel:[1,0,0] op_sel_hi:[0,1,0]
	v_mov_b32_e32 v115, v91
	v_pk_mul_f32 v[90:91], v[156:157], v[114:115] op_sel_hi:[0,1]

;     __device__ __forceinline__ void operator()(const Acc& acc, const Unit& u, int wr, int wc, int fr, int fq) const {
;     ...
;                 if (kind <= 1) {
;                     float s2 = 0.f;
; #pragma unroll
;                     for (int bj = 0; bj < 2; ++bj)
; #pragma unroll
;                         for (int n = 0; n < 2; ++n) s2 += (v[bj][n][0] * v[bj][n][0] + v[bj][n][1] * v[bj][n][1]) + (v[bj][n][2] * v[bj][n][2] + v[bj][n][3] * v[bj][n][3]);
;                     s2 += __shfl_xor(s2, 16); s2 += __shfl_xor(s2, 32);
;                     const float r = rsqrtf(s2 * (1.0f / 64.0f) + EPS);
; #pragma unroll
;                     for (int bj = 0; bj < 2; ++bj)
; #pragma unroll
;                         for (int n = 0; n < 2; ++n) { const f32x4 gv = *(const f32x4*)(gp + bj * 32 + fq * 8 + n * 4); v[bj][n] = v[bj][n] * r * gv; }
; #pragma unroll
;                     for (int n = 0; n < 2; ++n) { const f32x4 csa = *(const f32x4*)(rope + ((size_t)posidx * 8 + 4 * n) * 2), csb = *(const f32x4*)(rope + ((size_t)posidx * 8 + 4 * n) * 2 + 4);
;                         const float cc[4] = {csa[0], csa[2], csb[0], csb[2]}, sn[4] = {csa[1], csa[3], csb[1], csb[3]};
; #pragma unroll
;                         for (int j = 0; j < 4; ++j) { const float mine = v[0][n][j], other = __shfl_xor(mine, 16);
;                             const float rot = (fq == 0) ? (mine * cc[j] - other * sn[j]) : (mine * cc[j] + other * sn[j]);
;                             v[0][n][j] = (fq < 2) ? rot : mine; } }
;                     if (kind == 0) {
; #pragma unroll
;                         for (int bj = 0; bj < 2; ++bj)
; #pragma unroll
;                             for (int n = 0; n < 2; ++n) v[bj][n] = v[bj][n] * 0.125f;
;                     }
.LBB0_745:
	s_andn2_b64 vcc, exec, s[0:1]
	s_cbranch_vccnz .LBB0_748
	v_pk_mul_f32 v[80:81], v[108:109], v[108:109]
	v_pk_mul_f32 v[82:83], v[112:113], v[112:113]
	s_nop 0
	v_pk_mov_b32 v[84:85], v[82:83], v[80:81] op_sel:[1,0]
	v_mov_b32_e32 v83, v81
	v_pk_add_f32 v[80:81], v[84:85], v[82:83]
	v_pk_mul_f32 v[82:83], v[104:105], v[104:105]
	v_pk_add_f32 v[80:81], v[80:81], v[80:81] op_sel_hi:[0,1]
	v_pk_mul_f32 v[84:85], v[110:111], v[110:111]
	v_mul_f32_e32 v80, v102, v102
	v_pk_mov_b32 v[86:87], v[84:85], v[82:83] op_sel:[1,0]
	v_mov_b32_e32 v85, v83
	v_pk_add_f32 v[82:83], v[86:87], v[84:85]
	v_pk_fma_f32 v[84:85], v[102:103], v[102:103], v[80:81] op_sel_hi:[1,1,0]
	v_mul_f32_e32 v80, v98, v98
	v_pk_add_f32 v[82:83], v[82:83], v[82:83] op_sel_hi:[0,1]
	v_pk_fma_f32 v[86:87], v[98:99], v[98:99], v[80:81] op_sel_hi:[1,1,0]
	v_mul_f32_e32 v84, v100, v100
	v_mul_f32_e32 v86, v101, v101
	v_mul_f32_e32 v80, v96, v96
	v_mul_f32_e32 v82, v97, v97
	v_pk_add_f32 v[84:85], v[84:85], v[86:87]
	v_pk_add_f32 v[80:81], v[80:81], v[82:83]
	v_and_b32_e32 v82, 64, v178
	v_pk_add_f32 v[80:81], v[84:85], v[80:81]
	v_add_u32_e32 v82, 64, v82
	v_add_f32_e32 v80, v80, v81
	v_xor_b32_e32 v81, 16, v178
	v_cmp_lt_i32_e32 vcc, v81, v82
	s_nop 1
	v_cndmask_b32_e32 v81, v178, v81, vcc
	v_lshlrev_b32_e32 v117, 2, v81
	ds_bpermute_b32 v81, v117, v80
	s_waitcnt lgkmcnt(0)
	v_add_f32_e32 v80, v80, v81
	v_xor_b32_e32 v81, 32, v178
	v_cmp_lt_i32_e32 vcc, v81, v82
	s_nop 1
	v_cndmask_b32_e32 v81, v178, v81, vcc
	v_lshlrev_b32_e32 v81, 2, v81
	ds_bpermute_b32 v81, v81, v80
	s_waitcnt lgkmcnt(0)
	v_add_f32_e32 v80, v80, v81
	v_fmamk_f32 v80, v80, 0x3c800000, v174
	v_cmp_gt_f32_e32 vcc, s74, v80
	v_mul_f32_e32 v81, 0x4b800000, v80
	s_nop 0
	v_cndmask_b32_e32 v80, v80, v81, vcc
	v_rsq_f32_e32 v80, v80
	s_nop 0
	v_mul_f32_e32 v81, 0x45800000, v80
	v_cndmask_b32_e32 v84, v80, v81, vcc
	v_mov_b32_e32 v80, v188
	v_mov_b32_e32 v81, v189
	v_mov_b32_e32 v82, v190
	v_mov_b32_e32 v83, v191
	v_mov_b32_e32 v86, v192
	v_mov_b32_e32 v87, v193
	v_mov_b32_e32 v88, v194
	v_mov_b32_e32 v89, v195
	v_pk_mul_f32 v[90:91], v[112:113], v[84:85] op_sel_hi:[1,0]
	v_pk_mul_f32 v[92:93], v[108:109], v[84:85] op_sel_hi:[1,0]
	v_pk_mul_f32 v[94:95], v[98:99], v[84:85] op_sel_hi:[1,0]
	s_and_b64 vcc, exec, s[10:11]
	s_nop 0
	v_pk_mul_f32 v[112:113], v[88:89], v[92:93]
	v_pk_mul_f32 v[114:115], v[86:87], v[90:91]
	v_pk_mul_f32 v[86:87], v[110:111], v[84:85] op_sel_hi:[1,0]
	v_pk_mul_f32 v[88:89], v[104:105], v[84:85] op_sel_hi:[1,0]
	v_pk_mul_f32 v[92:93], v[80:81], v[86:87]
	v_pk_mul_f32 v[108:109], v[82:83], v[88:89]
	v_mov_b32_e32 v86, v196
	v_mov_b32_e32 v87, v197
	v_mov_b32_e32 v88, v198
	v_mov_b32_e32 v89, v199
	v_mov_b32_e32 v80, v200
	v_mov_b32_e32 v81, v201
	v_mov_b32_e32 v82, v202
	v_mov_b32_e32 v83, v203
	v_pk_mul_f32 v[90:91], v[102:103], v[84:85] op_sel_hi:[1,0]
	ds_bpermute_b32 v110, v117, v114
	s_nop 0
	v_pk_mul_f32 v[82:83], v[82:83], v[94:95]
	v_pk_mul_f32 v[94:95], v[100:101], v[84:85] op_sel_hi:[1,0]
	v_pk_mul_f32 v[84:85], v[96:97], v[84:85] op_sel_hi:[1,0]
	v_pk_mul_f32 v[80:81], v[80:81], v[90:91]
	v_pk_mul_f32 v[90:91], v[88:89], v[84:85]
	v_lshlrev_b32_e32 v84, 6, v116
	v_pk_mul_f32 v[88:89], v[86:87], v[94:95]
	s_waitcnt vmcnt(2)
	v_mov_b32_e32 v94, v212
	v_mov_b32_e32 v95, v213
	v_mov_b32_e32 v96, v214
	v_mov_b32_e32 v97, v215
	v_mov_b32_e32 v98, v216
	v_mov_b32_e32 v99, v217
	v_mov_b32_e32 v100, v218
	v_mov_b32_e32 v101, v219
	v_mov_b32_e32 v102, v220
	v_mov_b32_e32 v103, v221
	v_mov_b32_e32 v104, v222
	v_mov_b32_e32 v105, v223
	s_nop 0
	v_mov_b32_e32 v84, v224
	v_mov_b32_e32 v85, v225
	v_mov_b32_e32 v86, v226
	v_mov_b32_e32 v87, v227
	v_lshlrev_b32_e32 v236, 6, v116
	v_add_u32_e32 v236, 1024, v236
	global_load_dwordx4 v[212:215], v236, s[26:27] offset:48
	global_load_dwordx4 v[216:219], v236, s[26:27] offset:32
	global_load_dwordx4 v[220:223], v236, s[26:27] offset:16
	global_load_dwordx4 v[224:227], v236, s[26:27]
	s_waitcnt lgkmcnt(0)
	v_mul_f32_e32 v85, v85, v110
	v_cndmask_b32_e64 v85, v85, -v85, s[4:5]
	v_fmac_f32_e32 v85, v84, v114
	v_cndmask_b32_e64 v84, v114, v85, s[6:7]
	ds_bpermute_b32 v85, v117, v115
	s_waitcnt lgkmcnt(0)
	v_mul_f32_e32 v85, v87, v85
	v_cndmask_b32_e64 v85, v85, -v85, s[4:5]
	v_fmac_f32_e32 v85, v86, v115
	ds_bpermute_b32 v86, v117, v112
	ds_bpermute_b32 v87, v117, v113
	v_cndmask_b32_e64 v85, v115, v85, s[6:7]
	s_waitcnt lgkmcnt(1)
	v_mul_f32_e32 v86, v103, v86
	v_cndmask_b32_e64 v86, v86, -v86, s[4:5]
	v_fmac_f32_e32 v86, v102, v112
	ds_bpermute_b32 v102, v117, v92
	s_waitcnt lgkmcnt(1)
	v_mul_f32_e32 v87, v105, v87
	v_cndmask_b32_e64 v87, v87, -v87, s[4:5]
	v_fmac_f32_e32 v87, v104, v113
	v_cndmask_b32_e64 v86, v112, v86, s[6:7]
	s_waitcnt lgkmcnt(0)
	v_mul_f32_e32 v99, v99, v102
	v_cndmask_b32_e64 v99, v99, -v99, s[4:5]
	v_fmac_f32_e32 v99, v98, v92
	ds_bpermute_b32 v98, v117, v93
	v_cndmask_b32_e64 v87, v113, v87, s[6:7]
	v_cndmask_b32_e64 v92, v92, v99, s[6:7]
	s_waitcnt lgkmcnt(0)
	v_mul_f32_e32 v98, v101, v98
	v_cndmask_b32_e64 v98, v98, -v98, s[4:5]
	v_fmac_f32_e32 v98, v100, v93
	v_cndmask_b32_e64 v93, v93, v98, s[6:7]
	ds_bpermute_b32 v98, v117, v108
	s_waitcnt lgkmcnt(0)
	v_mul_f32_e32 v95, v95, v98
	v_cndmask_b32_e64 v95, v95, -v95, s[4:5]
	v_fmac_f32_e32 v95, v94, v108
	v_cndmask_b32_e64 v94, v108, v95, s[6:7]
	ds_bpermute_b32 v95, v117, v109
	s_waitcnt lgkmcnt(0)
	v_mul_f32_e32 v95, v97, v95
	v_cndmask_b32_e64 v95, v95, -v95, s[4:5]
	v_fmac_f32_e32 v95, v96, v109
	v_cndmask_b32_e64 v95, v109, v95, s[6:7]
	s_cbranch_vccnz .LBB0_748
	v_pk_mul_f32 v[86:87], v[86:87], s[42:43] op_sel_hi:[1,0]
	v_pk_mul_f32 v[84:85], v[84:85], s[42:43] op_sel_hi:[1,0]
	v_pk_mul_f32 v[94:95], v[94:95], s[42:43] op_sel_hi:[1,0]
	v_pk_mul_f32 v[92:93], v[92:93], s[42:43] op_sel_hi:[1,0]
	v_pk_mul_f32 v[82:83], v[82:83], s[42:43] op_sel_hi:[1,0]
	v_pk_mul_f32 v[80:81], v[80:81], s[42:43] op_sel_hi:[1,0]
	v_pk_mul_f32 v[90:91], v[90:91], s[42:43] op_sel_hi:[1,0]
	v_pk_mul_f32 v[88:89], v[88:89], s[42:43] op_sel_hi:[1,0]

; __device__ __forceinline__ float fast_sigmoid(float a) { return __builtin_amdgcn_rcpf(1.0f + __expf(-a)); }
;     __device__ __forceinline__ void operator()(const Acc& acc, const Unit& u, int wr, int wc, int fr, int fq) const {
;     ...
;                 const int row = u.pm * 256 + ai * 128 + wr * 64 + m * 16 + fr;
;                 const float rs = rsqrtf(ss1[row] * (1.0f / DM) + EPS);
;                 const int posidx = row < MPROMPT ? (row & 2047) : 2048;
;                 f32x4 v[2][2];
; #pragma unroll
;                 for (int bj = 0; bj < 2; ++bj)
; #pragma unroll
;                     for (int n = 0; n < 2; ++n) v[bj][n] = acc[ai][bj][m][n] * rs;
;     ...
;                 } else if (kind == 7) {
; #pragma unroll
;                     for (int bj = 0; bj < 2; ++bj)
; #pragma unroll
;                         for (int n = 0; n < 2; ++n)
; #pragma unroll
;                             for (int j = 0; j < 4; ++j) v[bj][n][j] = fast_sigmoid(v[bj][n][j]);
.LBB0_754:
	s_nop 0
	v_or_b32_e32 v90, 48, v160
	v_ashrrev_i32_e32 v91, 31, v90
	v_lshl_add_u64 v[80:81], v[90:91], 2, s[28:29]
	v_mov_b32_e32 v80, v183
	v_bitop3_b32 v91, v160, s96, 48 bitop3:0xc8
	v_cmp_lt_i32_e64 s[18:19], s75, v90
	s_mov_b64 s[0:1], -1
	s_nop 0
	v_fmamk_f32 v80, v80, 0x3a800000, v174
	v_cmp_gt_f32_e32 vcc, s74, v80
	v_mul_f32_e32 v81, 0x4b800000, v80
	s_nop 0
	v_cndmask_b32_e32 v80, v80, v81, vcc
	v_rsq_f32_e32 v80, v80
	s_nop 0
	v_mul_f32_e32 v81, 0x45800000, v80
	v_cndmask_b32_e32 v84, v80, v81, vcc
	v_cmp_gt_i32_e32 vcc, s64, v90
	v_pk_mul_f32 v[92:93], v[78:79], v[84:85] op_sel_hi:[1,0]
	v_pk_mul_f32 v[96:97], v[76:77], v[84:85] op_sel_hi:[1,0]
	v_pk_mul_f32 v[88:89], v[74:75], v[84:85] op_sel_hi:[1,0]
	v_pk_mul_f32 v[94:95], v[72:73], v[84:85] op_sel_hi:[1,0]
	v_pk_mul_f32 v[82:83], v[70:71], v[84:85] op_sel_hi:[1,0]
	v_pk_mul_f32 v[86:87], v[68:69], v[84:85] op_sel_hi:[1,0]
	v_pk_mul_f32 v[80:81], v[66:67], v[84:85] op_sel_hi:[1,0]
	v_pk_mul_f32 v[84:85], v[64:65], v[84:85] op_sel_hi:[1,0]
	v_cndmask_b32_e32 v100, v177, v91, vcc
	s_and_b64 vcc, exec, s[16:17]
	s_cbranch_vccnz .LBB0_765
	s_and_b64 vcc, exec, s[12:13]
	s_cbranch_vccnz .LBB0_762
	s_cmp_gt_i32 s49, 6
	s_cbranch_scc0 .LBB0_758
	v_mul_f32_e32 v64, 0xbfb8aa3b, v96
	v_exp_f32_e32 v64, v64
	v_mul_f32_e32 v65, 0xbfb8aa3b, v97
	v_exp_f32_e32 v65, v65
	v_mul_f32_e32 v66, 0xbfb8aa3b, v93
	v_add_f32_e32 v64, 1.0, v64
	v_rcp_f32_e32 v68, v64
	v_mul_f32_e32 v64, 0xbfb8aa3b, v92
	v_exp_f32_e32 v64, v64
	v_exp_f32_e32 v66, v66
	v_add_f32_e32 v65, 1.0, v65
	v_rcp_f32_e32 v69, v65
	v_add_f32_e32 v64, 1.0, v64
	v_mul_f32_e32 v65, 0xbfb8aa3b, v94
	v_rcp_f32_e32 v70, v64
	v_add_f32_e32 v64, 1.0, v66
	v_exp_f32_e32 v65, v65
	v_mul_f32_e32 v66, 0xbfb8aa3b, v95
	v_exp_f32_e32 v66, v66
	v_rcp_f32_e32 v71, v64
	v_add_f32_e32 v64, 1.0, v65
	v_mul_f32_e32 v65, 0xbfb8aa3b, v88
	v_rcp_f32_e32 v76, v64
	v_add_f32_e32 v64, 1.0, v66
	v_exp_f32_e32 v65, v65
	v_mul_f32_e32 v66, 0xbfb8aa3b, v89
	v_exp_f32_e32 v66, v66
	v_rcp_f32_e32 v77, v64
	v_add_f32_e32 v64, 1.0, v65
	v_rcp_f32_e32 v78, v64
	v_add_f32_e32 v64, 1.0, v66
	v_mul_f32_e32 v65, 0xbfb8aa3b, v86
	v_mul_f32_e32 v66, 0xbfb8aa3b, v87
	v_exp_f32_e32 v65, v65
	v_exp_f32_e32 v66, v66
	v_rcp_f32_e32 v79, v64
	v_mul_f32_e32 v67, 0xbfb8aa3b, v83
	v_add_f32_e32 v64, 1.0, v65
	v_add_f32_e32 v65, 1.0, v66
	v_mul_f32_e32 v66, 0xbfb8aa3b, v82
	v_mul_f32_e32 v72, 0xbfb8aa3b, v84
	v_mul_f32_e32 v73, 0xbfb8aa3b, v85
	v_mul_f32_e32 v74, 0xbfb8aa3b, v80
	v_mul_f32_e32 v75, 0xbfb8aa3b, v81
	v_exp_f32_e32 v66, v66
	v_exp_f32_e32 v67, v67
	v_exp_f32_e32 v72, v72
	v_exp_f32_e32 v73, v73
	v_exp_f32_e32 v74, v74
	v_exp_f32_e32 v75, v75
	v_add_f32_e32 v66, 1.0, v66
	v_add_f32_e32 v67, 1.0, v67
	v_add_f32_e32 v72, 1.0, v72
	v_add_f32_e32 v73, 1.0, v73
	v_add_f32_e32 v74, 1.0, v74
	v_add_f32_e32 v75, 1.0, v75
	v_rcp_f32_e32 v64, v64
	v_rcp_f32_e32 v65, v65
	v_rcp_f32_e32 v66, v66
	v_rcp_f32_e32 v67, v67
	v_rcp_f32_e32 v72, v72
	v_rcp_f32_e32 v73, v73
	v_rcp_f32_e32 v74, v74
	v_rcp_f32_e32 v75, v75
	s_mov_b64 s[0:1], 0

;     __device__ __forceinline__ void operator()(const Acc& acc, const Unit& u, int wr, int wc, int fr, int fq) const {
;     ...
;                 } else if (kind == 3 || kind == 4) {
;                     const float ksc = (kind == 4) ? 0.0625f : 1.0f;
; #pragma unroll
;                     for (int bj = 0; bj < 2; ++bj)
; #pragma unroll
;                         for (int n = 0; n < 2; ++n) {
;                             const int i0 = (wc * 64 + bj * 32 + fq * 8 + n * 4) >> 1;
;                             const f32x4 cs = *(const f32x4*)(rrot + ((size_t)posidx * 128 + i0) * 2);
;                             const f32x4 x = v[bj][n]; f32x4 o;
;                             o[0] = (x[0] * cs[0] - x[1] * cs[1]) * ksc; o[1] = (x[1] * cs[0] + x[0] * cs[1]) * ksc;
;                             o[2] = (x[2] * cs[2] - x[3] * cs[3]) * ksc; o[3] = (x[3] * cs[2] + x[2] * cs[3]) * ksc;
;                             v[bj][n] = o;
;                         }
.LBB0_762:
	s_and_b64 vcc, exec, s[0:1]
	s_cbranch_vccz .LBB0_764
	v_lshlrev_b32_e32 v64, 2, v170
	v_lshl_or_b32 v98, v100, 10, v64
	v_add_u32_e32 v236, 0x14000, v98
	global_load_dwordx4 v[188:191], v236, s[20:21] offset:16
	global_load_dwordx4 v[192:195], v236, s[20:21]
	global_load_dwordx4 v[196:199], v236, s[20:21] offset:144
	global_load_dwordx4 v[200:203], v236, s[20:21] offset:128
	s_waitcnt vmcnt(6)
	v_mov_b32_e32 v64, v212
	v_mov_b32_e32 v65, v213
	v_mov_b32_e32 v66, v214
	v_mov_b32_e32 v67, v215
	v_mov_b32_e32 v68, v216
	v_mov_b32_e32 v69, v217
	v_mov_b32_e32 v70, v218
	v_mov_b32_e32 v71, v219
	v_pk_mul_f32 v[72:73], v[96:97], v[68:69] op_sel:[1,1] op_sel_hi:[0,1]
	v_pk_fma_f32 v[74:75], v[96:97], v[68:69], v[72:73] neg_lo:[0,0,1] neg_hi:[0,0,1]
	v_pk_fma_f32 v[68:69], v[96:97], v[68:69], v[72:73] op_sel_hi:[1,0,1]
	v_mul_f32_e32 v72, v93, v71
	v_mov_b32_e32 v75, v69
	v_pk_mul_f32 v[68:69], v[156:157], v[74:75] op_sel_hi:[0,1]
	v_mul_f32_e32 v74, v93, v70
	v_pk_fma_f32 v[72:73], v[92:93], v[70:71], v[72:73] op_sel_hi:[1,1,0] neg_lo:[0,0,1] neg_hi:[0,0,1]
	v_pk_fma_f32 v[70:71], v[92:93], v[70:71], v[74:75] op_sel:[1,0,0] op_sel_hi:[0,1,0]
	v_mov_b32_e32 v73, v71
	v_pk_mul_f32 v[70:71], v[156:157], v[72:73] op_sel_hi:[0,1]
	v_pk_mul_f32 v[72:73], v[94:95], v[64:65] op_sel:[1,1] op_sel_hi:[0,1]
	v_pk_fma_f32 v[74:75], v[94:95], v[64:65], v[72:73] neg_lo:[0,0,1] neg_hi:[0,0,1]
	v_pk_fma_f32 v[64:65], v[94:95], v[64:65], v[72:73] op_sel_hi:[1,0,1]
	v_mul_f32_e32 v72, v89, v66
	v_mul_f32_e32 v64, v89, v67
	v_mov_b32_e32 v75, v65
	v_pk_fma_f32 v[64:65], v[88:89], v[66:67], v[64:65] op_sel_hi:[1,1,0] neg_lo:[0,0,1] neg_hi:[0,0,1]
	v_pk_fma_f32 v[66:67], v[88:89], v[66:67], v[72:73] op_sel:[1,0,0] op_sel_hi:[0,1,0]
	v_mov_b32_e32 v65, v67
	v_pk_mul_f32 v[76:77], v[156:157], v[74:75] op_sel_hi:[0,1]
	v_pk_mul_f32 v[78:79], v[156:157], v[64:65] op_sel_hi:[0,1]
	v_mov_b32_e32 v72, v220
	v_mov_b32_e32 v73, v221
	v_mov_b32_e32 v74, v222
	v_mov_b32_e32 v75, v223
	v_mov_b32_e32 v64, v224
	v_mov_b32_e32 v65, v225
	v_mov_b32_e32 v66, v226
	v_mov_b32_e32 v67, v227
	s_nop 0
	v_pk_mul_f32 v[98:99], v[86:87], v[64:65] op_sel:[1,1] op_sel_hi:[0,1]
	v_pk_fma_f32 v[102:103], v[86:87], v[64:65], v[98:99] neg_lo:[0,0,1] neg_hi:[0,0,1]
	v_pk_fma_f32 v[64:65], v[86:87], v[64:65], v[98:99] op_sel_hi:[1,0,1]
	v_mul_f32_e32 v98, v83, v67
	v_mov_b32_e32 v103, v65
	v_pk_mul_f32 v[64:65], v[156:157], v[102:103] op_sel_hi:[0,1]
	v_mul_f32_e32 v102, v83, v66
	v_pk_fma_f32 v[98:99], v[82:83], v[66:67], v[98:99] op_sel_hi:[1,1,0] neg_lo:[0,0,1] neg_hi:[0,0,1]
	v_pk_fma_f32 v[66:67], v[82:83], v[66:67], v[102:103] op_sel:[1,0,0] op_sel_hi:[0,1,0]
	v_mov_b32_e32 v99, v67
	v_pk_mul_f32 v[66:67], v[156:157], v[98:99] op_sel_hi:[0,1]
	v_pk_mul_f32 v[98:99], v[84:85], v[72:73] op_sel:[1,1] op_sel_hi:[0,1]
	v_pk_fma_f32 v[102:103], v[84:85], v[72:73], v[98:99] neg_lo:[0,0,1] neg_hi:[0,0,1]
	v_pk_fma_f32 v[72:73], v[84:85], v[72:73], v[98:99] op_sel_hi:[1,0,1]
	v_mul_f32_e32 v98, v81, v75
	v_mov_b32_e32 v103, v73
	v_pk_mul_f32 v[72:73], v[156:157], v[102:103] op_sel_hi:[0,1]
	v_mul_f32_e32 v102, v81, v74
	v_pk_fma_f32 v[98:99], v[80:81], v[74:75], v[98:99] op_sel_hi:[1,1,0] neg_lo:[0,0,1] neg_hi:[0,0,1]
	v_pk_fma_f32 v[74:75], v[80:81], v[74:75], v[102:103] op_sel:[1,0,0] op_sel_hi:[0,1,0]
	v_mov_b32_e32 v99, v75
	v_pk_mul_f32 v[74:75], v[156:157], v[98:99] op_sel_hi:[0,1]

;     __device__ __forceinline__ void operator()(const Acc& acc, const Unit& u, int wr, int wc, int fr, int fq) const {
;     ...
;                 if (kind <= 1) {
;                     float s2 = 0.f;
; #pragma unroll
;                     for (int bj = 0; bj < 2; ++bj)
; #pragma unroll
;                         for (int n = 0; n < 2; ++n) s2 += (v[bj][n][0] * v[bj][n][0] + v[bj][n][1] * v[bj][n][1]) + (v[bj][n][2] * v[bj][n][2] + v[bj][n][3] * v[bj][n][3]);
;                     s2 += __shfl_xor(s2, 16); s2 += __shfl_xor(s2, 32);
;                     const float r = rsqrtf(s2 * (1.0f / 64.0f) + EPS);
; #pragma unroll
;                     for (int bj = 0; bj < 2; ++bj)
; #pragma unroll
;                         for (int n = 0; n < 2; ++n) { const f32x4 gv = *(const f32x4*)(gp + bj * 32 + fq * 8 + n * 4); v[bj][n] = v[bj][n] * r * gv; }
; #pragma unroll
;                     for (int n = 0; n < 2; ++n) { const f32x4 csa = *(const f32x4*)(rope + ((size_t)posidx * 8 + 4 * n) * 2), csb = *(const f32x4*)(rope + ((size_t)posidx * 8 + 4 * n) * 2 + 4);
;                         const float cc[4] = {csa[0], csa[2], csb[0], csb[2]}, sn[4] = {csa[1], csa[3], csb[1], csb[3]};
; #pragma unroll
;                         for (int j = 0; j < 4; ++j) { const float mine = v[0][n][j], other = __shfl_xor(mine, 16);
;                             const float rot = (fq == 0) ? (mine * cc[j] - other * sn[j]) : (mine * cc[j] + other * sn[j]);
;                             v[0][n][j] = (fq < 2) ? rot : mine; } }
;                     if (kind == 0) {
; #pragma unroll
;                         for (int bj = 0; bj < 2; ++bj)
; #pragma unroll
;                             for (int n = 0; n < 2; ++n) v[bj][n] = v[bj][n] * 0.125f;
;                     }
.LBB0_765:
	s_andn2_b64 vcc, exec, s[0:1]
	s_cbranch_vccnz .LBB0_768
	v_pk_mul_f32 v[64:65], v[92:93], v[92:93]
	v_pk_mul_f32 v[66:67], v[96:97], v[96:97]
	s_nop 0
	v_pk_mov_b32 v[68:69], v[66:67], v[64:65] op_sel:[1,0]
	v_mov_b32_e32 v67, v65
	v_pk_add_f32 v[64:65], v[68:69], v[66:67]
	v_pk_mul_f32 v[66:67], v[88:89], v[88:89]
	v_pk_add_f32 v[64:65], v[64:65], v[64:65] op_sel_hi:[0,1]
	v_pk_mul_f32 v[68:69], v[94:95], v[94:95]
	v_mul_f32_e32 v64, v86, v86
	v_pk_mov_b32 v[70:71], v[68:69], v[66:67] op_sel:[1,0]
	v_mov_b32_e32 v69, v67
	v_pk_add_f32 v[66:67], v[70:71], v[68:69]
	v_pk_fma_f32 v[68:69], v[86:87], v[86:87], v[64:65] op_sel_hi:[1,1,0]
	v_mul_f32_e32 v64, v82, v82
	v_pk_add_f32 v[66:67], v[66:67], v[66:67] op_sel_hi:[0,1]
	v_pk_fma_f32 v[70:71], v[82:83], v[82:83], v[64:65] op_sel_hi:[1,1,0]
	v_mul_f32_e32 v68, v84, v84
	v_mul_f32_e32 v70, v85, v85
	v_mul_f32_e32 v64, v80, v80
	v_mul_f32_e32 v66, v81, v81
	v_pk_add_f32 v[68:69], v[68:69], v[70:71]
	v_pk_add_f32 v[64:65], v[64:65], v[66:67]
	v_and_b32_e32 v66, 64, v178
	v_pk_add_f32 v[64:65], v[68:69], v[64:65]
	v_add_u32_e32 v66, 64, v66
	v_add_f32_e32 v64, v64, v65
	v_xor_b32_e32 v65, 16, v178
	v_cmp_lt_i32_e32 vcc, v65, v66
	s_nop 1
	v_cndmask_b32_e32 v65, v178, v65, vcc
	v_lshlrev_b32_e32 v101, 2, v65
	ds_bpermute_b32 v65, v101, v64
	s_waitcnt lgkmcnt(0)
	v_add_f32_e32 v64, v64, v65
	v_xor_b32_e32 v65, 32, v178
	v_cmp_lt_i32_e32 vcc, v65, v66
	s_nop 1
	v_cndmask_b32_e32 v65, v178, v65, vcc
	v_lshlrev_b32_e32 v65, 2, v65
	ds_bpermute_b32 v65, v65, v64
	s_waitcnt lgkmcnt(0)
	v_add_f32_e32 v64, v64, v65
	v_fmamk_f32 v64, v64, 0x3c800000, v174
	v_cmp_gt_f32_e32 vcc, s74, v64
	v_mul_f32_e32 v65, 0x4b800000, v64
	s_nop 0
	v_cndmask_b32_e32 v64, v64, v65, vcc
	v_rsq_f32_e32 v64, v64
	s_nop 0
	v_mul_f32_e32 v65, 0x45800000, v64
	v_cndmask_b32_e32 v68, v64, v65, vcc
	v_mov_b32_e32 v64, v188
	v_mov_b32_e32 v65, v189
	v_mov_b32_e32 v66, v190
	v_mov_b32_e32 v67, v191
	v_mov_b32_e32 v70, v192
	v_mov_b32_e32 v71, v193
	v_mov_b32_e32 v72, v194
	v_mov_b32_e32 v73, v195
	v_pk_mul_f32 v[74:75], v[96:97], v[68:69] op_sel_hi:[1,0]
	v_pk_mul_f32 v[76:77], v[92:93], v[68:69] op_sel_hi:[1,0]
	v_pk_mul_f32 v[78:79], v[82:83], v[68:69] op_sel_hi:[1,0]
	s_and_b64 vcc, exec, s[10:11]
	s_nop 0
	v_pk_mul_f32 v[96:97], v[72:73], v[76:77]
	v_pk_mul_f32 v[98:99], v[70:71], v[74:75]
	v_pk_mul_f32 v[70:71], v[94:95], v[68:69] op_sel_hi:[1,0]
	v_pk_mul_f32 v[72:73], v[88:89], v[68:69] op_sel_hi:[1,0]
	v_pk_mul_f32 v[76:77], v[64:65], v[70:71]
	v_pk_mul_f32 v[92:93], v[66:67], v[72:73]
	v_mov_b32_e32 v70, v196
	v_mov_b32_e32 v71, v197
	v_mov_b32_e32 v72, v198
	v_mov_b32_e32 v73, v199
	v_mov_b32_e32 v64, v200
	v_mov_b32_e32 v65, v201
	v_mov_b32_e32 v66, v202
	v_mov_b32_e32 v67, v203
	v_pk_mul_f32 v[74:75], v[86:87], v[68:69] op_sel_hi:[1,0]
	ds_bpermute_b32 v94, v101, v98
	s_nop 0
	v_pk_mul_f32 v[66:67], v[66:67], v[78:79]
	v_pk_mul_f32 v[78:79], v[84:85], v[68:69] op_sel_hi:[1,0]
	v_pk_mul_f32 v[68:69], v[80:81], v[68:69] op_sel_hi:[1,0]
	v_pk_mul_f32 v[64:65], v[64:65], v[74:75]
	v_pk_mul_f32 v[74:75], v[72:73], v[68:69]
	v_lshlrev_b32_e32 v68, 6, v100
	v_pk_mul_f32 v[72:73], v[70:71], v[78:79]
	s_waitcnt vmcnt(2)
	v_mov_b32_e32 v78, v212
	v_mov_b32_e32 v79, v213
	v_mov_b32_e32 v80, v214
	v_mov_b32_e32 v81, v215
	v_mov_b32_e32 v82, v216
	v_mov_b32_e32 v83, v217
	v_mov_b32_e32 v84, v218
	v_mov_b32_e32 v85, v219
	v_mov_b32_e32 v86, v220
	v_mov_b32_e32 v87, v221
	v_mov_b32_e32 v88, v222
	v_mov_b32_e32 v89, v223
	s_nop 0
	v_mov_b32_e32 v68, v224
	v_mov_b32_e32 v69, v225
	v_mov_b32_e32 v70, v226
	v_mov_b32_e32 v71, v227
	v_lshlrev_b32_e32 v236, 6, v100
	v_add_u32_e32 v236, 5120, v236
	global_load_dwordx4 v[212:215], v236, s[26:27] offset:48
	global_load_dwordx4 v[216:219], v236, s[26:27] offset:32
	global_load_dwordx4 v[220:223], v236, s[26:27] offset:16
	global_load_dwordx4 v[224:227], v236, s[26:27]
	s_waitcnt lgkmcnt(0)
	v_mul_f32_e32 v69, v69, v94
	v_cndmask_b32_e64 v69, v69, -v69, s[4:5]
	v_fmac_f32_e32 v69, v68, v98
	v_cndmask_b32_e64 v68, v98, v69, s[6:7]
	ds_bpermute_b32 v69, v101, v99
	s_waitcnt lgkmcnt(0)
	v_mul_f32_e32 v69, v71, v69
	v_cndmask_b32_e64 v69, v69, -v69, s[4:5]
	v_fmac_f32_e32 v69, v70, v99
	ds_bpermute_b32 v70, v101, v96
	ds_bpermute_b32 v71, v101, v97
	v_cndmask_b32_e64 v69, v99, v69, s[6:7]
	s_waitcnt lgkmcnt(1)
	v_mul_f32_e32 v70, v87, v70
	v_cndmask_b32_e64 v70, v70, -v70, s[4:5]
	v_fmac_f32_e32 v70, v86, v96
	ds_bpermute_b32 v86, v101, v76
	s_waitcnt lgkmcnt(1)
	v_mul_f32_e32 v71, v89, v71
	v_cndmask_b32_e64 v71, v71, -v71, s[4:5]
	v_fmac_f32_e32 v71, v88, v97
	v_cndmask_b32_e64 v70, v96, v70, s[6:7]
	s_waitcnt lgkmcnt(0)
	v_mul_f32_e32 v83, v83, v86
	v_cndmask_b32_e64 v83, v83, -v83, s[4:5]
	v_fmac_f32_e32 v83, v82, v76
	ds_bpermute_b32 v82, v101, v77
	v_cndmask_b32_e64 v71, v97, v71, s[6:7]
	v_cndmask_b32_e64 v76, v76, v83, s[6:7]
	s_waitcnt lgkmcnt(0)
	v_mul_f32_e32 v82, v85, v82
	v_cndmask_b32_e64 v82, v82, -v82, s[4:5]
	v_fmac_f32_e32 v82, v84, v77
	v_cndmask_b32_e64 v77, v77, v82, s[6:7]
	ds_bpermute_b32 v82, v101, v92
	s_waitcnt lgkmcnt(0)
	v_mul_f32_e32 v79, v79, v82
	v_cndmask_b32_e64 v79, v79, -v79, s[4:5]
	v_fmac_f32_e32 v79, v78, v92
	v_cndmask_b32_e64 v78, v92, v79, s[6:7]
	ds_bpermute_b32 v79, v101, v93
	s_waitcnt lgkmcnt(0)
	v_mul_f32_e32 v79, v81, v79
	v_cndmask_b32_e64 v79, v79, -v79, s[4:5]
	v_fmac_f32_e32 v79, v80, v93
	v_cndmask_b32_e64 v79, v93, v79, s[6:7]
	s_cbranch_vccnz .LBB0_768
	v_pk_mul_f32 v[70:71], v[70:71], s[42:43] op_sel_hi:[1,0]
	v_pk_mul_f32 v[68:69], v[68:69], s[42:43] op_sel_hi:[1,0]
	v_pk_mul_f32 v[78:79], v[78:79], s[42:43] op_sel_hi:[1,0]
	v_pk_mul_f32 v[76:77], v[76:77], s[42:43] op_sel_hi:[1,0]
	v_pk_mul_f32 v[66:67], v[66:67], s[42:43] op_sel_hi:[1,0]
	v_pk_mul_f32 v[64:65], v[64:65], s[42:43] op_sel_hi:[1,0]
	v_pk_mul_f32 v[74:75], v[74:75], s[42:43] op_sel_hi:[1,0]
	v_pk_mul_f32 v[72:73], v[72:73], s[42:43] op_sel_hi:[1,0]

; __device__ __forceinline__ float fast_sigmoid(float a) { return __builtin_amdgcn_rcpf(1.0f + __expf(-a)); }
;     __device__ __forceinline__ void operator()(const Acc& acc, const Unit& u, int wr, int wc, int fr, int fq) const {
;     ...
;                 const int row = u.pm * 256 + ai * 128 + wr * 64 + m * 16 + fr;
;                 const float rs = rsqrtf(ss1[row] * (1.0f / DM) + EPS);
;                 const int posidx = row < MPROMPT ? (row & 2047) : 2048;
;                 f32x4 v[2][2];
; #pragma unroll
;                 for (int bj = 0; bj < 2; ++bj)
; #pragma unroll
;                     for (int n = 0; n < 2; ++n) v[bj][n] = acc[ai][bj][m][n] * rs;
;     ...
;                 } else if (kind == 7) {
; #pragma unroll
;                     for (int bj = 0; bj < 2; ++bj)
; #pragma unroll
;                         for (int n = 0; n < 2; ++n)
; #pragma unroll
;                             for (int j = 0; j < 4; ++j) v[bj][n][j] = fast_sigmoid(v[bj][n][j]);
.LBB0_774:
	s_addk_i32 s87, 0x80
	v_or_b32_e32 v74, s87, v145
	v_ashrrev_i32_e32 v75, 31, v74
	v_lshl_add_u64 v[64:65], v[74:75], 2, s[28:29]
	v_mov_b32_e32 v64, v184
	v_bitop3_b32 v75, s87, v176, v145 bitop3:0xc8
	v_cmp_lt_i32_e64 s[18:19], s75, v74
	s_mov_b64 s[0:1], -1
	s_nop 0
	v_fmamk_f32 v64, v64, 0x3a800000, v174
	v_cmp_gt_f32_e32 vcc, s74, v64
	v_mul_f32_e32 v65, 0x4b800000, v64
	s_nop 0
	v_cndmask_b32_e32 v64, v64, v65, vcc
	v_rsq_f32_e32 v64, v64
	s_nop 0
	v_mul_f32_e32 v65, 0x45800000, v64
	v_cndmask_b32_e32 v68, v64, v65, vcc
	v_cmp_gt_i32_e32 vcc, s64, v74
	v_pk_mul_f32 v[76:77], v[62:63], v[68:69] op_sel_hi:[1,0]
	v_pk_mul_f32 v[80:81], v[60:61], v[68:69] op_sel_hi:[1,0]
	v_pk_mul_f32 v[72:73], v[58:59], v[68:69] op_sel_hi:[1,0]
	v_pk_mul_f32 v[78:79], v[56:57], v[68:69] op_sel_hi:[1,0]
	v_pk_mul_f32 v[66:67], v[54:55], v[68:69] op_sel_hi:[1,0]
	v_pk_mul_f32 v[70:71], v[52:53], v[68:69] op_sel_hi:[1,0]
	v_pk_mul_f32 v[64:65], v[50:51], v[68:69] op_sel_hi:[1,0]
	v_pk_mul_f32 v[68:69], v[48:49], v[68:69] op_sel_hi:[1,0]
	v_cndmask_b32_e32 v84, v177, v75, vcc
	s_and_b64 vcc, exec, s[16:17]
	s_cbranch_vccnz .LBB0_785
	s_and_b64 vcc, exec, s[12:13]
	s_cbranch_vccnz .LBB0_782
	s_cmp_gt_i32 s49, 6
	s_cbranch_scc0 .LBB0_778
	v_mul_f32_e32 v48, 0xbfb8aa3b, v80
	v_exp_f32_e32 v48, v48
	v_mul_f32_e32 v49, 0xbfb8aa3b, v81
	v_exp_f32_e32 v49, v49
	v_mul_f32_e32 v50, 0xbfb8aa3b, v77
	v_add_f32_e32 v48, 1.0, v48
	v_rcp_f32_e32 v52, v48
	v_mul_f32_e32 v48, 0xbfb8aa3b, v76
	v_exp_f32_e32 v48, v48
	v_exp_f32_e32 v50, v50
	v_add_f32_e32 v49, 1.0, v49
	v_rcp_f32_e32 v53, v49
	v_add_f32_e32 v48, 1.0, v48
	v_mul_f32_e32 v49, 0xbfb8aa3b, v78
	v_rcp_f32_e32 v54, v48
	v_add_f32_e32 v48, 1.0, v50
	v_exp_f32_e32 v49, v49
	v_mul_f32_e32 v50, 0xbfb8aa3b, v79
	v_exp_f32_e32 v50, v50
	v_rcp_f32_e32 v55, v48
	v_add_f32_e32 v48, 1.0, v49
	v_mul_f32_e32 v49, 0xbfb8aa3b, v72
	v_rcp_f32_e32 v60, v48
	v_add_f32_e32 v48, 1.0, v50
	v_exp_f32_e32 v49, v49
	v_mul_f32_e32 v50, 0xbfb8aa3b, v73
	v_exp_f32_e32 v50, v50
	v_rcp_f32_e32 v61, v48
	v_add_f32_e32 v48, 1.0, v49
	v_rcp_f32_e32 v62, v48
	v_add_f32_e32 v48, 1.0, v50
	v_mul_f32_e32 v49, 0xbfb8aa3b, v70
	v_mul_f32_e32 v50, 0xbfb8aa3b, v71
	v_exp_f32_e32 v49, v49
	v_exp_f32_e32 v50, v50
	v_rcp_f32_e32 v63, v48
	v_mul_f32_e32 v51, 0xbfb8aa3b, v67
	v_add_f32_e32 v48, 1.0, v49
	v_add_f32_e32 v49, 1.0, v50
	v_mul_f32_e32 v50, 0xbfb8aa3b, v66
	v_mul_f32_e32 v56, 0xbfb8aa3b, v68
	v_mul_f32_e32 v57, 0xbfb8aa3b, v69
	v_mul_f32_e32 v58, 0xbfb8aa3b, v64
	v_mul_f32_e32 v59, 0xbfb8aa3b, v65
	v_exp_f32_e32 v50, v50
	v_exp_f32_e32 v51, v51
	v_exp_f32_e32 v56, v56
	v_exp_f32_e32 v57, v57
	v_exp_f32_e32 v58, v58
	v_exp_f32_e32 v59, v59
	v_add_f32_e32 v50, 1.0, v50
	v_add_f32_e32 v51, 1.0, v51
	v_add_f32_e32 v56, 1.0, v56
	v_add_f32_e32 v57, 1.0, v57
	v_add_f32_e32 v58, 1.0, v58
	v_add_f32_e32 v59, 1.0, v59
	v_rcp_f32_e32 v48, v48
	v_rcp_f32_e32 v49, v49
	v_rcp_f32_e32 v50, v50
	v_rcp_f32_e32 v51, v51
	v_rcp_f32_e32 v56, v56
	v_rcp_f32_e32 v57, v57
	v_rcp_f32_e32 v58, v58
	v_rcp_f32_e32 v59, v59
	s_mov_b64 s[0:1], 0

;     __device__ __forceinline__ void operator()(const Acc& acc, const Unit& u, int wr, int wc, int fr, int fq) const {
;     ...
;                 } else if (kind == 3 || kind == 4) {
;                     const float ksc = (kind == 4) ? 0.0625f : 1.0f;
; #pragma unroll
;                     for (int bj = 0; bj < 2; ++bj)
; #pragma unroll
;                         for (int n = 0; n < 2; ++n) {
;                             const int i0 = (wc * 64 + bj * 32 + fq * 8 + n * 4) >> 1;
;                             const f32x4 cs = *(const f32x4*)(rrot + ((size_t)posidx * 128 + i0) * 2);
;                             const f32x4 x = v[bj][n]; f32x4 o;
;                             o[0] = (x[0] * cs[0] - x[1] * cs[1]) * ksc; o[1] = (x[1] * cs[0] + x[0] * cs[1]) * ksc;
;                             o[2] = (x[2] * cs[2] - x[3] * cs[3]) * ksc; o[3] = (x[3] * cs[2] + x[2] * cs[3]) * ksc;
;                             v[bj][n] = o;
;                         }
.LBB0_782:
	s_and_b64 vcc, exec, s[0:1]
	s_cbranch_vccz .LBB0_784
	v_lshlrev_b32_e32 v48, 2, v170
	v_lshl_or_b32 v82, v84, 10, v48
	v_add_u32_e32 v236, 0x4000, v82
	global_load_dwordx4 v[212:215], v236, s[20:21] offset:16
	global_load_dwordx4 v[216:219], v236, s[20:21]
	global_load_dwordx4 v[220:223], v236, s[20:21] offset:144
	global_load_dwordx4 v[224:227], v236, s[20:21] offset:128
	s_waitcnt vmcnt(6)
	v_mov_b32_e32 v48, v188
	v_mov_b32_e32 v49, v189
	v_mov_b32_e32 v50, v190
	v_mov_b32_e32 v51, v191
	v_mov_b32_e32 v52, v192
	v_mov_b32_e32 v53, v193
	v_mov_b32_e32 v54, v194
	v_mov_b32_e32 v55, v195
	v_pk_mul_f32 v[56:57], v[80:81], v[52:53] op_sel:[1,1] op_sel_hi:[0,1]
	v_pk_fma_f32 v[58:59], v[80:81], v[52:53], v[56:57] neg_lo:[0,0,1] neg_hi:[0,0,1]
	v_pk_fma_f32 v[52:53], v[80:81], v[52:53], v[56:57] op_sel_hi:[1,0,1]
	v_mul_f32_e32 v56, v77, v55
	v_mov_b32_e32 v59, v53
	v_pk_mul_f32 v[52:53], v[156:157], v[58:59] op_sel_hi:[0,1]
	v_mul_f32_e32 v58, v77, v54
	v_pk_fma_f32 v[56:57], v[76:77], v[54:55], v[56:57] op_sel_hi:[1,1,0] neg_lo:[0,0,1] neg_hi:[0,0,1]
	v_pk_fma_f32 v[54:55], v[76:77], v[54:55], v[58:59] op_sel:[1,0,0] op_sel_hi:[0,1,0]
	v_mov_b32_e32 v57, v55
	v_pk_mul_f32 v[54:55], v[156:157], v[56:57] op_sel_hi:[0,1]
	v_pk_mul_f32 v[56:57], v[78:79], v[48:49] op_sel:[1,1] op_sel_hi:[0,1]
	v_pk_fma_f32 v[58:59], v[78:79], v[48:49], v[56:57] neg_lo:[0,0,1] neg_hi:[0,0,1]
	v_pk_fma_f32 v[48:49], v[78:79], v[48:49], v[56:57] op_sel_hi:[1,0,1]
	v_mul_f32_e32 v56, v73, v50
	v_mul_f32_e32 v48, v73, v51
	v_mov_b32_e32 v59, v49
	v_pk_fma_f32 v[48:49], v[72:73], v[50:51], v[48:49] op_sel_hi:[1,1,0] neg_lo:[0,0,1] neg_hi:[0,0,1]
	v_pk_fma_f32 v[50:51], v[72:73], v[50:51], v[56:57] op_sel:[1,0,0] op_sel_hi:[0,1,0]
	v_mov_b32_e32 v49, v51
	v_pk_mul_f32 v[60:61], v[156:157], v[58:59] op_sel_hi:[0,1]
	v_pk_mul_f32 v[62:63], v[156:157], v[48:49] op_sel_hi:[0,1]
	v_mov_b32_e32 v56, v196
	v_mov_b32_e32 v57, v197
	v_mov_b32_e32 v58, v198
	v_mov_b32_e32 v59, v199
	v_mov_b32_e32 v48, v200
	v_mov_b32_e32 v49, v201
	v_mov_b32_e32 v50, v202
	v_mov_b32_e32 v51, v203
	s_nop 0
	v_pk_mul_f32 v[82:83], v[70:71], v[48:49] op_sel:[1,1] op_sel_hi:[0,1]
	v_pk_fma_f32 v[86:87], v[70:71], v[48:49], v[82:83] neg_lo:[0,0,1] neg_hi:[0,0,1]
	v_pk_fma_f32 v[48:49], v[70:71], v[48:49], v[82:83] op_sel_hi:[1,0,1]
	v_mul_f32_e32 v82, v67, v51
	v_mov_b32_e32 v87, v49
	v_pk_mul_f32 v[48:49], v[156:157], v[86:87] op_sel_hi:[0,1]
	v_mul_f32_e32 v86, v67, v50
	v_pk_fma_f32 v[82:83], v[66:67], v[50:51], v[82:83] op_sel_hi:[1,1,0] neg_lo:[0,0,1] neg_hi:[0,0,1]
	v_pk_fma_f32 v[50:51], v[66:67], v[50:51], v[86:87] op_sel:[1,0,0] op_sel_hi:[0,1,0]
	v_mov_b32_e32 v83, v51
	v_pk_mul_f32 v[50:51], v[156:157], v[82:83] op_sel_hi:[0,1]
	v_pk_mul_f32 v[82:83], v[68:69], v[56:57] op_sel:[1,1] op_sel_hi:[0,1]
	v_pk_fma_f32 v[86:87], v[68:69], v[56:57], v[82:83] neg_lo:[0,0,1] neg_hi:[0,0,1]
	v_pk_fma_f32 v[56:57], v[68:69], v[56:57], v[82:83] op_sel_hi:[1,0,1]
	v_mul_f32_e32 v82, v65, v59
	v_mov_b32_e32 v87, v57
	v_pk_mul_f32 v[56:57], v[156:157], v[86:87] op_sel_hi:[0,1]
	v_mul_f32_e32 v86, v65, v58
	v_pk_fma_f32 v[82:83], v[64:65], v[58:59], v[82:83] op_sel_hi:[1,1,0] neg_lo:[0,0,1] neg_hi:[0,0,1]
	v_pk_fma_f32 v[58:59], v[64:65], v[58:59], v[86:87] op_sel:[1,0,0] op_sel_hi:[0,1,0]
	v_mov_b32_e32 v83, v59
	v_pk_mul_f32 v[58:59], v[156:157], v[82:83] op_sel_hi:[0,1]

;     __device__ __forceinline__ void operator()(const Acc& acc, const Unit& u, int wr, int wc, int fr, int fq) const {
;     ...
;                 if (kind <= 1) {
;                     float s2 = 0.f;
; #pragma unroll
;                     for (int bj = 0; bj < 2; ++bj)
; #pragma unroll
;                         for (int n = 0; n < 2; ++n) s2 += (v[bj][n][0] * v[bj][n][0] + v[bj][n][1] * v[bj][n][1]) + (v[bj][n][2] * v[bj][n][2] + v[bj][n][3] * v[bj][n][3]);
;                     s2 += __shfl_xor(s2, 16); s2 += __shfl_xor(s2, 32);
;                     const float r = rsqrtf(s2 * (1.0f / 64.0f) + EPS);
; #pragma unroll
;                     for (int bj = 0; bj < 2; ++bj)
; #pragma unroll
;                         for (int n = 0; n < 2; ++n) { const f32x4 gv = *(const f32x4*)(gp + bj * 32 + fq * 8 + n * 4); v[bj][n] = v[bj][n] * r * gv; }
; #pragma unroll
;                     for (int n = 0; n < 2; ++n) { const f32x4 csa = *(const f32x4*)(rope + ((size_t)posidx * 8 + 4 * n) * 2), csb = *(const f32x4*)(rope + ((size_t)posidx * 8 + 4 * n) * 2 + 4);
;                         const float cc[4] = {csa[0], csa[2], csb[0], csb[2]}, sn[4] = {csa[1], csa[3], csb[1], csb[3]};
; #pragma unroll
;                         for (int j = 0; j < 4; ++j) { const float mine = v[0][n][j], other = __shfl_xor(mine, 16);
;                             const float rot = (fq == 0) ? (mine * cc[j] - other * sn[j]) : (mine * cc[j] + other * sn[j]);
;                             v[0][n][j] = (fq < 2) ? rot : mine; } }
;                     if (kind == 0) {
; #pragma unroll
;                         for (int bj = 0; bj < 2; ++bj)
; #pragma unroll
;                             for (int n = 0; n < 2; ++n) v[bj][n] = v[bj][n] * 0.125f;
;                     }
.LBB0_785:
	s_andn2_b64 vcc, exec, s[0:1]
	s_cbranch_vccnz .LBB0_788
	v_pk_mul_f32 v[48:49], v[76:77], v[76:77]
	v_pk_mul_f32 v[50:51], v[80:81], v[80:81]
	s_nop 0
	v_pk_mov_b32 v[52:53], v[50:51], v[48:49] op_sel:[1,0]
	v_mov_b32_e32 v51, v49
	v_pk_add_f32 v[48:49], v[52:53], v[50:51]
	v_pk_mul_f32 v[50:51], v[72:73], v[72:73]
	v_pk_add_f32 v[48:49], v[48:49], v[48:49] op_sel_hi:[0,1]
	v_pk_mul_f32 v[52:53], v[78:79], v[78:79]
	v_mul_f32_e32 v48, v70, v70
	v_pk_mov_b32 v[54:55], v[52:53], v[50:51] op_sel:[1,0]
	v_mov_b32_e32 v53, v51
	v_pk_add_f32 v[50:51], v[54:55], v[52:53]
	v_pk_fma_f32 v[52:53], v[70:71], v[70:71], v[48:49] op_sel_hi:[1,1,0]
	v_mul_f32_e32 v48, v66, v66
	v_pk_add_f32 v[50:51], v[50:51], v[50:51] op_sel_hi:[0,1]
	v_pk_fma_f32 v[54:55], v[66:67], v[66:67], v[48:49] op_sel_hi:[1,1,0]
	v_mul_f32_e32 v52, v68, v68
	v_mul_f32_e32 v54, v69, v69
	v_mul_f32_e32 v48, v64, v64
	v_mul_f32_e32 v50, v65, v65
	v_pk_add_f32 v[52:53], v[52:53], v[54:55]
	v_pk_add_f32 v[48:49], v[48:49], v[50:51]
	v_and_b32_e32 v50, 64, v178
	v_pk_add_f32 v[48:49], v[52:53], v[48:49]
	v_add_u32_e32 v50, 64, v50
	v_add_f32_e32 v48, v48, v49
	v_xor_b32_e32 v49, 16, v178
	v_cmp_lt_i32_e32 vcc, v49, v50
	s_nop 1
	v_cndmask_b32_e32 v49, v178, v49, vcc
	v_lshlrev_b32_e32 v85, 2, v49
	ds_bpermute_b32 v49, v85, v48
	s_waitcnt lgkmcnt(0)
	v_add_f32_e32 v48, v48, v49
	v_xor_b32_e32 v49, 32, v178
	v_cmp_lt_i32_e32 vcc, v49, v50
	s_nop 1
	v_cndmask_b32_e32 v49, v178, v49, vcc
	v_lshlrev_b32_e32 v49, 2, v49
	ds_bpermute_b32 v49, v49, v48
	s_waitcnt lgkmcnt(0)
	v_add_f32_e32 v48, v48, v49
	v_fmamk_f32 v48, v48, 0x3c800000, v174
	v_cmp_gt_f32_e32 vcc, s74, v48
	v_mul_f32_e32 v49, 0x4b800000, v48
	s_nop 0
	v_cndmask_b32_e32 v48, v48, v49, vcc
	v_rsq_f32_e32 v48, v48
	s_nop 0
	v_mul_f32_e32 v49, 0x45800000, v48
	v_cndmask_b32_e32 v52, v48, v49, vcc
	v_mov_b32_e32 v48, v188
	v_mov_b32_e32 v49, v189
	v_mov_b32_e32 v50, v190
	v_mov_b32_e32 v51, v191
	v_mov_b32_e32 v54, v192
	v_mov_b32_e32 v55, v193
	v_mov_b32_e32 v56, v194
	v_mov_b32_e32 v57, v195
	v_pk_mul_f32 v[58:59], v[80:81], v[52:53] op_sel_hi:[1,0]
	v_pk_mul_f32 v[60:61], v[76:77], v[52:53] op_sel_hi:[1,0]
	v_pk_mul_f32 v[62:63], v[66:67], v[52:53] op_sel_hi:[1,0]
	s_and_b64 vcc, exec, s[10:11]
	s_nop 0
	v_pk_mul_f32 v[80:81], v[56:57], v[60:61]
	v_pk_mul_f32 v[82:83], v[54:55], v[58:59]
	v_pk_mul_f32 v[54:55], v[78:79], v[52:53] op_sel_hi:[1,0]
	v_pk_mul_f32 v[56:57], v[72:73], v[52:53] op_sel_hi:[1,0]
	v_pk_mul_f32 v[60:61], v[48:49], v[54:55]
	v_pk_mul_f32 v[76:77], v[50:51], v[56:57]
	v_mov_b32_e32 v54, v196
	v_mov_b32_e32 v55, v197
	v_mov_b32_e32 v56, v198
	v_mov_b32_e32 v57, v199
	v_mov_b32_e32 v48, v200
	v_mov_b32_e32 v49, v201
	v_mov_b32_e32 v50, v202
	v_mov_b32_e32 v51, v203
	v_pk_mul_f32 v[58:59], v[70:71], v[52:53] op_sel_hi:[1,0]
	ds_bpermute_b32 v78, v85, v82
	s_nop 0
	v_pk_mul_f32 v[50:51], v[50:51], v[62:63]
	v_pk_mul_f32 v[62:63], v[68:69], v[52:53] op_sel_hi:[1,0]
	v_pk_mul_f32 v[52:53], v[64:65], v[52:53] op_sel_hi:[1,0]
	v_pk_mul_f32 v[48:49], v[48:49], v[58:59]
	v_pk_mul_f32 v[58:59], v[56:57], v[52:53]
	v_lshlrev_b32_e32 v52, 6, v84
	v_pk_mul_f32 v[56:57], v[54:55], v[62:63]
	s_waitcnt vmcnt(2)
	v_mov_b32_e32 v62, v212
	v_mov_b32_e32 v63, v213
	v_mov_b32_e32 v64, v214
	v_mov_b32_e32 v65, v215
	v_mov_b32_e32 v66, v216
	v_mov_b32_e32 v67, v217
	v_mov_b32_e32 v68, v218
	v_mov_b32_e32 v69, v219
	v_mov_b32_e32 v70, v220
	v_mov_b32_e32 v71, v221
	v_mov_b32_e32 v72, v222
	v_mov_b32_e32 v73, v223
	s_nop 0
	v_mov_b32_e32 v52, v224
	v_mov_b32_e32 v53, v225
	v_mov_b32_e32 v54, v226
	v_mov_b32_e32 v55, v227
	v_lshlrev_b32_e32 v236, 6, v84
	v_add_u32_e32 v236, 1024, v236
	global_load_dwordx4 v[212:215], v236, s[26:27] offset:48
	global_load_dwordx4 v[216:219], v236, s[26:27] offset:32
	global_load_dwordx4 v[220:223], v236, s[26:27] offset:16
	global_load_dwordx4 v[224:227], v236, s[26:27]
	s_waitcnt lgkmcnt(0)
	v_mul_f32_e32 v53, v53, v78
	v_cndmask_b32_e64 v53, v53, -v53, s[4:5]
	v_fmac_f32_e32 v53, v52, v82
	v_cndmask_b32_e64 v52, v82, v53, s[6:7]
	ds_bpermute_b32 v53, v85, v83
	s_waitcnt lgkmcnt(0)
	v_mul_f32_e32 v53, v55, v53
	v_cndmask_b32_e64 v53, v53, -v53, s[4:5]
	v_fmac_f32_e32 v53, v54, v83
	ds_bpermute_b32 v54, v85, v80
	ds_bpermute_b32 v55, v85, v81
	v_cndmask_b32_e64 v53, v83, v53, s[6:7]
	s_waitcnt lgkmcnt(1)
	v_mul_f32_e32 v54, v71, v54
	v_cndmask_b32_e64 v54, v54, -v54, s[4:5]
	v_fmac_f32_e32 v54, v70, v80
	ds_bpermute_b32 v70, v85, v60
	s_waitcnt lgkmcnt(1)
	v_mul_f32_e32 v55, v73, v55
	v_cndmask_b32_e64 v55, v55, -v55, s[4:5]
	v_fmac_f32_e32 v55, v72, v81
	v_cndmask_b32_e64 v54, v80, v54, s[6:7]
	s_waitcnt lgkmcnt(0)
	v_mul_f32_e32 v67, v67, v70
	v_cndmask_b32_e64 v67, v67, -v67, s[4:5]
	v_fmac_f32_e32 v67, v66, v60
	ds_bpermute_b32 v66, v85, v61
	v_cndmask_b32_e64 v55, v81, v55, s[6:7]
	v_cndmask_b32_e64 v60, v60, v67, s[6:7]
	s_waitcnt lgkmcnt(0)
	v_mul_f32_e32 v66, v69, v66
	v_cndmask_b32_e64 v66, v66, -v66, s[4:5]
	v_fmac_f32_e32 v66, v68, v61
	v_cndmask_b32_e64 v61, v61, v66, s[6:7]
	ds_bpermute_b32 v66, v85, v76
	s_waitcnt lgkmcnt(0)
	v_mul_f32_e32 v63, v63, v66
	v_cndmask_b32_e64 v63, v63, -v63, s[4:5]
	v_fmac_f32_e32 v63, v62, v76
	v_cndmask_b32_e64 v62, v76, v63, s[6:7]
	ds_bpermute_b32 v63, v85, v77
	s_waitcnt lgkmcnt(0)
	v_mul_f32_e32 v63, v65, v63
	v_cndmask_b32_e64 v63, v63, -v63, s[4:5]
	v_fmac_f32_e32 v63, v64, v77
	v_cndmask_b32_e64 v63, v77, v63, s[6:7]
	s_cbranch_vccnz .LBB0_788
	v_pk_mul_f32 v[54:55], v[54:55], s[42:43] op_sel_hi:[1,0]
	v_pk_mul_f32 v[52:53], v[52:53], s[42:43] op_sel_hi:[1,0]
	v_pk_mul_f32 v[62:63], v[62:63], s[42:43] op_sel_hi:[1,0]
	v_pk_mul_f32 v[60:61], v[60:61], s[42:43] op_sel_hi:[1,0]
	v_pk_mul_f32 v[50:51], v[50:51], s[42:43] op_sel_hi:[1,0]
	v_pk_mul_f32 v[48:49], v[48:49], s[42:43] op_sel_hi:[1,0]
	v_pk_mul_f32 v[58:59], v[58:59], s[42:43] op_sel_hi:[1,0]
	v_pk_mul_f32 v[56:57], v[56:57], s[42:43] op_sel_hi:[1,0]

; __device__ __forceinline__ float fast_sigmoid(float a) { return __builtin_amdgcn_rcpf(1.0f + __expf(-a)); }
;     __device__ __forceinline__ void operator()(const Acc& acc, const Unit& u, int wr, int wc, int fr, int fq) const {
;     ...
;                 const int row = u.pm * 256 + ai * 128 + wr * 64 + m * 16 + fr;
;                 const float rs = rsqrtf(ss1[row] * (1.0f / DM) + EPS);
;                 const int posidx = row < MPROMPT ? (row & 2047) : 2048;
;                 f32x4 v[2][2];
; #pragma unroll
;                 for (int bj = 0; bj < 2; ++bj)
; #pragma unroll
;                     for (int n = 0; n < 2; ++n) v[bj][n] = acc[ai][bj][m][n] * rs;
;     ...
;                 } else if (kind == 7) {
; #pragma unroll
;                     for (int bj = 0; bj < 2; ++bj)
; #pragma unroll
;                         for (int n = 0; n < 2; ++n)
; #pragma unroll
;                             for (int j = 0; j < 4; ++j) v[bj][n][j] = fast_sigmoid(v[bj][n][j]);
.LBB0_794:
	s_nop 0
	v_or_b32_e32 v58, 16, v74
	v_ashrrev_i32_e32 v59, 31, v58
	v_lshl_add_u64 v[48:49], v[58:59], 2, s[28:29]
	v_mov_b32_e32 v48, v185
	v_bitop3_b32 v59, v74, s91, 16 bitop3:0xc8
	v_cmp_lt_i32_e64 s[18:19], s75, v58
	s_mov_b64 s[0:1], -1
	s_nop 0
	v_fmamk_f32 v48, v48, 0x3a800000, v174
	v_cmp_gt_f32_e32 vcc, s74, v48
	v_mul_f32_e32 v49, 0x4b800000, v48
	s_nop 0
	v_cndmask_b32_e32 v48, v48, v49, vcc
	v_rsq_f32_e32 v48, v48
	s_nop 0
	v_mul_f32_e32 v49, 0x45800000, v48
	v_cndmask_b32_e32 v52, v48, v49, vcc
	v_cmp_gt_i32_e32 vcc, s64, v58
	v_pk_mul_f32 v[60:61], v[46:47], v[52:53] op_sel_hi:[1,0]
	v_pk_mul_f32 v[64:65], v[44:45], v[52:53] op_sel_hi:[1,0]
	v_pk_mul_f32 v[56:57], v[42:43], v[52:53] op_sel_hi:[1,0]
	v_pk_mul_f32 v[62:63], v[40:41], v[52:53] op_sel_hi:[1,0]
	v_pk_mul_f32 v[50:51], v[38:39], v[52:53] op_sel_hi:[1,0]
	v_pk_mul_f32 v[54:55], v[36:37], v[52:53] op_sel_hi:[1,0]
	v_pk_mul_f32 v[48:49], v[34:35], v[52:53] op_sel_hi:[1,0]
	v_pk_mul_f32 v[52:53], v[32:33], v[52:53] op_sel_hi:[1,0]
	v_cndmask_b32_e32 v68, v177, v59, vcc
	s_and_b64 vcc, exec, s[16:17]
	s_cbranch_vccnz .LBB0_805
	s_and_b64 vcc, exec, s[12:13]
	s_cbranch_vccnz .LBB0_802
	s_cmp_gt_i32 s49, 6
	s_cbranch_scc0 .LBB0_798
	v_mul_f32_e32 v32, 0xbfb8aa3b, v64
	v_exp_f32_e32 v32, v32
	v_mul_f32_e32 v33, 0xbfb8aa3b, v65
	v_exp_f32_e32 v33, v33
	v_mul_f32_e32 v34, 0xbfb8aa3b, v61
	v_add_f32_e32 v32, 1.0, v32
	v_rcp_f32_e32 v36, v32
	v_mul_f32_e32 v32, 0xbfb8aa3b, v60
	v_exp_f32_e32 v32, v32
	v_exp_f32_e32 v34, v34
	v_add_f32_e32 v33, 1.0, v33
	v_rcp_f32_e32 v37, v33
	v_add_f32_e32 v32, 1.0, v32
	v_mul_f32_e32 v33, 0xbfb8aa3b, v62
	v_rcp_f32_e32 v38, v32
	v_add_f32_e32 v32, 1.0, v34
	v_exp_f32_e32 v33, v33
	v_mul_f32_e32 v34, 0xbfb8aa3b, v63
	v_exp_f32_e32 v34, v34
	v_rcp_f32_e32 v39, v32
	v_add_f32_e32 v32, 1.0, v33
	v_mul_f32_e32 v33, 0xbfb8aa3b, v56
	v_rcp_f32_e32 v44, v32
	v_add_f32_e32 v32, 1.0, v34
	v_exp_f32_e32 v33, v33
	v_mul_f32_e32 v34, 0xbfb8aa3b, v57
	v_exp_f32_e32 v34, v34
	v_rcp_f32_e32 v45, v32
	v_add_f32_e32 v32, 1.0, v33
	v_rcp_f32_e32 v46, v32
	v_add_f32_e32 v32, 1.0, v34
	v_mul_f32_e32 v33, 0xbfb8aa3b, v54
	v_mul_f32_e32 v34, 0xbfb8aa3b, v55
	v_exp_f32_e32 v33, v33
	v_exp_f32_e32 v34, v34
	v_rcp_f32_e32 v47, v32
	v_mul_f32_e32 v35, 0xbfb8aa3b, v51
	v_add_f32_e32 v32, 1.0, v33
	v_add_f32_e32 v33, 1.0, v34
	v_mul_f32_e32 v34, 0xbfb8aa3b, v50
	v_mul_f32_e32 v40, 0xbfb8aa3b, v52
	v_mul_f32_e32 v41, 0xbfb8aa3b, v53
	v_mul_f32_e32 v42, 0xbfb8aa3b, v48
	v_mul_f32_e32 v43, 0xbfb8aa3b, v49
	v_exp_f32_e32 v34, v34
	v_exp_f32_e32 v35, v35
	v_exp_f32_e32 v40, v40
	v_exp_f32_e32 v41, v41
	v_exp_f32_e32 v42, v42
	v_exp_f32_e32 v43, v43
	v_add_f32_e32 v34, 1.0, v34
	v_add_f32_e32 v35, 1.0, v35
	v_add_f32_e32 v40, 1.0, v40
	v_add_f32_e32 v41, 1.0, v41
	v_add_f32_e32 v42, 1.0, v42
	v_add_f32_e32 v43, 1.0, v43
	v_rcp_f32_e32 v32, v32
	v_rcp_f32_e32 v33, v33
	v_rcp_f32_e32 v34, v34
	v_rcp_f32_e32 v35, v35
	v_rcp_f32_e32 v40, v40
	v_rcp_f32_e32 v41, v41
	v_rcp_f32_e32 v42, v42
	v_rcp_f32_e32 v43, v43
	s_mov_b64 s[0:1], 0

;     __device__ __forceinline__ void operator()(const Acc& acc, const Unit& u, int wr, int wc, int fr, int fq) const {
;     ...
;                 } else if (kind == 3 || kind == 4) {
;                     const float ksc = (kind == 4) ? 0.0625f : 1.0f;
; #pragma unroll
;                     for (int bj = 0; bj < 2; ++bj)
; #pragma unroll
;                         for (int n = 0; n < 2; ++n) {
;                             const int i0 = (wc * 64 + bj * 32 + fq * 8 + n * 4) >> 1;
;                             const f32x4 cs = *(const f32x4*)(rrot + ((size_t)posidx * 128 + i0) * 2);
;                             const f32x4 x = v[bj][n]; f32x4 o;
;                             o[0] = (x[0] * cs[0] - x[1] * cs[1]) * ksc; o[1] = (x[1] * cs[0] + x[0] * cs[1]) * ksc;
;                             o[2] = (x[2] * cs[2] - x[3] * cs[3]) * ksc; o[3] = (x[3] * cs[2] + x[2] * cs[3]) * ksc;
;                             v[bj][n] = o;
;                         }
.LBB0_802:
	s_and_b64 vcc, exec, s[0:1]
	s_cbranch_vccz .LBB0_804
	v_lshlrev_b32_e32 v32, 2, v170
	v_lshl_or_b32 v66, v68, 10, v32
	v_add_u32_e32 v236, 0x4000, v66
	global_load_dwordx4 v[188:191], v236, s[20:21] offset:16
	global_load_dwordx4 v[192:195], v236, s[20:21]
	global_load_dwordx4 v[196:199], v236, s[20:21] offset:144
	global_load_dwordx4 v[200:203], v236, s[20:21] offset:128
	s_waitcnt vmcnt(6)
	v_mov_b32_e32 v32, v212
	v_mov_b32_e32 v33, v213
	v_mov_b32_e32 v34, v214
	v_mov_b32_e32 v35, v215
	v_mov_b32_e32 v36, v216
	v_mov_b32_e32 v37, v217
	v_mov_b32_e32 v38, v218
	v_mov_b32_e32 v39, v219
	v_pk_mul_f32 v[40:41], v[64:65], v[36:37] op_sel:[1,1] op_sel_hi:[0,1]
	v_pk_fma_f32 v[42:43], v[64:65], v[36:37], v[40:41] neg_lo:[0,0,1] neg_hi:[0,0,1]
	v_pk_fma_f32 v[36:37], v[64:65], v[36:37], v[40:41] op_sel_hi:[1,0,1]
	v_mul_f32_e32 v40, v61, v39
	v_mov_b32_e32 v43, v37
	v_pk_mul_f32 v[36:37], v[156:157], v[42:43] op_sel_hi:[0,1]
	v_mul_f32_e32 v42, v61, v38
	v_pk_fma_f32 v[40:41], v[60:61], v[38:39], v[40:41] op_sel_hi:[1,1,0] neg_lo:[0,0,1] neg_hi:[0,0,1]
	v_pk_fma_f32 v[38:39], v[60:61], v[38:39], v[42:43] op_sel:[1,0,0] op_sel_hi:[0,1,0]
	v_mov_b32_e32 v41, v39
	v_pk_mul_f32 v[38:39], v[156:157], v[40:41] op_sel_hi:[0,1]
	v_pk_mul_f32 v[40:41], v[62:63], v[32:33] op_sel:[1,1] op_sel_hi:[0,1]
	v_pk_fma_f32 v[42:43], v[62:63], v[32:33], v[40:41] neg_lo:[0,0,1] neg_hi:[0,0,1]
	v_pk_fma_f32 v[32:33], v[62:63], v[32:33], v[40:41] op_sel_hi:[1,0,1]
	v_mul_f32_e32 v40, v57, v34
	v_mul_f32_e32 v32, v57, v35
	v_mov_b32_e32 v43, v33
	v_pk_fma_f32 v[32:33], v[56:57], v[34:35], v[32:33] op_sel_hi:[1,1,0] neg_lo:[0,0,1] neg_hi:[0,0,1]
	v_pk_fma_f32 v[34:35], v[56:57], v[34:35], v[40:41] op_sel:[1,0,0] op_sel_hi:[0,1,0]
	v_mov_b32_e32 v33, v35
	v_pk_mul_f32 v[44:45], v[156:157], v[42:43] op_sel_hi:[0,1]
	v_pk_mul_f32 v[46:47], v[156:157], v[32:33] op_sel_hi:[0,1]
	v_mov_b32_e32 v40, v220
	v_mov_b32_e32 v41, v221
	v_mov_b32_e32 v42, v222
	v_mov_b32_e32 v43, v223
	v_mov_b32_e32 v32, v224
	v_mov_b32_e32 v33, v225
	v_mov_b32_e32 v34, v226
	v_mov_b32_e32 v35, v227
	s_nop 0
	v_pk_mul_f32 v[66:67], v[54:55], v[32:33] op_sel:[1,1] op_sel_hi:[0,1]
	v_pk_fma_f32 v[70:71], v[54:55], v[32:33], v[66:67] neg_lo:[0,0,1] neg_hi:[0,0,1]
	v_pk_fma_f32 v[32:33], v[54:55], v[32:33], v[66:67] op_sel_hi:[1,0,1]
	v_mul_f32_e32 v66, v51, v35
	v_mov_b32_e32 v71, v33
	v_pk_mul_f32 v[32:33], v[156:157], v[70:71] op_sel_hi:[0,1]
	v_mul_f32_e32 v70, v51, v34
	v_pk_fma_f32 v[66:67], v[50:51], v[34:35], v[66:67] op_sel_hi:[1,1,0] neg_lo:[0,0,1] neg_hi:[0,0,1]
	v_pk_fma_f32 v[34:35], v[50:51], v[34:35], v[70:71] op_sel:[1,0,0] op_sel_hi:[0,1,0]
	v_mov_b32_e32 v67, v35
	v_pk_mul_f32 v[34:35], v[156:157], v[66:67] op_sel_hi:[0,1]
	v_pk_mul_f32 v[66:67], v[52:53], v[40:41] op_sel:[1,1] op_sel_hi:[0,1]
	v_pk_fma_f32 v[70:71], v[52:53], v[40:41], v[66:67] neg_lo:[0,0,1] neg_hi:[0,0,1]
	v_pk_fma_f32 v[40:41], v[52:53], v[40:41], v[66:67] op_sel_hi:[1,0,1]
	v_mul_f32_e32 v66, v49, v43
	v_mov_b32_e32 v71, v41
	v_pk_mul_f32 v[40:41], v[156:157], v[70:71] op_sel_hi:[0,1]
	v_mul_f32_e32 v70, v49, v42
	v_pk_fma_f32 v[66:67], v[48:49], v[42:43], v[66:67] op_sel_hi:[1,1,0] neg_lo:[0,0,1] neg_hi:[0,0,1]
	v_pk_fma_f32 v[42:43], v[48:49], v[42:43], v[70:71] op_sel:[1,0,0] op_sel_hi:[0,1,0]
	v_mov_b32_e32 v67, v43
	v_pk_mul_f32 v[42:43], v[156:157], v[66:67] op_sel_hi:[0,1]

;     __device__ __forceinline__ void operator()(const Acc& acc, const Unit& u, int wr, int wc, int fr, int fq) const {
;     ...
;                 if (kind <= 1) {
;                     float s2 = 0.f;
; #pragma unroll
;                     for (int bj = 0; bj < 2; ++bj)
; #pragma unroll
;                         for (int n = 0; n < 2; ++n) s2 += (v[bj][n][0] * v[bj][n][0] + v[bj][n][1] * v[bj][n][1]) + (v[bj][n][2] * v[bj][n][2] + v[bj][n][3] * v[bj][n][3]);
;                     s2 += __shfl_xor(s2, 16); s2 += __shfl_xor(s2, 32);
;                     const float r = rsqrtf(s2 * (1.0f / 64.0f) + EPS);
; #pragma unroll
;                     for (int bj = 0; bj < 2; ++bj)
; #pragma unroll
;                         for (int n = 0; n < 2; ++n) { const f32x4 gv = *(const f32x4*)(gp + bj * 32 + fq * 8 + n * 4); v[bj][n] = v[bj][n] * r * gv; }
; #pragma unroll
;                     for (int n = 0; n < 2; ++n) { const f32x4 csa = *(const f32x4*)(rope + ((size_t)posidx * 8 + 4 * n) * 2), csb = *(const f32x4*)(rope + ((size_t)posidx * 8 + 4 * n) * 2 + 4);
;                         const float cc[4] = {csa[0], csa[2], csb[0], csb[2]}, sn[4] = {csa[1], csa[3], csb[1], csb[3]};
; #pragma unroll
;                         for (int j = 0; j < 4; ++j) { const float mine = v[0][n][j], other = __shfl_xor(mine, 16);
;                             const float rot = (fq == 0) ? (mine * cc[j] - other * sn[j]) : (mine * cc[j] + other * sn[j]);
;                             v[0][n][j] = (fq < 2) ? rot : mine; } }
;                     if (kind == 0) {
; #pragma unroll
;                         for (int bj = 0; bj < 2; ++bj)
; #pragma unroll
;                             for (int n = 0; n < 2; ++n) v[bj][n] = v[bj][n] * 0.125f;
;                     }
.LBB0_805:
	s_andn2_b64 vcc, exec, s[0:1]
	s_cbranch_vccnz .LBB0_808
	v_pk_mul_f32 v[32:33], v[60:61], v[60:61]
	v_pk_mul_f32 v[34:35], v[64:65], v[64:65]
	s_nop 0
	v_pk_mov_b32 v[36:37], v[34:35], v[32:33] op_sel:[1,0]
	v_mov_b32_e32 v35, v33
	v_pk_add_f32 v[32:33], v[36:37], v[34:35]
	v_pk_mul_f32 v[34:35], v[56:57], v[56:57]
	v_pk_add_f32 v[32:33], v[32:33], v[32:33] op_sel_hi:[0,1]
	v_pk_mul_f32 v[36:37], v[62:63], v[62:63]
	v_mul_f32_e32 v32, v54, v54
	v_pk_mov_b32 v[38:39], v[36:37], v[34:35] op_sel:[1,0]
	v_mov_b32_e32 v37, v35
	v_pk_add_f32 v[34:35], v[38:39], v[36:37]
	v_pk_fma_f32 v[36:37], v[54:55], v[54:55], v[32:33] op_sel_hi:[1,1,0]
	v_mul_f32_e32 v32, v50, v50
	v_pk_add_f32 v[34:35], v[34:35], v[34:35] op_sel_hi:[0,1]
	v_pk_fma_f32 v[38:39], v[50:51], v[50:51], v[32:33] op_sel_hi:[1,1,0]
	v_mul_f32_e32 v36, v52, v52
	v_mul_f32_e32 v38, v53, v53
	v_mul_f32_e32 v32, v48, v48
	v_mul_f32_e32 v34, v49, v49
	v_pk_add_f32 v[36:37], v[36:37], v[38:39]
	v_pk_add_f32 v[32:33], v[32:33], v[34:35]
	v_and_b32_e32 v34, 64, v178
	v_pk_add_f32 v[32:33], v[36:37], v[32:33]
	v_add_u32_e32 v34, 64, v34
	v_add_f32_e32 v32, v32, v33
	v_xor_b32_e32 v33, 16, v178
	v_cmp_lt_i32_e32 vcc, v33, v34
	s_nop 1
	v_cndmask_b32_e32 v33, v178, v33, vcc
	v_lshlrev_b32_e32 v69, 2, v33
	ds_bpermute_b32 v33, v69, v32
	s_waitcnt lgkmcnt(0)
	v_add_f32_e32 v32, v32, v33
	v_xor_b32_e32 v33, 32, v178
	v_cmp_lt_i32_e32 vcc, v33, v34
	s_nop 1
	v_cndmask_b32_e32 v33, v178, v33, vcc
	v_lshlrev_b32_e32 v33, 2, v33
	ds_bpermute_b32 v33, v33, v32
	s_waitcnt lgkmcnt(0)
	v_add_f32_e32 v32, v32, v33
	v_fmamk_f32 v32, v32, 0x3c800000, v174
	v_cmp_gt_f32_e32 vcc, s74, v32
	v_mul_f32_e32 v33, 0x4b800000, v32
	s_nop 0
	v_cndmask_b32_e32 v32, v32, v33, vcc
	v_rsq_f32_e32 v32, v32
	s_nop 0
	v_mul_f32_e32 v33, 0x45800000, v32
	v_cndmask_b32_e32 v36, v32, v33, vcc
	v_mov_b32_e32 v32, v188
	v_mov_b32_e32 v33, v189
	v_mov_b32_e32 v34, v190
	v_mov_b32_e32 v35, v191
	v_mov_b32_e32 v38, v192
	v_mov_b32_e32 v39, v193
	v_mov_b32_e32 v40, v194
	v_mov_b32_e32 v41, v195
	v_pk_mul_f32 v[42:43], v[64:65], v[36:37] op_sel_hi:[1,0]
	v_pk_mul_f32 v[44:45], v[60:61], v[36:37] op_sel_hi:[1,0]
	v_pk_mul_f32 v[46:47], v[50:51], v[36:37] op_sel_hi:[1,0]
	s_and_b64 vcc, exec, s[10:11]
	s_nop 0
	v_pk_mul_f32 v[64:65], v[40:41], v[44:45]
	v_pk_mul_f32 v[66:67], v[38:39], v[42:43]
	v_pk_mul_f32 v[38:39], v[62:63], v[36:37] op_sel_hi:[1,0]
	v_pk_mul_f32 v[40:41], v[56:57], v[36:37] op_sel_hi:[1,0]
	v_pk_mul_f32 v[44:45], v[32:33], v[38:39]
	v_pk_mul_f32 v[60:61], v[34:35], v[40:41]
	v_mov_b32_e32 v38, v196
	v_mov_b32_e32 v39, v197
	v_mov_b32_e32 v40, v198
	v_mov_b32_e32 v41, v199
	v_mov_b32_e32 v32, v200
	v_mov_b32_e32 v33, v201
	v_mov_b32_e32 v34, v202
	v_mov_b32_e32 v35, v203
	v_pk_mul_f32 v[42:43], v[54:55], v[36:37] op_sel_hi:[1,0]
	ds_bpermute_b32 v62, v69, v66
	s_nop 0
	v_pk_mul_f32 v[34:35], v[34:35], v[46:47]
	v_pk_mul_f32 v[46:47], v[52:53], v[36:37] op_sel_hi:[1,0]
	v_pk_mul_f32 v[36:37], v[48:49], v[36:37] op_sel_hi:[1,0]
	v_pk_mul_f32 v[32:33], v[32:33], v[42:43]
	v_pk_mul_f32 v[42:43], v[40:41], v[36:37]
	v_lshlrev_b32_e32 v36, 6, v68
	v_pk_mul_f32 v[40:41], v[38:39], v[46:47]
	s_waitcnt vmcnt(2)
	v_mov_b32_e32 v46, v212
	v_mov_b32_e32 v47, v213
	v_mov_b32_e32 v48, v214
	v_mov_b32_e32 v49, v215
	v_mov_b32_e32 v50, v216
	v_mov_b32_e32 v51, v217
	v_mov_b32_e32 v52, v218
	v_mov_b32_e32 v53, v219
	v_mov_b32_e32 v54, v220
	v_mov_b32_e32 v55, v221
	v_mov_b32_e32 v56, v222
	v_mov_b32_e32 v57, v223
	s_nop 0
	v_mov_b32_e32 v36, v224
	v_mov_b32_e32 v37, v225
	v_mov_b32_e32 v38, v226
	v_mov_b32_e32 v39, v227
	v_lshlrev_b32_e32 v236, 6, v68
	v_add_u32_e32 v236, 1024, v236
	global_load_dwordx4 v[212:215], v236, s[26:27] offset:48
	global_load_dwordx4 v[216:219], v236, s[26:27] offset:32
	global_load_dwordx4 v[220:223], v236, s[26:27] offset:16
	global_load_dwordx4 v[224:227], v236, s[26:27]
	s_waitcnt lgkmcnt(0)
	v_mul_f32_e32 v37, v37, v62
	v_cndmask_b32_e64 v37, v37, -v37, s[4:5]
	v_fmac_f32_e32 v37, v36, v66
	v_cndmask_b32_e64 v36, v66, v37, s[6:7]
	ds_bpermute_b32 v37, v69, v67
	s_waitcnt lgkmcnt(0)
	v_mul_f32_e32 v37, v39, v37
	v_cndmask_b32_e64 v37, v37, -v37, s[4:5]
	v_fmac_f32_e32 v37, v38, v67
	ds_bpermute_b32 v38, v69, v64
	ds_bpermute_b32 v39, v69, v65
	v_cndmask_b32_e64 v37, v67, v37, s[6:7]
	s_waitcnt lgkmcnt(1)
	v_mul_f32_e32 v38, v55, v38
	v_cndmask_b32_e64 v38, v38, -v38, s[4:5]
	v_fmac_f32_e32 v38, v54, v64
	ds_bpermute_b32 v54, v69, v44
	s_waitcnt lgkmcnt(1)
	v_mul_f32_e32 v39, v57, v39
	v_cndmask_b32_e64 v39, v39, -v39, s[4:5]
	v_fmac_f32_e32 v39, v56, v65
	v_cndmask_b32_e64 v38, v64, v38, s[6:7]
	s_waitcnt lgkmcnt(0)
	v_mul_f32_e32 v51, v51, v54
	v_cndmask_b32_e64 v51, v51, -v51, s[4:5]
	v_fmac_f32_e32 v51, v50, v44
	ds_bpermute_b32 v50, v69, v45
	v_cndmask_b32_e64 v39, v65, v39, s[6:7]
	v_cndmask_b32_e64 v44, v44, v51, s[6:7]
	s_waitcnt lgkmcnt(0)
	v_mul_f32_e32 v50, v53, v50
	v_cndmask_b32_e64 v50, v50, -v50, s[4:5]
	v_fmac_f32_e32 v50, v52, v45
	v_cndmask_b32_e64 v45, v45, v50, s[6:7]
	ds_bpermute_b32 v50, v69, v60
	s_waitcnt lgkmcnt(0)
	v_mul_f32_e32 v47, v47, v50
	v_cndmask_b32_e64 v47, v47, -v47, s[4:5]
	v_fmac_f32_e32 v47, v46, v60
	v_cndmask_b32_e64 v46, v60, v47, s[6:7]
	ds_bpermute_b32 v47, v69, v61
	s_waitcnt lgkmcnt(0)
	v_mul_f32_e32 v47, v49, v47
	v_cndmask_b32_e64 v47, v47, -v47, s[4:5]
	v_fmac_f32_e32 v47, v48, v61
	v_cndmask_b32_e64 v47, v61, v47, s[6:7]
	s_cbranch_vccnz .LBB0_808
	v_pk_mul_f32 v[38:39], v[38:39], s[42:43] op_sel_hi:[1,0]
	v_pk_mul_f32 v[36:37], v[36:37], s[42:43] op_sel_hi:[1,0]
	v_pk_mul_f32 v[46:47], v[46:47], s[42:43] op_sel_hi:[1,0]
	v_pk_mul_f32 v[44:45], v[44:45], s[42:43] op_sel_hi:[1,0]
	v_pk_mul_f32 v[34:35], v[34:35], s[42:43] op_sel_hi:[1,0]
	v_pk_mul_f32 v[32:33], v[32:33], s[42:43] op_sel_hi:[1,0]
	v_pk_mul_f32 v[42:43], v[42:43], s[42:43] op_sel_hi:[1,0]
	v_pk_mul_f32 v[40:41], v[40:41], s[42:43] op_sel_hi:[1,0]

; __device__ __forceinline__ float fast_sigmoid(float a) { return __builtin_amdgcn_rcpf(1.0f + __expf(-a)); }
;     __device__ __forceinline__ void operator()(const Acc& acc, const Unit& u, int wr, int wc, int fr, int fq) const {
;     ...
;                 const int row = u.pm * 256 + ai * 128 + wr * 64 + m * 16 + fr;
;                 const float rs = rsqrtf(ss1[row] * (1.0f / DM) + EPS);
;                 const int posidx = row < MPROMPT ? (row & 2047) : 2048;
;                 f32x4 v[2][2];
; #pragma unroll
;                 for (int bj = 0; bj < 2; ++bj)
; #pragma unroll
;                     for (int n = 0; n < 2; ++n) v[bj][n] = acc[ai][bj][m][n] * rs;
;     ...
;                 } else if (kind == 7) {
; #pragma unroll
;                     for (int bj = 0; bj < 2; ++bj)
; #pragma unroll
;                         for (int n = 0; n < 2; ++n)
; #pragma unroll
;                             for (int j = 0; j < 4; ++j) v[bj][n][j] = fast_sigmoid(v[bj][n][j]);
.LBB0_814:
	s_nop 0
	v_or_b32_e32 v42, 32, v74
	v_ashrrev_i32_e32 v43, 31, v42
	v_lshl_add_u64 v[32:33], v[42:43], 2, s[28:29]
	v_mov_b32_e32 v32, v186
	v_bitop3_b32 v43, v74, s92, 32 bitop3:0xc8
	v_cmp_lt_i32_e64 s[18:19], s75, v42
	s_mov_b64 s[0:1], -1
	s_nop 0
	v_fmamk_f32 v32, v32, 0x3a800000, v174
	v_cmp_gt_f32_e32 vcc, s74, v32
	v_mul_f32_e32 v33, 0x4b800000, v32
	s_nop 0
	v_cndmask_b32_e32 v32, v32, v33, vcc
	v_rsq_f32_e32 v32, v32
	s_nop 0
	v_mul_f32_e32 v33, 0x45800000, v32
	v_cndmask_b32_e32 v36, v32, v33, vcc
	v_cmp_gt_i32_e32 vcc, s64, v42
	v_pk_mul_f32 v[44:45], v[30:31], v[36:37] op_sel_hi:[1,0]
	v_pk_mul_f32 v[48:49], v[28:29], v[36:37] op_sel_hi:[1,0]
	v_pk_mul_f32 v[40:41], v[26:27], v[36:37] op_sel_hi:[1,0]
	v_pk_mul_f32 v[46:47], v[24:25], v[36:37] op_sel_hi:[1,0]
	v_pk_mul_f32 v[34:35], v[22:23], v[36:37] op_sel_hi:[1,0]
	v_pk_mul_f32 v[38:39], v[20:21], v[36:37] op_sel_hi:[1,0]
	v_pk_mul_f32 v[32:33], v[18:19], v[36:37] op_sel_hi:[1,0]
	v_pk_mul_f32 v[36:37], v[16:17], v[36:37] op_sel_hi:[1,0]
	v_cndmask_b32_e32 v52, v177, v43, vcc
	s_and_b64 vcc, exec, s[16:17]
	s_cbranch_vccnz .LBB0_825
	s_and_b64 vcc, exec, s[12:13]
	s_cbranch_vccnz .LBB0_822
	s_cmp_gt_i32 s49, 6
	s_cbranch_scc0 .LBB0_818
	v_mul_f32_e32 v16, 0xbfb8aa3b, v48
	v_exp_f32_e32 v16, v16
	v_mul_f32_e32 v17, 0xbfb8aa3b, v49
	v_exp_f32_e32 v17, v17
	v_mul_f32_e32 v18, 0xbfb8aa3b, v45
	v_add_f32_e32 v16, 1.0, v16
	v_rcp_f32_e32 v20, v16
	v_mul_f32_e32 v16, 0xbfb8aa3b, v44
	v_exp_f32_e32 v16, v16
	v_exp_f32_e32 v18, v18
	v_add_f32_e32 v17, 1.0, v17
	v_rcp_f32_e32 v21, v17
	v_add_f32_e32 v16, 1.0, v16
	v_mul_f32_e32 v17, 0xbfb8aa3b, v46
	v_rcp_f32_e32 v22, v16
	v_add_f32_e32 v16, 1.0, v18
	v_exp_f32_e32 v17, v17
	v_mul_f32_e32 v18, 0xbfb8aa3b, v47
	v_exp_f32_e32 v18, v18
	v_rcp_f32_e32 v23, v16
	v_add_f32_e32 v16, 1.0, v17
	v_mul_f32_e32 v17, 0xbfb8aa3b, v40
	v_rcp_f32_e32 v28, v16
	v_add_f32_e32 v16, 1.0, v18
	v_exp_f32_e32 v17, v17
	v_mul_f32_e32 v18, 0xbfb8aa3b, v41
	v_exp_f32_e32 v18, v18
	v_rcp_f32_e32 v29, v16
	v_add_f32_e32 v16, 1.0, v17
	v_rcp_f32_e32 v30, v16
	v_add_f32_e32 v16, 1.0, v18
	v_mul_f32_e32 v17, 0xbfb8aa3b, v38
	v_mul_f32_e32 v18, 0xbfb8aa3b, v39
	v_exp_f32_e32 v17, v17
	v_exp_f32_e32 v18, v18
	v_rcp_f32_e32 v31, v16
	v_mul_f32_e32 v19, 0xbfb8aa3b, v35
	v_add_f32_e32 v16, 1.0, v17
	v_add_f32_e32 v17, 1.0, v18
	v_mul_f32_e32 v18, 0xbfb8aa3b, v34
	v_mul_f32_e32 v24, 0xbfb8aa3b, v36
	v_mul_f32_e32 v25, 0xbfb8aa3b, v37
	v_mul_f32_e32 v26, 0xbfb8aa3b, v32
	v_mul_f32_e32 v27, 0xbfb8aa3b, v33
	v_exp_f32_e32 v18, v18
	v_exp_f32_e32 v19, v19
	v_exp_f32_e32 v24, v24
	v_exp_f32_e32 v25, v25
	v_exp_f32_e32 v26, v26
	v_exp_f32_e32 v27, v27
	v_add_f32_e32 v18, 1.0, v18
	v_add_f32_e32 v19, 1.0, v19
	v_add_f32_e32 v24, 1.0, v24
	v_add_f32_e32 v25, 1.0, v25
	v_add_f32_e32 v26, 1.0, v26
	v_add_f32_e32 v27, 1.0, v27
	v_rcp_f32_e32 v16, v16
	v_rcp_f32_e32 v17, v17
	v_rcp_f32_e32 v18, v18
	v_rcp_f32_e32 v19, v19
	v_rcp_f32_e32 v24, v24
	v_rcp_f32_e32 v25, v25
	v_rcp_f32_e32 v26, v26
	v_rcp_f32_e32 v27, v27
	s_mov_b64 s[0:1], 0

;     __device__ __forceinline__ void operator()(const Acc& acc, const Unit& u, int wr, int wc, int fr, int fq) const {
;     ...
;                 } else if (kind == 3 || kind == 4) {
;                     const float ksc = (kind == 4) ? 0.0625f : 1.0f;
; #pragma unroll
;                     for (int bj = 0; bj < 2; ++bj)
; #pragma unroll
;                         for (int n = 0; n < 2; ++n) {
;                             const int i0 = (wc * 64 + bj * 32 + fq * 8 + n * 4) >> 1;
;                             const f32x4 cs = *(const f32x4*)(rrot + ((size_t)posidx * 128 + i0) * 2);
;                             const f32x4 x = v[bj][n]; f32x4 o;
;                             o[0] = (x[0] * cs[0] - x[1] * cs[1]) * ksc; o[1] = (x[1] * cs[0] + x[0] * cs[1]) * ksc;
;                             o[2] = (x[2] * cs[2] - x[3] * cs[3]) * ksc; o[3] = (x[3] * cs[2] + x[2] * cs[3]) * ksc;
;                             v[bj][n] = o;
;                         }
.LBB0_822:
	s_and_b64 vcc, exec, s[0:1]
	s_cbranch_vccz .LBB0_824
	v_lshlrev_b32_e32 v16, 2, v170
	v_lshl_or_b32 v50, v52, 10, v16
	v_add_u32_e32 v236, 0x4000, v50
	global_load_dwordx4 v[212:215], v236, s[20:21] offset:16
	global_load_dwordx4 v[216:219], v236, s[20:21]
	global_load_dwordx4 v[220:223], v236, s[20:21] offset:144
	global_load_dwordx4 v[224:227], v236, s[20:21] offset:128
	s_waitcnt vmcnt(6)
	v_mov_b32_e32 v16, v188
	v_mov_b32_e32 v17, v189
	v_mov_b32_e32 v18, v190
	v_mov_b32_e32 v19, v191
	v_mov_b32_e32 v20, v192
	v_mov_b32_e32 v21, v193
	v_mov_b32_e32 v22, v194
	v_mov_b32_e32 v23, v195
	v_pk_mul_f32 v[24:25], v[48:49], v[20:21] op_sel:[1,1] op_sel_hi:[0,1]
	v_pk_fma_f32 v[26:27], v[48:49], v[20:21], v[24:25] neg_lo:[0,0,1] neg_hi:[0,0,1]
	v_pk_fma_f32 v[20:21], v[48:49], v[20:21], v[24:25] op_sel_hi:[1,0,1]
	v_mul_f32_e32 v24, v45, v23
	v_mov_b32_e32 v27, v21
	v_pk_mul_f32 v[20:21], v[156:157], v[26:27] op_sel_hi:[0,1]
	v_mul_f32_e32 v26, v45, v22
	v_pk_fma_f32 v[24:25], v[44:45], v[22:23], v[24:25] op_sel_hi:[1,1,0] neg_lo:[0,0,1] neg_hi:[0,0,1]
	v_pk_fma_f32 v[22:23], v[44:45], v[22:23], v[26:27] op_sel:[1,0,0] op_sel_hi:[0,1,0]
	v_mov_b32_e32 v25, v23
	v_pk_mul_f32 v[22:23], v[156:157], v[24:25] op_sel_hi:[0,1]
	v_pk_mul_f32 v[24:25], v[46:47], v[16:17] op_sel:[1,1] op_sel_hi:[0,1]
	v_pk_fma_f32 v[26:27], v[46:47], v[16:17], v[24:25] neg_lo:[0,0,1] neg_hi:[0,0,1]
	v_pk_fma_f32 v[16:17], v[46:47], v[16:17], v[24:25] op_sel_hi:[1,0,1]
	v_mul_f32_e32 v24, v41, v18
	v_mul_f32_e32 v16, v41, v19
	v_mov_b32_e32 v27, v17
	v_pk_fma_f32 v[16:17], v[40:41], v[18:19], v[16:17] op_sel_hi:[1,1,0] neg_lo:[0,0,1] neg_hi:[0,0,1]
	v_pk_fma_f32 v[18:19], v[40:41], v[18:19], v[24:25] op_sel:[1,0,0] op_sel_hi:[0,1,0]
	v_mov_b32_e32 v17, v19
	v_pk_mul_f32 v[28:29], v[156:157], v[26:27] op_sel_hi:[0,1]
	v_pk_mul_f32 v[30:31], v[156:157], v[16:17] op_sel_hi:[0,1]
	v_mov_b32_e32 v24, v196
	v_mov_b32_e32 v25, v197
	v_mov_b32_e32 v26, v198
	v_mov_b32_e32 v27, v199
	v_mov_b32_e32 v16, v200
	v_mov_b32_e32 v17, v201
	v_mov_b32_e32 v18, v202
	v_mov_b32_e32 v19, v203
	s_nop 0
	v_pk_mul_f32 v[50:51], v[38:39], v[16:17] op_sel:[1,1] op_sel_hi:[0,1]
	v_pk_fma_f32 v[54:55], v[38:39], v[16:17], v[50:51] neg_lo:[0,0,1] neg_hi:[0,0,1]
	v_pk_fma_f32 v[16:17], v[38:39], v[16:17], v[50:51] op_sel_hi:[1,0,1]
	v_mul_f32_e32 v50, v35, v19
	v_mov_b32_e32 v55, v17
	v_pk_mul_f32 v[16:17], v[156:157], v[54:55] op_sel_hi:[0,1]
	v_mul_f32_e32 v54, v35, v18
	v_pk_fma_f32 v[50:51], v[34:35], v[18:19], v[50:51] op_sel_hi:[1,1,0] neg_lo:[0,0,1] neg_hi:[0,0,1]
	v_pk_fma_f32 v[18:19], v[34:35], v[18:19], v[54:55] op_sel:[1,0,0] op_sel_hi:[0,1,0]
	v_mov_b32_e32 v51, v19
	v_pk_mul_f32 v[18:19], v[156:157], v[50:51] op_sel_hi:[0,1]
	v_pk_mul_f32 v[50:51], v[36:37], v[24:25] op_sel:[1,1] op_sel_hi:[0,1]
	v_pk_fma_f32 v[54:55], v[36:37], v[24:25], v[50:51] neg_lo:[0,0,1] neg_hi:[0,0,1]
	v_pk_fma_f32 v[24:25], v[36:37], v[24:25], v[50:51] op_sel_hi:[1,0,1]
	v_mul_f32_e32 v50, v33, v27
	v_mov_b32_e32 v55, v25
	v_pk_mul_f32 v[24:25], v[156:157], v[54:55] op_sel_hi:[0,1]
	v_mul_f32_e32 v54, v33, v26
	v_pk_fma_f32 v[50:51], v[32:33], v[26:27], v[50:51] op_sel_hi:[1,1,0] neg_lo:[0,0,1] neg_hi:[0,0,1]
	v_pk_fma_f32 v[26:27], v[32:33], v[26:27], v[54:55] op_sel:[1,0,0] op_sel_hi:[0,1,0]
	v_mov_b32_e32 v51, v27
	v_pk_mul_f32 v[26:27], v[156:157], v[50:51] op_sel_hi:[0,1]

;     __device__ __forceinline__ void operator()(const Acc& acc, const Unit& u, int wr, int wc, int fr, int fq) const {
;     ...
;                 if (kind <= 1) {
;                     float s2 = 0.f;
; #pragma unroll
;                     for (int bj = 0; bj < 2; ++bj)
; #pragma unroll
;                         for (int n = 0; n < 2; ++n) s2 += (v[bj][n][0] * v[bj][n][0] + v[bj][n][1] * v[bj][n][1]) + (v[bj][n][2] * v[bj][n][2] + v[bj][n][3] * v[bj][n][3]);
;                     s2 += __shfl_xor(s2, 16); s2 += __shfl_xor(s2, 32);
;                     const float r = rsqrtf(s2 * (1.0f / 64.0f) + EPS);
; #pragma unroll
;                     for (int bj = 0; bj < 2; ++bj)
; #pragma unroll
;                         for (int n = 0; n < 2; ++n) { const f32x4 gv = *(const f32x4*)(gp + bj * 32 + fq * 8 + n * 4); v[bj][n] = v[bj][n] * r * gv; }
; #pragma unroll
;                     for (int n = 0; n < 2; ++n) { const f32x4 csa = *(const f32x4*)(rope + ((size_t)posidx * 8 + 4 * n) * 2), csb = *(const f32x4*)(rope + ((size_t)posidx * 8 + 4 * n) * 2 + 4);
;                         const float cc[4] = {csa[0], csa[2], csb[0], csb[2]}, sn[4] = {csa[1], csa[3], csb[1], csb[3]};
; #pragma unroll
;                         for (int j = 0; j < 4; ++j) { const float mine = v[0][n][j], other = __shfl_xor(mine, 16);
;                             const float rot = (fq == 0) ? (mine * cc[j] - other * sn[j]) : (mine * cc[j] + other * sn[j]);
;                             v[0][n][j] = (fq < 2) ? rot : mine; } }
;                     if (kind == 0) {
; #pragma unroll
;                         for (int bj = 0; bj < 2; ++bj)
; #pragma unroll
;                             for (int n = 0; n < 2; ++n) v[bj][n] = v[bj][n] * 0.125f;
;                     }
.LBB0_825:
	s_andn2_b64 vcc, exec, s[0:1]
	s_cbranch_vccnz .LBB0_828
	v_pk_mul_f32 v[16:17], v[44:45], v[44:45]
	v_pk_mul_f32 v[18:19], v[48:49], v[48:49]
	s_nop 0
	v_pk_mov_b32 v[20:21], v[18:19], v[16:17] op_sel:[1,0]
	v_mov_b32_e32 v19, v17
	v_pk_add_f32 v[16:17], v[20:21], v[18:19]
	v_pk_mul_f32 v[18:19], v[40:41], v[40:41]
	v_pk_add_f32 v[16:17], v[16:17], v[16:17] op_sel_hi:[0,1]
	v_pk_mul_f32 v[20:21], v[46:47], v[46:47]
	v_mul_f32_e32 v16, v38, v38
	v_pk_mov_b32 v[22:23], v[20:21], v[18:19] op_sel:[1,0]
	v_mov_b32_e32 v21, v19
	v_pk_add_f32 v[18:19], v[22:23], v[20:21]
	v_pk_fma_f32 v[20:21], v[38:39], v[38:39], v[16:17] op_sel_hi:[1,1,0]
	v_mul_f32_e32 v16, v34, v34
	v_pk_add_f32 v[18:19], v[18:19], v[18:19] op_sel_hi:[0,1]
	v_pk_fma_f32 v[22:23], v[34:35], v[34:35], v[16:17] op_sel_hi:[1,1,0]
	v_mul_f32_e32 v20, v36, v36
	v_mul_f32_e32 v22, v37, v37
	v_mul_f32_e32 v16, v32, v32
	v_mul_f32_e32 v18, v33, v33
	v_pk_add_f32 v[20:21], v[20:21], v[22:23]
	v_pk_add_f32 v[16:17], v[16:17], v[18:19]
	v_and_b32_e32 v18, 64, v178
	v_pk_add_f32 v[16:17], v[20:21], v[16:17]
	v_add_u32_e32 v18, 64, v18
	v_add_f32_e32 v16, v16, v17
	v_xor_b32_e32 v17, 16, v178
	v_cmp_lt_i32_e32 vcc, v17, v18
	s_nop 1
	v_cndmask_b32_e32 v17, v178, v17, vcc
	v_lshlrev_b32_e32 v53, 2, v17
	ds_bpermute_b32 v17, v53, v16
	s_waitcnt lgkmcnt(0)
	v_add_f32_e32 v16, v16, v17
	v_xor_b32_e32 v17, 32, v178
	v_cmp_lt_i32_e32 vcc, v17, v18
	s_nop 1
	v_cndmask_b32_e32 v17, v178, v17, vcc
	v_lshlrev_b32_e32 v17, 2, v17
	ds_bpermute_b32 v17, v17, v16
	s_waitcnt lgkmcnt(0)
	v_add_f32_e32 v16, v16, v17
	v_fmamk_f32 v16, v16, 0x3c800000, v174
	v_cmp_gt_f32_e32 vcc, s74, v16
	v_mul_f32_e32 v17, 0x4b800000, v16
	s_nop 0
	v_cndmask_b32_e32 v16, v16, v17, vcc
	v_rsq_f32_e32 v16, v16
	s_nop 0
	v_mul_f32_e32 v17, 0x45800000, v16
	v_cndmask_b32_e32 v20, v16, v17, vcc
	v_mov_b32_e32 v16, v188
	v_mov_b32_e32 v17, v189
	v_mov_b32_e32 v18, v190
	v_mov_b32_e32 v19, v191
	v_mov_b32_e32 v22, v192
	v_mov_b32_e32 v23, v193
	v_mov_b32_e32 v24, v194
	v_mov_b32_e32 v25, v195
	v_pk_mul_f32 v[26:27], v[48:49], v[20:21] op_sel_hi:[1,0]
	v_pk_mul_f32 v[28:29], v[44:45], v[20:21] op_sel_hi:[1,0]
	v_pk_mul_f32 v[30:31], v[34:35], v[20:21] op_sel_hi:[1,0]
	s_and_b64 vcc, exec, s[10:11]
	s_nop 0
	v_pk_mul_f32 v[48:49], v[24:25], v[28:29]
	v_pk_mul_f32 v[50:51], v[22:23], v[26:27]
	v_pk_mul_f32 v[22:23], v[46:47], v[20:21] op_sel_hi:[1,0]
	v_pk_mul_f32 v[24:25], v[40:41], v[20:21] op_sel_hi:[1,0]
	v_pk_mul_f32 v[28:29], v[16:17], v[22:23]
	v_pk_mul_f32 v[44:45], v[18:19], v[24:25]
	v_mov_b32_e32 v22, v196
	v_mov_b32_e32 v23, v197
	v_mov_b32_e32 v24, v198
	v_mov_b32_e32 v25, v199
	v_mov_b32_e32 v16, v200
	v_mov_b32_e32 v17, v201
	v_mov_b32_e32 v18, v202
	v_mov_b32_e32 v19, v203
	v_pk_mul_f32 v[26:27], v[38:39], v[20:21] op_sel_hi:[1,0]
	ds_bpermute_b32 v46, v53, v50
	s_nop 0
	v_pk_mul_f32 v[18:19], v[18:19], v[30:31]
	v_pk_mul_f32 v[30:31], v[36:37], v[20:21] op_sel_hi:[1,0]
	v_pk_mul_f32 v[20:21], v[32:33], v[20:21] op_sel_hi:[1,0]
	v_pk_mul_f32 v[16:17], v[16:17], v[26:27]
	v_pk_mul_f32 v[26:27], v[24:25], v[20:21]
	v_lshlrev_b32_e32 v20, 6, v52
	v_pk_mul_f32 v[24:25], v[22:23], v[30:31]
	s_waitcnt vmcnt(2)
	v_mov_b32_e32 v30, v212
	v_mov_b32_e32 v31, v213
	v_mov_b32_e32 v32, v214
	v_mov_b32_e32 v33, v215
	v_mov_b32_e32 v34, v216
	v_mov_b32_e32 v35, v217
	v_mov_b32_e32 v36, v218
	v_mov_b32_e32 v37, v219
	v_mov_b32_e32 v38, v220
	v_mov_b32_e32 v39, v221
	v_mov_b32_e32 v40, v222
	v_mov_b32_e32 v41, v223
	s_nop 0
	v_mov_b32_e32 v20, v224
	v_mov_b32_e32 v21, v225
	v_mov_b32_e32 v22, v226
	v_mov_b32_e32 v23, v227
	v_lshlrev_b32_e32 v236, 6, v52
	v_add_u32_e32 v236, 1024, v236
	global_load_dwordx4 v[212:215], v236, s[26:27] offset:48
	global_load_dwordx4 v[216:219], v236, s[26:27] offset:32
	global_load_dwordx4 v[220:223], v236, s[26:27] offset:16
	global_load_dwordx4 v[224:227], v236, s[26:27]
	s_waitcnt lgkmcnt(0)
	v_mul_f32_e32 v21, v21, v46
	v_cndmask_b32_e64 v21, v21, -v21, s[4:5]
	v_fmac_f32_e32 v21, v20, v50
	v_cndmask_b32_e64 v20, v50, v21, s[6:7]
	ds_bpermute_b32 v21, v53, v51
	s_waitcnt lgkmcnt(0)
	v_mul_f32_e32 v21, v23, v21
	v_cndmask_b32_e64 v21, v21, -v21, s[4:5]
	v_fmac_f32_e32 v21, v22, v51
	ds_bpermute_b32 v22, v53, v48
	ds_bpermute_b32 v23, v53, v49
	v_cndmask_b32_e64 v21, v51, v21, s[6:7]
	s_waitcnt lgkmcnt(1)
	v_mul_f32_e32 v22, v39, v22
	v_cndmask_b32_e64 v22, v22, -v22, s[4:5]
	v_fmac_f32_e32 v22, v38, v48
	ds_bpermute_b32 v38, v53, v28
	s_waitcnt lgkmcnt(1)
	v_mul_f32_e32 v23, v41, v23
	v_cndmask_b32_e64 v23, v23, -v23, s[4:5]
	v_fmac_f32_e32 v23, v40, v49
	v_cndmask_b32_e64 v22, v48, v22, s[6:7]
	s_waitcnt lgkmcnt(0)
	v_mul_f32_e32 v35, v35, v38
	v_cndmask_b32_e64 v35, v35, -v35, s[4:5]
	v_fmac_f32_e32 v35, v34, v28
	ds_bpermute_b32 v34, v53, v29
	v_cndmask_b32_e64 v23, v49, v23, s[6:7]
	v_cndmask_b32_e64 v28, v28, v35, s[6:7]
	s_waitcnt lgkmcnt(0)
	v_mul_f32_e32 v34, v37, v34
	v_cndmask_b32_e64 v34, v34, -v34, s[4:5]
	v_fmac_f32_e32 v34, v36, v29
	v_cndmask_b32_e64 v29, v29, v34, s[6:7]
	ds_bpermute_b32 v34, v53, v44
	s_waitcnt lgkmcnt(0)
	v_mul_f32_e32 v31, v31, v34
	v_cndmask_b32_e64 v31, v31, -v31, s[4:5]
	v_fmac_f32_e32 v31, v30, v44
	v_cndmask_b32_e64 v30, v44, v31, s[6:7]
	ds_bpermute_b32 v31, v53, v45
	s_waitcnt lgkmcnt(0)
	v_mul_f32_e32 v31, v33, v31
	v_cndmask_b32_e64 v31, v31, -v31, s[4:5]
	v_fmac_f32_e32 v31, v32, v45
	v_cndmask_b32_e64 v31, v45, v31, s[6:7]
	s_cbranch_vccnz .LBB0_828
	v_pk_mul_f32 v[22:23], v[22:23], s[42:43] op_sel_hi:[1,0]
	v_pk_mul_f32 v[20:21], v[20:21], s[42:43] op_sel_hi:[1,0]
	v_pk_mul_f32 v[30:31], v[30:31], s[42:43] op_sel_hi:[1,0]
	v_pk_mul_f32 v[28:29], v[28:29], s[42:43] op_sel_hi:[1,0]
	v_pk_mul_f32 v[18:19], v[18:19], s[42:43] op_sel_hi:[1,0]
	v_pk_mul_f32 v[16:17], v[16:17], s[42:43] op_sel_hi:[1,0]
	v_pk_mul_f32 v[26:27], v[26:27], s[42:43] op_sel_hi:[1,0]
	v_pk_mul_f32 v[24:25], v[24:25], s[42:43] op_sel_hi:[1,0]

; __device__ __forceinline__ float fast_sigmoid(float a) { return __builtin_amdgcn_rcpf(1.0f + __expf(-a)); }
;     __device__ __forceinline__ void operator()(const Acc& acc, const Unit& u, int wr, int wc, int fr, int fq) const {
;     ...
;                 const int row = u.pm * 256 + ai * 128 + wr * 64 + m * 16 + fr;
;                 const float rs = rsqrtf(ss1[row] * (1.0f / DM) + EPS);
;                 const int posidx = row < MPROMPT ? (row & 2047) : 2048;
;                 f32x4 v[2][2];
; #pragma unroll
;                 for (int bj = 0; bj < 2; ++bj)
; #pragma unroll
;                     for (int n = 0; n < 2; ++n) v[bj][n] = acc[ai][bj][m][n] * rs;
;     ...
;                 } else if (kind == 7) {
; #pragma unroll
;                     for (int bj = 0; bj < 2; ++bj)
; #pragma unroll
;                         for (int n = 0; n < 2; ++n)
; #pragma unroll
;                             for (int j = 0; j < 4; ++j) v[bj][n][j] = fast_sigmoid(v[bj][n][j]);
.LBB0_834:
	s_nop 0
	v_or_b32_e32 v26, 48, v74
	v_ashrrev_i32_e32 v27, 31, v26
	v_lshl_add_u64 v[16:17], v[26:27], 2, s[28:29]
	v_mov_b32_e32 v16, v187
	v_bitop3_b32 v27, v74, s96, 48 bitop3:0xc8
	v_cmp_gt_i32_e64 s[18:19], s64, v26
	s_and_b64 vcc, exec, s[16:17]
	v_cmp_lt_i32_e64 s[16:17], s75, v26
	v_cndmask_b32_e64 v36, v177, v27, s[18:19]
	s_nop 0
	v_fmamk_f32 v16, v16, 0x3a800000, v174
	v_mul_f32_e32 v17, 0x4b800000, v16
	v_cmp_gt_f32_e64 s[0:1], s74, v16
	s_nop 1
	v_cndmask_b32_e64 v16, v16, v17, s[0:1]
	v_rsq_f32_e32 v16, v16
	s_nop 0
	v_mul_f32_e32 v17, 0x45800000, v16
	v_cndmask_b32_e64 v20, v16, v17, s[0:1]
	v_pk_mul_f32 v[28:29], v[14:15], v[20:21] op_sel_hi:[1,0]
	v_pk_mul_f32 v[32:33], v[12:13], v[20:21] op_sel_hi:[1,0]
	v_pk_mul_f32 v[24:25], v[10:11], v[20:21] op_sel_hi:[1,0]
	v_pk_mul_f32 v[30:31], v[8:9], v[20:21] op_sel_hi:[1,0]
	v_pk_mul_f32 v[18:19], v[6:7], v[20:21] op_sel_hi:[1,0]
	v_pk_mul_f32 v[22:23], v[4:5], v[20:21] op_sel_hi:[1,0]
	v_pk_mul_f32 v[16:17], v[2:3], v[20:21] op_sel_hi:[1,0]
	v_pk_mul_f32 v[20:21], v[0:1], v[20:21] op_sel_hi:[1,0]
	s_mov_b64 s[0:1], -1
	s_cbranch_vccnz .LBB0_845
	s_and_b64 vcc, exec, s[12:13]
	s_cbranch_vccnz .LBB0_842
	s_cmp_gt_i32 s49, 6
	s_cbranch_scc0 .LBB0_838
	v_mul_f32_e32 v0, 0xbfb8aa3b, v32
	v_exp_f32_e32 v0, v0
	v_mul_f32_e32 v1, 0xbfb8aa3b, v33
	v_exp_f32_e32 v1, v1
	v_mul_f32_e32 v2, 0xbfb8aa3b, v29
	v_add_f32_e32 v0, 1.0, v0
	v_rcp_f32_e32 v4, v0
	v_mul_f32_e32 v0, 0xbfb8aa3b, v28
	v_exp_f32_e32 v0, v0
	v_exp_f32_e32 v2, v2
	v_add_f32_e32 v1, 1.0, v1
	v_rcp_f32_e32 v5, v1
	v_add_f32_e32 v0, 1.0, v0
	v_mul_f32_e32 v1, 0xbfb8aa3b, v30
	v_rcp_f32_e32 v6, v0
	v_add_f32_e32 v0, 1.0, v2
	v_exp_f32_e32 v1, v1
	v_mul_f32_e32 v2, 0xbfb8aa3b, v31
	v_exp_f32_e32 v2, v2
	v_rcp_f32_e32 v7, v0
	v_add_f32_e32 v0, 1.0, v1
	v_mul_f32_e32 v1, 0xbfb8aa3b, v24
	v_rcp_f32_e32 v12, v0
	v_add_f32_e32 v0, 1.0, v2
	v_exp_f32_e32 v1, v1
	v_mul_f32_e32 v2, 0xbfb8aa3b, v25
	v_exp_f32_e32 v2, v2
	v_rcp_f32_e32 v13, v0
	v_add_f32_e32 v0, 1.0, v1
	v_rcp_f32_e32 v14, v0
	v_add_f32_e32 v0, 1.0, v2
	v_mul_f32_e32 v1, 0xbfb8aa3b, v22
	v_mul_f32_e32 v2, 0xbfb8aa3b, v23
	v_exp_f32_e32 v1, v1
	v_exp_f32_e32 v2, v2
	v_rcp_f32_e32 v15, v0
	v_mul_f32_e32 v3, 0xbfb8aa3b, v19
	v_add_f32_e32 v0, 1.0, v1
	v_add_f32_e32 v1, 1.0, v2
	v_mul_f32_e32 v2, 0xbfb8aa3b, v18
	v_mul_f32_e32 v8, 0xbfb8aa3b, v20
	v_mul_f32_e32 v9, 0xbfb8aa3b, v21
	v_mul_f32_e32 v10, 0xbfb8aa3b, v16
	v_mul_f32_e32 v11, 0xbfb8aa3b, v17
	v_exp_f32_e32 v2, v2
	v_exp_f32_e32 v3, v3
	v_exp_f32_e32 v8, v8
	v_exp_f32_e32 v9, v9
	v_exp_f32_e32 v10, v10
	v_exp_f32_e32 v11, v11
	v_add_f32_e32 v2, 1.0, v2
	v_add_f32_e32 v3, 1.0, v3
	v_add_f32_e32 v8, 1.0, v8
	v_add_f32_e32 v9, 1.0, v9
	v_add_f32_e32 v10, 1.0, v10
	v_add_f32_e32 v11, 1.0, v11
	v_rcp_f32_e32 v0, v0
	v_rcp_f32_e32 v1, v1
	v_rcp_f32_e32 v2, v2
	v_rcp_f32_e32 v3, v3
	v_rcp_f32_e32 v8, v8
	v_rcp_f32_e32 v9, v9
	v_rcp_f32_e32 v10, v10
	v_rcp_f32_e32 v11, v11
	s_mov_b64 s[0:1], 0

;     __device__ __forceinline__ void operator()(const Acc& acc, const Unit& u, int wr, int wc, int fr, int fq) const {
;     ...
;                 } else if (kind == 3 || kind == 4) {
;                     const float ksc = (kind == 4) ? 0.0625f : 1.0f;
; #pragma unroll
;                     for (int bj = 0; bj < 2; ++bj)
; #pragma unroll
;                         for (int n = 0; n < 2; ++n) {
;                             const int i0 = (wc * 64 + bj * 32 + fq * 8 + n * 4) >> 1;
;                             const f32x4 cs = *(const f32x4*)(rrot + ((size_t)posidx * 128 + i0) * 2);
;                             const f32x4 x = v[bj][n]; f32x4 o;
;                             o[0] = (x[0] * cs[0] - x[1] * cs[1]) * ksc; o[1] = (x[1] * cs[0] + x[0] * cs[1]) * ksc;
;                             o[2] = (x[2] * cs[2] - x[3] * cs[3]) * ksc; o[3] = (x[3] * cs[2] + x[2] * cs[3]) * ksc;
;                             v[bj][n] = o;
;                         }
.LBB0_842:
	s_and_b64 vcc, exec, s[0:1]
	s_cbranch_vccz .LBB0_844
	v_lshlrev_b32_e32 v0, 2, v170
	v_lshl_or_b32 v34, v36, 10, v0
	s_waitcnt vmcnt(2)
	v_mov_b32_e32 v0, v212
	v_mov_b32_e32 v1, v213
	v_mov_b32_e32 v2, v214
	v_mov_b32_e32 v3, v215
	v_mov_b32_e32 v4, v216
	v_mov_b32_e32 v5, v217
	v_mov_b32_e32 v6, v218
	v_mov_b32_e32 v7, v219
	v_pk_mul_f32 v[8:9], v[32:33], v[4:5] op_sel:[1,1] op_sel_hi:[0,1]
	v_pk_fma_f32 v[10:11], v[32:33], v[4:5], v[8:9] neg_lo:[0,0,1] neg_hi:[0,0,1]
	v_pk_fma_f32 v[4:5], v[32:33], v[4:5], v[8:9] op_sel_hi:[1,0,1]
	v_mul_f32_e32 v8, v29, v7
	v_mov_b32_e32 v11, v5
	v_pk_mul_f32 v[4:5], v[156:157], v[10:11] op_sel_hi:[0,1]
	v_mul_f32_e32 v10, v29, v6
	v_pk_fma_f32 v[8:9], v[28:29], v[6:7], v[8:9] op_sel_hi:[1,1,0] neg_lo:[0,0,1] neg_hi:[0,0,1]
	v_pk_fma_f32 v[6:7], v[28:29], v[6:7], v[10:11] op_sel:[1,0,0] op_sel_hi:[0,1,0]
	v_mov_b32_e32 v9, v7
	v_pk_mul_f32 v[6:7], v[156:157], v[8:9] op_sel_hi:[0,1]
	v_pk_mul_f32 v[8:9], v[30:31], v[0:1] op_sel:[1,1] op_sel_hi:[0,1]
	v_pk_fma_f32 v[10:11], v[30:31], v[0:1], v[8:9] neg_lo:[0,0,1] neg_hi:[0,0,1]
	v_pk_fma_f32 v[0:1], v[30:31], v[0:1], v[8:9] op_sel_hi:[1,0,1]
	v_mul_f32_e32 v8, v25, v2
	v_mul_f32_e32 v0, v25, v3
	v_mov_b32_e32 v11, v1
	v_pk_fma_f32 v[0:1], v[24:25], v[2:3], v[0:1] op_sel_hi:[1,1,0] neg_lo:[0,0,1] neg_hi:[0,0,1]
	v_pk_fma_f32 v[2:3], v[24:25], v[2:3], v[8:9] op_sel:[1,0,0] op_sel_hi:[0,1,0]
	v_mov_b32_e32 v1, v3
	v_pk_mul_f32 v[12:13], v[156:157], v[10:11] op_sel_hi:[0,1]
	v_pk_mul_f32 v[14:15], v[156:157], v[0:1] op_sel_hi:[0,1]
	v_mov_b32_e32 v8, v220
	v_mov_b32_e32 v9, v221
	v_mov_b32_e32 v10, v222
	v_mov_b32_e32 v11, v223
	v_mov_b32_e32 v0, v224
	v_mov_b32_e32 v1, v225
	v_mov_b32_e32 v2, v226
	v_mov_b32_e32 v3, v227
	s_nop 0
	v_pk_mul_f32 v[34:35], v[22:23], v[0:1] op_sel:[1,1] op_sel_hi:[0,1]
	v_pk_fma_f32 v[38:39], v[22:23], v[0:1], v[34:35] neg_lo:[0,0,1] neg_hi:[0,0,1]
	v_pk_fma_f32 v[0:1], v[22:23], v[0:1], v[34:35] op_sel_hi:[1,0,1]
	v_mul_f32_e32 v34, v19, v3
	v_mov_b32_e32 v39, v1
	v_pk_mul_f32 v[0:1], v[156:157], v[38:39] op_sel_hi:[0,1]
	v_mul_f32_e32 v38, v19, v2
	v_pk_fma_f32 v[34:35], v[18:19], v[2:3], v[34:35] op_sel_hi:[1,1,0] neg_lo:[0,0,1] neg_hi:[0,0,1]
	v_pk_fma_f32 v[2:3], v[18:19], v[2:3], v[38:39] op_sel:[1,0,0] op_sel_hi:[0,1,0]
	v_mov_b32_e32 v35, v3
	v_pk_mul_f32 v[2:3], v[156:157], v[34:35] op_sel_hi:[0,1]
	v_pk_mul_f32 v[34:35], v[20:21], v[8:9] op_sel:[1,1] op_sel_hi:[0,1]
	v_pk_fma_f32 v[38:39], v[20:21], v[8:9], v[34:35] neg_lo:[0,0,1] neg_hi:[0,0,1]
	v_pk_fma_f32 v[8:9], v[20:21], v[8:9], v[34:35] op_sel_hi:[1,0,1]
	v_mul_f32_e32 v34, v17, v11
	v_mov_b32_e32 v39, v9
	v_pk_mul_f32 v[8:9], v[156:157], v[38:39] op_sel_hi:[0,1]
	v_mul_f32_e32 v38, v17, v10
	v_pk_fma_f32 v[34:35], v[16:17], v[10:11], v[34:35] op_sel_hi:[1,1,0] neg_lo:[0,0,1] neg_hi:[0,0,1]
	v_pk_fma_f32 v[10:11], v[16:17], v[10:11], v[38:39] op_sel:[1,0,0] op_sel_hi:[0,1,0]
	v_mov_b32_e32 v35, v11
	v_pk_mul_f32 v[10:11], v[156:157], v[34:35] op_sel_hi:[0,1]

;     __device__ __forceinline__ void operator()(const Acc& acc, const Unit& u, int wr, int wc, int fr, int fq) const {
;     ...
;                 if (kind <= 1) {
;                     float s2 = 0.f;
; #pragma unroll
;                     for (int bj = 0; bj < 2; ++bj)
; #pragma unroll
;                         for (int n = 0; n < 2; ++n) s2 += (v[bj][n][0] * v[bj][n][0] + v[bj][n][1] * v[bj][n][1]) + (v[bj][n][2] * v[bj][n][2] + v[bj][n][3] * v[bj][n][3]);
;                     s2 += __shfl_xor(s2, 16); s2 += __shfl_xor(s2, 32);
;                     const float r = rsqrtf(s2 * (1.0f / 64.0f) + EPS);
; #pragma unroll
;                     for (int bj = 0; bj < 2; ++bj)
; #pragma unroll
;                         for (int n = 0; n < 2; ++n) { const f32x4 gv = *(const f32x4*)(gp + bj * 32 + fq * 8 + n * 4); v[bj][n] = v[bj][n] * r * gv; }
; #pragma unroll
;                     for (int n = 0; n < 2; ++n) { const f32x4 csa = *(const f32x4*)(rope + ((size_t)posidx * 8 + 4 * n) * 2), csb = *(const f32x4*)(rope + ((size_t)posidx * 8 + 4 * n) * 2 + 4);
;                         const float cc[4] = {csa[0], csa[2], csb[0], csb[2]}, sn[4] = {csa[1], csa[3], csb[1], csb[3]};
; #pragma unroll
;                         for (int j = 0; j < 4; ++j) { const float mine = v[0][n][j], other = __shfl_xor(mine, 16);
;                             const float rot = (fq == 0) ? (mine * cc[j] - other * sn[j]) : (mine * cc[j] + other * sn[j]);
;                             v[0][n][j] = (fq < 2) ? rot : mine; } }
;                     if (kind == 0) {
; #pragma unroll
;                         for (int bj = 0; bj < 2; ++bj)
; #pragma unroll
;                             for (int n = 0; n < 2; ++n) v[bj][n] = v[bj][n] * 0.125f;
;                     }
.LBB0_845:
	s_andn2_b64 vcc, exec, s[0:1]
	s_cbranch_vccnz .LBB0_848
	v_pk_mul_f32 v[0:1], v[28:29], v[28:29]
	v_pk_mul_f32 v[2:3], v[32:33], v[32:33]
	s_nop 0
	v_pk_mov_b32 v[4:5], v[2:3], v[0:1] op_sel:[1,0]
	v_mov_b32_e32 v3, v1
	v_pk_add_f32 v[0:1], v[4:5], v[2:3]
	v_pk_mul_f32 v[2:3], v[24:25], v[24:25]
	v_pk_add_f32 v[0:1], v[0:1], v[0:1] op_sel_hi:[0,1]
	v_pk_mul_f32 v[4:5], v[30:31], v[30:31]
	v_mul_f32_e32 v0, v22, v22
	v_pk_mov_b32 v[6:7], v[4:5], v[2:3] op_sel:[1,0]
	v_mov_b32_e32 v5, v3
	v_pk_add_f32 v[2:3], v[6:7], v[4:5]
	v_pk_fma_f32 v[4:5], v[22:23], v[22:23], v[0:1] op_sel_hi:[1,1,0]
	v_mul_f32_e32 v0, v18, v18
	v_pk_add_f32 v[2:3], v[2:3], v[2:3] op_sel_hi:[0,1]
	v_pk_fma_f32 v[6:7], v[18:19], v[18:19], v[0:1] op_sel_hi:[1,1,0]
	v_mul_f32_e32 v4, v20, v20
	v_mul_f32_e32 v6, v21, v21
	v_mul_f32_e32 v0, v16, v16
	v_mul_f32_e32 v2, v17, v17
	v_pk_add_f32 v[4:5], v[4:5], v[6:7]
	v_pk_add_f32 v[0:1], v[0:1], v[2:3]
	v_and_b32_e32 v2, 64, v178
	v_pk_add_f32 v[0:1], v[4:5], v[0:1]
	v_add_u32_e32 v2, 64, v2
	v_add_f32_e32 v0, v0, v1
	v_xor_b32_e32 v1, 16, v178
	v_cmp_lt_i32_e32 vcc, v1, v2
	s_nop 1
	v_cndmask_b32_e32 v1, v178, v1, vcc
	v_lshlrev_b32_e32 v37, 2, v1
	ds_bpermute_b32 v1, v37, v0
	s_waitcnt lgkmcnt(0)
	v_add_f32_e32 v0, v0, v1
	v_xor_b32_e32 v1, 32, v178
	v_cmp_lt_i32_e32 vcc, v1, v2
	s_nop 1
	v_cndmask_b32_e32 v1, v178, v1, vcc
	v_lshlrev_b32_e32 v1, 2, v1
	ds_bpermute_b32 v1, v1, v0
	s_waitcnt lgkmcnt(0)
	v_add_f32_e32 v0, v0, v1
	v_fmamk_f32 v0, v0, 0x3c800000, v174
	v_cmp_gt_f32_e32 vcc, s74, v0
	v_mul_f32_e32 v1, 0x4b800000, v0
	s_nop 0
	v_cndmask_b32_e32 v0, v0, v1, vcc
	v_rsq_f32_e32 v0, v0
	s_nop 0
	v_mul_f32_e32 v1, 0x45800000, v0
	v_cndmask_b32_e32 v4, v0, v1, vcc
	v_mov_b32_e32 v0, v188
	v_mov_b32_e32 v1, v189
	v_mov_b32_e32 v2, v190
	v_mov_b32_e32 v3, v191
	v_mov_b32_e32 v6, v192
	v_mov_b32_e32 v7, v193
	v_mov_b32_e32 v8, v194
	v_mov_b32_e32 v9, v195
	v_pk_mul_f32 v[10:11], v[32:33], v[4:5] op_sel_hi:[1,0]
	v_pk_mul_f32 v[12:13], v[28:29], v[4:5] op_sel_hi:[1,0]
	v_pk_mul_f32 v[14:15], v[18:19], v[4:5] op_sel_hi:[1,0]
	s_and_b64 vcc, exec, s[10:11]
	s_nop 0
	v_pk_mul_f32 v[32:33], v[8:9], v[12:13]
	v_pk_mul_f32 v[34:35], v[6:7], v[10:11]
	v_pk_mul_f32 v[6:7], v[30:31], v[4:5] op_sel_hi:[1,0]
	v_pk_mul_f32 v[8:9], v[24:25], v[4:5] op_sel_hi:[1,0]
	v_pk_mul_f32 v[12:13], v[0:1], v[6:7]
	v_pk_mul_f32 v[28:29], v[2:3], v[8:9]
	v_mov_b32_e32 v6, v196
	v_mov_b32_e32 v7, v197
	v_mov_b32_e32 v8, v198
	v_mov_b32_e32 v9, v199
	v_mov_b32_e32 v0, v200
	v_mov_b32_e32 v1, v201
	v_mov_b32_e32 v2, v202
	v_mov_b32_e32 v3, v203
	v_pk_mul_f32 v[10:11], v[22:23], v[4:5] op_sel_hi:[1,0]
	ds_bpermute_b32 v30, v37, v34
	s_nop 0
	v_pk_mul_f32 v[2:3], v[2:3], v[14:15]
	v_pk_mul_f32 v[14:15], v[20:21], v[4:5] op_sel_hi:[1,0]
	v_pk_mul_f32 v[4:5], v[16:17], v[4:5] op_sel_hi:[1,0]
	v_pk_mul_f32 v[0:1], v[0:1], v[10:11]
	v_pk_mul_f32 v[10:11], v[8:9], v[4:5]
	v_lshlrev_b32_e32 v4, 6, v36
	v_pk_mul_f32 v[8:9], v[6:7], v[14:15]
	s_waitcnt vmcnt(2)
	v_mov_b32_e32 v14, v212
	v_mov_b32_e32 v15, v213
	v_mov_b32_e32 v16, v214
	v_mov_b32_e32 v17, v215
	v_mov_b32_e32 v18, v216
	v_mov_b32_e32 v19, v217
	v_mov_b32_e32 v20, v218
	v_mov_b32_e32 v21, v219
	v_mov_b32_e32 v22, v220
	v_mov_b32_e32 v23, v221
	v_mov_b32_e32 v24, v222
	v_mov_b32_e32 v25, v223
	s_nop 0
	v_mov_b32_e32 v4, v224
	v_mov_b32_e32 v5, v225
	v_mov_b32_e32 v6, v226
	v_mov_b32_e32 v7, v227
	s_waitcnt lgkmcnt(0)
	v_mul_f32_e32 v5, v5, v30
	v_cndmask_b32_e64 v5, v5, -v5, s[4:5]
	v_fmac_f32_e32 v5, v4, v34
	v_cndmask_b32_e64 v4, v34, v5, s[6:7]
	ds_bpermute_b32 v5, v37, v35
	s_waitcnt lgkmcnt(0)
	v_mul_f32_e32 v5, v7, v5
	v_cndmask_b32_e64 v5, v5, -v5, s[4:5]
	v_fmac_f32_e32 v5, v6, v35
	ds_bpermute_b32 v6, v37, v32
	ds_bpermute_b32 v7, v37, v33
	v_cndmask_b32_e64 v5, v35, v5, s[6:7]
	s_waitcnt lgkmcnt(1)
	v_mul_f32_e32 v6, v23, v6
	v_cndmask_b32_e64 v6, v6, -v6, s[4:5]
	v_fmac_f32_e32 v6, v22, v32
	ds_bpermute_b32 v22, v37, v12
	s_waitcnt lgkmcnt(1)
	v_mul_f32_e32 v7, v25, v7
	v_cndmask_b32_e64 v7, v7, -v7, s[4:5]
	v_fmac_f32_e32 v7, v24, v33
	v_cndmask_b32_e64 v6, v32, v6, s[6:7]
	s_waitcnt lgkmcnt(0)
	v_mul_f32_e32 v19, v19, v22
	v_cndmask_b32_e64 v19, v19, -v19, s[4:5]
	v_fmac_f32_e32 v19, v18, v12
	ds_bpermute_b32 v18, v37, v13
	v_cndmask_b32_e64 v7, v33, v7, s[6:7]
	v_cndmask_b32_e64 v12, v12, v19, s[6:7]
	s_waitcnt lgkmcnt(0)
	v_mul_f32_e32 v18, v21, v18
	v_cndmask_b32_e64 v18, v18, -v18, s[4:5]
	v_fmac_f32_e32 v18, v20, v13
	v_cndmask_b32_e64 v13, v13, v18, s[6:7]
	ds_bpermute_b32 v18, v37, v28
	s_waitcnt lgkmcnt(0)
	v_mul_f32_e32 v15, v15, v18
	v_cndmask_b32_e64 v15, v15, -v15, s[4:5]
	v_fmac_f32_e32 v15, v14, v28
	v_cndmask_b32_e64 v14, v28, v15, s[6:7]
	ds_bpermute_b32 v15, v37, v29
	s_waitcnt lgkmcnt(0)
	v_mul_f32_e32 v15, v17, v15
	v_cndmask_b32_e64 v15, v15, -v15, s[4:5]
	v_fmac_f32_e32 v15, v16, v29
	v_cndmask_b32_e64 v15, v29, v15, s[6:7]
	s_cbranch_vccnz .LBB0_848
	v_pk_mul_f32 v[6:7], v[6:7], s[42:43] op_sel_hi:[1,0]
	v_pk_mul_f32 v[4:5], v[4:5], s[42:43] op_sel_hi:[1,0]
	v_pk_mul_f32 v[14:15], v[14:15], s[42:43] op_sel_hi:[1,0]
	v_pk_mul_f32 v[12:13], v[12:13], s[42:43] op_sel_hi:[1,0]
	v_pk_mul_f32 v[2:3], v[2:3], s[42:43] op_sel_hi:[1,0]
	v_pk_mul_f32 v[0:1], v[0:1], s[42:43] op_sel_hi:[1,0]
	v_pk_mul_f32 v[10:11], v[10:11], s[42:43] op_sel_hi:[1,0]
	v_pk_mul_f32 v[8:9], v[8:9], s[42:43] op_sel_hi:[1,0]

; #define LAS __attribute__((address_space(3)))
; __device__ __forceinline__ unsigned cvt_pk_bf16(float lo, float hi) { unsigned r; asm volatile("v_cvt_pk_bf16_f32 %0, %1, %2" : "=v"(r) : "v"(lo), "v"(hi)); return r; }
; __device__ __forceinline__ float bflo(unsigned w) { return __uint_as_float(w << 16); }
; __device__ __forceinline__ float bfhi(unsigned w) { return __uint_as_float(w & 0xffff0000u); }
; #define SCHED_BAR() __builtin_amdgcn_sched_barrier(0)
; __device__ __forceinline__ void ret_unit(LAS unsigned char* lds, bf16_t* proj, float* out, float* rss, unsigned* cnt, int unit, bool same_xcd) {
;     ...
;         for (int it = 0; it < 8; ++it) { const int p = tid + 512 * it; *(LAS u32x4*)(KI + (p >> 5) * RK_P + (p & 31) * 16) = Kn[it]; }
; #pragma unroll
;         for (int it = 0; it < 2; ++it) { const int p = tid + 512 * it, j = p >> 3, pc = p & 7; const u32x4 v = Vn[it];
;             const float sc = exp2f(l2g * (float)(127 - j));
;             u32x4 o; o.x = cvt_pk_bf16(bflo(v.x) * sc, bfhi(v.x) * sc); o.y = cvt_pk_bf16(bflo(v.y) * sc, bfhi(v.y) * sc);
;             o.z = cvt_pk_bf16(bflo(v.z) * sc, bfhi(v.z) * sc); o.w = cvt_pk_bf16(bflo(v.w) * sc, bfhi(v.w) * sc);
;             *(LAS u32x4*)(VI + j * RV_P + pc * 16) = o; }
;         bf16x8 Qf[8]; u32x2 Gc[4];
; #pragma unroll
;         for (int ks = 0; ks < 8; ++ks) Qf[ks] = Qn[ks];
; #pragma unroll
;         for (int et = 0; et < 4; ++et) Gc[et] = Gn[et];
;         SCHED_BAR();
;         if (c < 15) RET_LOAD_KV(c + 1);
.LBB0_1208:
	s_waitcnt vmcnt(13)
	v_lshlrev_b32_e32 v104, 16, v64
	v_and_b32_e32 v105, 0xffff0000, v64
	v_mul_f32_e32 v104, v242, v104
	v_mul_f32_e32 v105, v242, v105
	ds_write_b128 v211, v[0:3]
	ds_write_b128 v213, v[4:7]
	ds_write_b128 v211, v[8:11] offset:17920
	ds_write_b128 v223, v[12:15]
	ds_write_b128 v211, v[16:19] offset:35840
	ds_write_b128 v224, v[20:23]
	ds_write_b128 v211, v[32:35] offset:53760
	ds_write_b128 v225, v[44:47]
	v_cvt_pk_bf16_f32 v104, v104, v105
	v_lshlrev_b32_e32 v105, 16, v65
	v_and_b32_e32 v106, 0xffff0000, v65
	v_mul_f32_e32 v105, v242, v105
	v_mul_f32_e32 v106, v242, v106
	v_cvt_pk_bf16_f32 v105, v105, v106
	v_lshlrev_b32_e32 v106, 16, v66
	v_and_b32_e32 v107, 0xffff0000, v66
	v_mul_f32_e32 v106, v242, v106
	v_mul_f32_e32 v107, v242, v107
	v_cvt_pk_bf16_f32 v106, v106, v107
	v_lshlrev_b32_e32 v107, 16, v67
	v_mul_f32_e32 v107, v242, v107
	v_and_b32_e32 v108, 0xffff0000, v67
	v_mul_f32_e32 v108, v242, v108
	v_cvt_pk_bf16_f32 v107, v107, v108
	ds_write_b128 v226, v[104:107]
	s_waitcnt vmcnt(12)
	v_lshlrev_b32_e32 v104, 16, v68
	v_and_b32_e32 v105, 0xffff0000, v68
	v_mul_f32_e32 v104, v243, v104
	v_mul_f32_e32 v105, v243, v105
	v_cvt_pk_bf16_f32 v104, v104, v105
	v_lshlrev_b32_e32 v105, 16, v69
	v_and_b32_e32 v106, 0xffff0000, v69
	v_mul_f32_e32 v105, v243, v105
	v_mul_f32_e32 v106, v243, v106
	v_cvt_pk_bf16_f32 v105, v105, v106
	v_lshlrev_b32_e32 v106, 16, v70
	v_and_b32_e32 v107, 0xffff0000, v70
	v_mul_f32_e32 v106, v243, v106
	v_mul_f32_e32 v107, v243, v107
	v_cvt_pk_bf16_f32 v106, v106, v107
	v_lshlrev_b32_e32 v107, 16, v71
	v_mul_f32_e32 v107, v243, v107
	v_and_b32_e32 v108, 0xffff0000, v71
	v_mul_f32_e32 v108, v243, v108
	v_cvt_pk_bf16_f32 v107, v107, v108
	ds_write_b128 v227, v[104:107]
	s_cmp_lg_u32 s58, 0x2ee0000
	s_cselect_b64 s[60:61], -1, 0
	s_cmp_eq_u32 s58, 0x2ee0000
	s_cbranch_scc1 .LBB0_1210
	v_lshl_add_u64 v[32:33], v[198:199], 0, s[58:59]
	v_add_co_u32_e32 v0, vcc, 0x9022000, v32
	v_lshl_add_u64 v[64:65], v[196:197], 0, s[58:59]
	s_nop 0
	v_addc_co_u32_e32 v1, vcc, 0, v33, vcc
	v_add_co_u32_e32 v4, vcc, 0x9086000, v32
	v_lshl_add_u64 v[68:69], v[192:193], 0, s[58:59]
	s_nop 0
	v_addc_co_u32_e32 v5, vcc, 0, v33, vcc
	v_add_co_u32_e32 v8, vcc, 0x90ea000, v32
	global_load_dwordx4 v[0:3], v[0:1], off offset:3072
	s_nop 0
	global_load_dwordx4 v[4:7], v[4:5], off offset:3072
	v_addc_co_u32_e32 v9, vcc, 0, v33, vcc
	v_add_co_u32_e32 v12, vcc, 0x914e000, v32
	s_nop 1
	v_addc_co_u32_e32 v13, vcc, 0, v33, vcc
	v_add_co_u32_e32 v16, vcc, 0x91b2000, v32
	global_load_dwordx4 v[8:11], v[8:9], off offset:3072
	s_nop 0
	global_load_dwordx4 v[12:15], v[12:13], off offset:3072
	v_addc_co_u32_e32 v17, vcc, 0, v33, vcc
	v_add_co_u32_e32 v20, vcc, 0x9216000, v32
	s_nop 1
	v_addc_co_u32_e32 v21, vcc, 0, v33, vcc
	v_add_co_u32_e32 v34, vcc, 0x927a000, v32
	global_load_dwordx4 v[16:19], v[16:17], off offset:3072
	s_nop 0
	global_load_dwordx4 v[20:23], v[20:21], off offset:3072
	v_addc_co_u32_e32 v35, vcc, 0, v33, vcc
	v_add_co_u32_e32 v44, vcc, 0x92de000, v32
	s_nop 1
	v_addc_co_u32_e32 v45, vcc, 0, v33, vcc
	global_load_dwordx4 v[32:35], v[34:35], off offset:3072
	s_nop 0
	global_load_dwordx4 v[44:47], v[44:45], off offset:3072
	s_nop 0
	global_load_dwordx4 v[64:67], v[64:65], off
	s_nop 0
	global_load_dwordx4 v[68:71], v[68:69], off
; #define LAS __attribute__((address_space(3)))
; #define SCHED_BAR() __builtin_amdgcn_sched_barrier(0)
; __device__ __forceinline__ void ret_unit(LAS unsigned char* lds, bf16_t* proj, float* out, float* rss, unsigned* cnt, int unit, bool same_xcd) {
;     ...
;         for (int ks = 0; ks < 8; ++ks) { bf16x8 F[4];
; #pragma unroll
;             for (int et = 0; et < 4; ++et) F[et] = *(const LAS bf16x8*)(ST + (16 * et + l16) * RS_P + (32 * ks + 8 * fq) * 2);
;             SCHED_BAR();
; #pragma unroll
;             for (int et = 0; et < 4; ++et) O[et] = __builtin_amdgcn_mfma_f32_16x16x32_bf16(F[et], Qf[ks], O[et], 0, 0, 0);
;             SCHED_BAR(); }
;     ...
;                     for (int k4 = 0; k4 < 4; ++k4) { F[k4] = *(const LAS bf16x8*)(KI + (32 * s + l16) * RK_P + (32 * (4 * hb + k4) + 8 * fq) * 2);
;                         F[4 + k4] = *(const LAS bf16x8*)(KI + (32 * s + 16 + l16) * RK_P + (32 * (4 * hb + k4) + 8 * fq) * 2); }
;                     SCHED_BAR();
; #pragma unroll
;                     for (int k4 = 0; k4 < 4; ++k4) { T0 = __builtin_amdgcn_mfma_f32_16x16x32_bf16(F[k4], Qf[4 * hb + k4], T0, 0, 0, 0);
;                         if (two) T1 = __builtin_amdgcn_mfma_f32_16x16x32_bf16(F[4 + k4], Qf[4 * hb + k4], T1, 0, 0, 0); }
.LBB0_1210:
	s_waitcnt lgkmcnt(0)
	s_barrier
	ds_read_b128 v[104:107], v228
	ds_read_b128 v[108:111], v228 offset:8448
	ds_read_b128 v[112:115], v228 offset:16896
	ds_read_b128 v[116:119], v228 offset:25344
	s_waitcnt vmcnt(11) lgkmcnt(3)
	v_mfma_f32_16x16x32_bf16 v[120:123], v[104:107], v[24:27], 0
	s_mov_b32 s54, s52
	s_mov_b32 s55, s52
	s_mov_b32 s53, s52
	s_waitcnt lgkmcnt(2)
	v_mfma_f32_16x16x32_bf16 v[108:111], v[108:111], v[24:27], 0
	v_mov_b64_e32 v[106:107], s[54:55]
	v_mov_b64_e32 v[104:105], s[52:53]
	s_waitcnt lgkmcnt(1)
	v_mfma_f32_16x16x32_bf16 v[112:115], v[112:115], v[24:27], 0
	s_waitcnt lgkmcnt(0)
	v_mfma_f32_16x16x32_bf16 v[116:119], v[116:119], v[24:27], 0
	ds_read_b128 v[124:127], v228 offset:64
	ds_read_b128 v[128:131], v228 offset:8512
	ds_read_b128 v[132:135], v228 offset:16960
	ds_read_b128 v[136:139], v228 offset:25408
	s_waitcnt vmcnt(10) lgkmcnt(3)
	v_mfma_f32_16x16x32_bf16 v[120:123], v[124:127], v[28:31], v[120:123]
	s_waitcnt lgkmcnt(2)
	v_mfma_f32_16x16x32_bf16 v[108:111], v[128:131], v[28:31], v[108:111]
	s_waitcnt lgkmcnt(1)
	v_mfma_f32_16x16x32_bf16 v[112:115], v[132:135], v[28:31], v[112:115]
	s_waitcnt lgkmcnt(0)
	v_mfma_f32_16x16x32_bf16 v[116:119], v[136:139], v[28:31], v[116:119]
	ds_read_b128 v[124:127], v228 offset:128
	ds_read_b128 v[128:131], v228 offset:8576
	ds_read_b128 v[132:135], v228 offset:17024
	ds_read_b128 v[136:139], v228 offset:25472
	s_waitcnt vmcnt(9) lgkmcnt(3)
	v_mfma_f32_16x16x32_bf16 v[120:123], v[124:127], v[36:39], v[120:123]
	s_waitcnt lgkmcnt(2)
	v_mfma_f32_16x16x32_bf16 v[108:111], v[128:131], v[36:39], v[108:111]
	s_waitcnt lgkmcnt(1)
	v_mfma_f32_16x16x32_bf16 v[112:115], v[132:135], v[36:39], v[112:115]
	s_waitcnt lgkmcnt(0)
	v_mfma_f32_16x16x32_bf16 v[116:119], v[136:139], v[36:39], v[116:119]
	ds_read_b128 v[124:127], v228 offset:192
	ds_read_b128 v[128:131], v228 offset:8640
	ds_read_b128 v[132:135], v228 offset:17088
	ds_read_b128 v[136:139], v228 offset:25536
	s_waitcnt vmcnt(8) lgkmcnt(3)
	v_mfma_f32_16x16x32_bf16 v[120:123], v[124:127], v[40:43], v[120:123]
	s_waitcnt lgkmcnt(2)
	v_mfma_f32_16x16x32_bf16 v[108:111], v[128:131], v[40:43], v[108:111]
	s_waitcnt lgkmcnt(1)
	v_mfma_f32_16x16x32_bf16 v[112:115], v[132:135], v[40:43], v[112:115]
	s_waitcnt lgkmcnt(0)
	v_mfma_f32_16x16x32_bf16 v[116:119], v[136:139], v[40:43], v[116:119]
	ds_read_b128 v[124:127], v228 offset:256
	ds_read_b128 v[128:131], v228 offset:8704
	ds_read_b128 v[132:135], v228 offset:17152
	ds_read_b128 v[136:139], v228 offset:25600
	s_waitcnt vmcnt(7) lgkmcnt(3)
	v_mfma_f32_16x16x32_bf16 v[120:123], v[124:127], v[48:51], v[120:123]
	s_waitcnt lgkmcnt(2)
	v_mfma_f32_16x16x32_bf16 v[108:111], v[128:131], v[48:51], v[108:111]
	s_waitcnt lgkmcnt(1)
	v_mfma_f32_16x16x32_bf16 v[112:115], v[132:135], v[48:51], v[112:115]
	s_waitcnt lgkmcnt(0)
	v_mfma_f32_16x16x32_bf16 v[116:119], v[136:139], v[48:51], v[116:119]
	ds_read_b128 v[124:127], v228 offset:320
	ds_read_b128 v[128:131], v228 offset:8768
	ds_read_b128 v[132:135], v228 offset:17216
	ds_read_b128 v[136:139], v228 offset:25664
	s_waitcnt vmcnt(6) lgkmcnt(3)
	v_mfma_f32_16x16x32_bf16 v[120:123], v[124:127], v[52:55], v[120:123]
	s_waitcnt lgkmcnt(2)
	v_mfma_f32_16x16x32_bf16 v[108:111], v[128:131], v[52:55], v[108:111]
	s_waitcnt lgkmcnt(1)
	v_mfma_f32_16x16x32_bf16 v[112:115], v[132:135], v[52:55], v[112:115]
	s_waitcnt lgkmcnt(0)
	v_mfma_f32_16x16x32_bf16 v[116:119], v[136:139], v[52:55], v[116:119]
	ds_read_b128 v[124:127], v228 offset:384
	ds_read_b128 v[128:131], v228 offset:8832
	ds_read_b128 v[132:135], v228 offset:17280
	ds_read_b128 v[136:139], v228 offset:25728
	s_waitcnt vmcnt(5) lgkmcnt(3)
	v_mfma_f32_16x16x32_bf16 v[120:123], v[124:127], v[56:59], v[120:123]
	s_waitcnt lgkmcnt(2)
	v_mfma_f32_16x16x32_bf16 v[108:111], v[128:131], v[56:59], v[108:111]
	s_waitcnt lgkmcnt(1)
	v_mfma_f32_16x16x32_bf16 v[112:115], v[132:135], v[56:59], v[112:115]
	s_waitcnt lgkmcnt(0)
	v_mfma_f32_16x16x32_bf16 v[124:127], v[136:139], v[56:59], v[116:119]
	s_nop 2
	ds_read_b128 v[116:119], v228 offset:448
	ds_read_b128 v[128:131], v228 offset:8896
	ds_read_b128 v[132:135], v228 offset:17344
	ds_read_b128 v[136:139], v228 offset:25792
	s_waitcnt vmcnt(4) lgkmcnt(3)
	v_mfma_f32_16x16x32_bf16 v[120:123], v[116:119], v[60:63], v[120:123]
	s_waitcnt lgkmcnt(2)
	v_mfma_f32_16x16x32_bf16 v[116:119], v[128:131], v[60:63], v[108:111]
	s_waitcnt lgkmcnt(1)
	v_mfma_f32_16x16x32_bf16 v[112:115], v[132:135], v[60:63], v[112:115]
	s_waitcnt lgkmcnt(0)
	v_mfma_f32_16x16x32_bf16 v[108:111], v[136:139], v[60:63], v[124:127]
	ds_read_b128 v[152:155], v238
	ds_read_b128 v[144:147], v238 offset:64
	ds_read_b128 v[148:151], v238 offset:8960
	ds_read_b128 v[140:143], v238 offset:9024
	ds_read_b128 v[132:135], v238 offset:128
	ds_read_b128 v[128:131], v238 offset:192
	ds_read_b128 v[136:139], v238 offset:9088
	ds_read_b128 v[124:127], v238 offset:9152
	s_waitcnt lgkmcnt(7)
	v_mfma_f32_16x16x32_bf16 v[152:155], v[152:155], v[24:27], 0
	v_cndmask_b32_e64 v179, 0, 1, s[2:3]
	v_cmp_ne_u32_e64 s[48:49], 1, v179
	s_andn2_b64 vcc, exec, s[2:3]
	s_cbranch_vccnz .LBB0_1212
	s_waitcnt lgkmcnt(5)
	v_mfma_f32_16x16x32_bf16 v[104:107], v[148:151], v[24:27], 0

; __device__ __forceinline__ void ret_unit(LAS unsigned char* lds, bf16_t* proj, float* out, float* rss, unsigned* cnt, int unit, bool same_xcd) {
;     ...
;         if (c < 15) RET_LOAD_QG(c + 1);
.LBB0_1280:
	s_andn2_b64 vcc, exec, s[60:61]
	s_waitcnt vmcnt(0)
	v_mov_b64_e32 v[126:127], v[202:203]
	v_mov_b64_e32 v[124:125], v[204:205]
	v_mov_b64_e32 v[122:123], v[206:207]
	v_mov_b64_e32 v[120:121], v[214:215]
	s_cbranch_vccnz .LBB0_1282
	v_lshl_add_u64 v[60:61], v[194:195], 0, s[58:59]
	global_load_dwordx4 v[24:27], v[60:61], off offset:-256
	global_load_dwordx4 v[28:31], v[60:61], off offset:-192
	global_load_dwordx4 v[36:39], v[60:61], off offset:-128
	global_load_dwordx4 v[40:43], v[60:61], off offset:-64
	global_load_dwordx4 v[48:51], v[60:61], off
	global_load_dwordx4 v[52:55], v[60:61], off offset:64
	global_load_dwordx4 v[56:59], v[60:61], off offset:128
	s_nop 0
	global_load_dwordx4 v[60:63], v[60:61], off offset:192
	v_lshl_add_u64 v[126:127], v[200:201], 0, s[58:59]
	global_load_dwordx2 v[120:121], v[126:127], off offset:-64
	global_load_dwordx2 v[122:123], v[126:127], off offset:-32
	global_load_dwordx2 v[124:125], v[126:127], off
	s_nop 0
	global_load_dwordx2 v[126:127], v[126:127], off offset:32
